# kpair variant: 2x2 accumulator blocks (boustrophedon inside) + dropwaits + rotary
# baseline (speedup 1.0000x reference)
.LBB0_642:
	ds_read_b128 v[148:151], v139
	ds_read_b128 v[152:155], v139 offset:1024
	ds_read_b128 v[156:159], v139 offset:2048
	ds_read_b128 v[160:163], v139 offset:3072
	ds_read_b128 v[164:167], v140
	ds_read_b128 v[168:171], v140 offset:1024
	ds_read_b128 v[172:175], v140 offset:2048
	ds_read_b128 v[176:179], v140 offset:3072
	s_add_i32 s18, s71, 0xffe80080
	s_cmp_eq_u32 s58, s73
	s_cselect_b32 s74, s69, s18
	s_cselect_b32 s76, s70, s72
	s_or_b32 s75, s74, 0x80
	s_add_i32 s18, s71, 0xfff80000
	s_mov_b32 m0, s59
	ds_read_b128 v[180:183], v141
	ds_read_b128 v[184:187], v141 offset:1024
	ds_read_b128 v[188:191], v141 offset:2048
	ds_read_b128 v[192:195], v141 offset:3072
	ds_read_b128 v[196:199], v141 offset:4096
	ds_read_b128 v[200:203], v141 offset:5120
	ds_read_b128 v[204:207], v141 offset:6144
	ds_read_b128 v[208:211], v141 offset:7168
	buffer_load_dwordx4 v137, s[12:15], s18 offen lds
	s_mov_b32 m0, s60
	s_nop 0
	buffer_load_dwordx4 v137, s[12:15], s71 offen lds
	s_waitcnt vmcnt(8)
	s_waitcnt lgkmcnt(0)
	s_setprio 1
	v_mfma_f32_16x16x32_bf16 v[118:121], v[148:151], v[180:183], v[118:121]
	s_barrier
	v_mfma_f32_16x16x32_bf16 v[118:121], v[152:155], v[184:187], v[118:121]
	v_mfma_f32_16x16x32_bf16 v[114:117], v[156:159], v[180:183], v[114:117]
	v_mfma_f32_16x16x32_bf16 v[114:117], v[160:163], v[184:187], v[114:117]
	v_mfma_f32_16x16x32_bf16 v[102:105], v[156:159], v[188:191], v[102:105]
	v_mfma_f32_16x16x32_bf16 v[102:105], v[160:163], v[192:195], v[102:105]
	v_mfma_f32_16x16x32_bf16 v[110:113], v[148:151], v[188:191], v[110:113]
	v_mfma_f32_16x16x32_bf16 v[110:113], v[152:155], v[192:195], v[110:113]
	v_mfma_f32_16x16x32_bf16 v[126:129], v[164:167], v[180:183], v[126:129]
	v_mfma_f32_16x16x32_bf16 v[126:129], v[168:171], v[184:187], v[126:129]
	v_mfma_f32_16x16x32_bf16 v[122:125], v[172:175], v[180:183], v[122:125]
	v_mfma_f32_16x16x32_bf16 v[122:125], v[176:179], v[184:187], v[122:125]
	v_mfma_f32_16x16x32_bf16 v[98:101], v[172:175], v[188:191], v[98:101]
	v_mfma_f32_16x16x32_bf16 v[98:101], v[176:179], v[192:195], v[98:101]
	v_mfma_f32_16x16x32_bf16 v[106:109], v[164:167], v[188:191], v[106:109]
	v_mfma_f32_16x16x32_bf16 v[106:109], v[168:171], v[192:195], v[106:109]
	v_mfma_f32_16x16x32_bf16 v[94:97], v[148:151], v[196:199], v[94:97]
	v_mfma_f32_16x16x32_bf16 v[94:97], v[152:155], v[200:203], v[94:97]
	v_mfma_f32_16x16x32_bf16 v[86:89], v[156:159], v[196:199], v[86:89]
	v_mfma_f32_16x16x32_bf16 v[86:89], v[160:163], v[200:203], v[86:89]
	v_mfma_f32_16x16x32_bf16 v[66:69], v[156:159], v[204:207], v[66:69]
	v_mfma_f32_16x16x32_bf16 v[66:69], v[160:163], v[208:211], v[66:69]
	v_mfma_f32_16x16x32_bf16 v[78:81], v[148:151], v[204:207], v[78:81]
	v_mfma_f32_16x16x32_bf16 v[78:81], v[152:155], v[208:211], v[78:81]
	v_mfma_f32_16x16x32_bf16 v[90:93], v[164:167], v[196:199], v[90:93]
	v_mfma_f32_16x16x32_bf16 v[90:93], v[168:171], v[200:203], v[90:93]
	v_mfma_f32_16x16x32_bf16 v[82:85], v[172:175], v[196:199], v[82:85]
	v_mfma_f32_16x16x32_bf16 v[82:85], v[176:179], v[200:203], v[82:85]
	v_mfma_f32_16x16x32_bf16 v[70:73], v[172:175], v[204:207], v[70:73]
	v_mfma_f32_16x16x32_bf16 v[70:73], v[176:179], v[208:211], v[70:73]
	v_mfma_f32_16x16x32_bf16 v[74:77], v[164:167], v[204:207], v[74:77]
	v_mfma_f32_16x16x32_bf16 v[74:77], v[168:171], v[208:211], v[74:77]
	s_setprio 0
	s_barrier
	s_mov_b32 m0, s30
	s_mov_b32 s18, s14
	s_mov_b32 s19, s15
	ds_read_b128 v[180:183], v141 offset:16384
	ds_read_b128 v[184:187], v141 offset:17408
	ds_read_b128 v[188:191], v141 offset:18432
	ds_read_b128 v[192:195], v141 offset:19456
	ds_read_b128 v[196:199], v141 offset:20480
	ds_read_b128 v[200:203], v141 offset:21504
	ds_read_b128 v[204:207], v141 offset:22528
	ds_read_b128 v[208:211], v141 offset:23552
	buffer_load_dwordx4 v138, s[16:19], s76 offen lds
	s_add_i32 s77, s76, 0x80000
	s_mov_b32 m0, s31
	s_nop 0
	buffer_load_dwordx4 v138, s[16:19], s77 offen lds
	s_add_i32 s77, s76, 0x100000
	s_mov_b32 m0, s44
	s_nop 0
	buffer_load_dwordx4 v138, s[16:19], s77 offen lds
	s_add_i32 s77, s76, 0x180000
	s_mov_b32 m0, s45
	s_nop 0
	buffer_load_dwordx4 v138, s[16:19], s77 offen lds
	s_mov_b32 m0, s27
	s_add_i32 s77, s74, 0x80000
	buffer_load_dwordx4 v137, s[12:15], s74 offen lds
	s_mov_b32 m0, s46
	s_nop 0
	buffer_load_dwordx4 v137, s[12:15], s77 offen lds
	s_waitcnt vmcnt(8)
	s_waitcnt lgkmcnt(0)
	s_setprio 1
	v_mfma_f32_16x16x32_bf16 v[62:65], v[148:151], v[180:183], v[62:65]
	s_barrier
	v_mfma_f32_16x16x32_bf16 v[62:65], v[152:155], v[184:187], v[62:65]
	v_mfma_f32_16x16x32_bf16 v[54:57], v[156:159], v[180:183], v[54:57]
	v_mfma_f32_16x16x32_bf16 v[54:57], v[160:163], v[184:187], v[54:57]
	v_mfma_f32_16x16x32_bf16 v[38:41], v[156:159], v[188:191], v[38:41]
	v_mfma_f32_16x16x32_bf16 v[38:41], v[160:163], v[192:195], v[38:41]
	v_mfma_f32_16x16x32_bf16 v[46:49], v[148:151], v[188:191], v[46:49]
	v_mfma_f32_16x16x32_bf16 v[46:49], v[152:155], v[192:195], v[46:49]
	v_mfma_f32_16x16x32_bf16 v[58:61], v[164:167], v[180:183], v[58:61]
	v_mfma_f32_16x16x32_bf16 v[58:61], v[168:171], v[184:187], v[58:61]
	v_mfma_f32_16x16x32_bf16 v[50:53], v[172:175], v[180:183], v[50:53]
	v_mfma_f32_16x16x32_bf16 v[50:53], v[176:179], v[184:187], v[50:53]
	v_mfma_f32_16x16x32_bf16 v[34:37], v[172:175], v[188:191], v[34:37]
	v_mfma_f32_16x16x32_bf16 v[34:37], v[176:179], v[192:195], v[34:37]
	v_mfma_f32_16x16x32_bf16 v[42:45], v[164:167], v[188:191], v[42:45]
	v_mfma_f32_16x16x32_bf16 v[42:45], v[168:171], v[192:195], v[42:45]
	v_mfma_f32_16x16x32_bf16 v[30:33], v[148:151], v[196:199], v[30:33]
	v_mfma_f32_16x16x32_bf16 v[30:33], v[152:155], v[200:203], v[30:33]
	v_mfma_f32_16x16x32_bf16 v[22:25], v[156:159], v[196:199], v[22:25]
	v_mfma_f32_16x16x32_bf16 v[22:25], v[160:163], v[200:203], v[22:25]
	v_mfma_f32_16x16x32_bf16 v[6:9], v[156:159], v[204:207], v[6:9]
	v_mfma_f32_16x16x32_bf16 v[6:9], v[160:163], v[208:211], v[6:9]
	v_mfma_f32_16x16x32_bf16 v[14:17], v[148:151], v[204:207], v[14:17]
	v_mfma_f32_16x16x32_bf16 v[14:17], v[152:155], v[208:211], v[14:17]
	v_mfma_f32_16x16x32_bf16 v[26:29], v[164:167], v[196:199], v[26:29]
	v_mfma_f32_16x16x32_bf16 v[26:29], v[168:171], v[200:203], v[26:29]
	v_mfma_f32_16x16x32_bf16 v[18:21], v[172:175], v[196:199], v[18:21]
	v_mfma_f32_16x16x32_bf16 v[18:21], v[176:179], v[200:203], v[18:21]
	v_mfma_f32_16x16x32_bf16 v[2:5], v[172:175], v[204:207], v[2:5]
	v_mfma_f32_16x16x32_bf16 v[2:5], v[176:179], v[208:211], v[2:5]
	v_mfma_f32_16x16x32_bf16 v[10:13], v[164:167], v[204:207], v[10:13]
	v_mfma_f32_16x16x32_bf16 v[10:13], v[168:171], v[208:211], v[10:13]
	s_setprio 0
	s_barrier
	ds_read_b128 v[148:151], v142
	ds_read_b128 v[152:155], v142 offset:1024
	ds_read_b128 v[156:159], v142 offset:2048
	ds_read_b128 v[160:163], v142 offset:3072
	ds_read_b128 v[164:167], v143
	ds_read_b128 v[168:171], v143 offset:1024
	ds_read_b128 v[172:175], v143 offset:2048
	ds_read_b128 v[176:179], v143 offset:3072
	s_mov_b32 m0, s47
	s_add_i32 s77, s74, 0x100000
	ds_read_b128 v[180:183], v141 offset:32768
	ds_read_b128 v[184:187], v141 offset:33792
	ds_read_b128 v[188:191], v141 offset:34816
	ds_read_b128 v[192:195], v141 offset:35840
	ds_read_b128 v[196:199], v141 offset:36864
	ds_read_b128 v[200:203], v141 offset:37888
	ds_read_b128 v[204:207], v141 offset:38912
	ds_read_b128 v[208:211], v141 offset:39936
	buffer_load_dwordx4 v137, s[12:15], s77 offen lds
	s_add_i32 s77, s74, 0x180000
	s_mov_b32 m0, s48
	s_nop 0
	buffer_load_dwordx4 v137, s[12:15], s77 offen lds
	s_waitcnt vmcnt(8)
	s_waitcnt lgkmcnt(0)
	s_setprio 1
	v_mfma_f32_16x16x32_bf16 v[118:121], v[148:151], v[180:183], v[118:121]
	s_barrier
	v_mfma_f32_16x16x32_bf16 v[118:121], v[152:155], v[184:187], v[118:121]
	v_mfma_f32_16x16x32_bf16 v[114:117], v[156:159], v[180:183], v[114:117]
	v_mfma_f32_16x16x32_bf16 v[114:117], v[160:163], v[184:187], v[114:117]
	v_mfma_f32_16x16x32_bf16 v[102:105], v[156:159], v[188:191], v[102:105]
	v_mfma_f32_16x16x32_bf16 v[102:105], v[160:163], v[192:195], v[102:105]
	v_mfma_f32_16x16x32_bf16 v[110:113], v[148:151], v[188:191], v[110:113]
	v_mfma_f32_16x16x32_bf16 v[110:113], v[152:155], v[192:195], v[110:113]
	v_mfma_f32_16x16x32_bf16 v[126:129], v[164:167], v[180:183], v[126:129]
	v_mfma_f32_16x16x32_bf16 v[126:129], v[168:171], v[184:187], v[126:129]
	v_mfma_f32_16x16x32_bf16 v[122:125], v[172:175], v[180:183], v[122:125]
	v_mfma_f32_16x16x32_bf16 v[122:125], v[176:179], v[184:187], v[122:125]
	v_mfma_f32_16x16x32_bf16 v[98:101], v[172:175], v[188:191], v[98:101]
	v_mfma_f32_16x16x32_bf16 v[98:101], v[176:179], v[192:195], v[98:101]
	v_mfma_f32_16x16x32_bf16 v[106:109], v[164:167], v[188:191], v[106:109]
	v_mfma_f32_16x16x32_bf16 v[106:109], v[168:171], v[192:195], v[106:109]
	v_mfma_f32_16x16x32_bf16 v[94:97], v[148:151], v[196:199], v[94:97]
	v_mfma_f32_16x16x32_bf16 v[94:97], v[152:155], v[200:203], v[94:97]
	v_mfma_f32_16x16x32_bf16 v[86:89], v[156:159], v[196:199], v[86:89]
	v_mfma_f32_16x16x32_bf16 v[86:89], v[160:163], v[200:203], v[86:89]
	v_mfma_f32_16x16x32_bf16 v[66:69], v[156:159], v[204:207], v[66:69]
	v_mfma_f32_16x16x32_bf16 v[66:69], v[160:163], v[208:211], v[66:69]
	v_mfma_f32_16x16x32_bf16 v[78:81], v[148:151], v[204:207], v[78:81]
	v_mfma_f32_16x16x32_bf16 v[78:81], v[152:155], v[208:211], v[78:81]
	v_mfma_f32_16x16x32_bf16 v[90:93], v[164:167], v[196:199], v[90:93]
	v_mfma_f32_16x16x32_bf16 v[90:93], v[168:171], v[200:203], v[90:93]
	v_mfma_f32_16x16x32_bf16 v[82:85], v[172:175], v[196:199], v[82:85]
	v_mfma_f32_16x16x32_bf16 v[82:85], v[176:179], v[200:203], v[82:85]
	v_mfma_f32_16x16x32_bf16 v[70:73], v[172:175], v[204:207], v[70:73]
	v_mfma_f32_16x16x32_bf16 v[70:73], v[176:179], v[208:211], v[70:73]
	v_mfma_f32_16x16x32_bf16 v[74:77], v[164:167], v[204:207], v[74:77]
	v_mfma_f32_16x16x32_bf16 v[74:77], v[168:171], v[208:211], v[74:77]
	s_setprio 0
	s_barrier
	s_mov_b32 m0, s50
	s_or_b32 s77, s76, 0x80
	ds_read_b128 v[180:183], v141 offset:49152
	ds_read_b128 v[184:187], v141 offset:50176
	ds_read_b128 v[188:191], v141 offset:51200
	ds_read_b128 v[192:195], v141 offset:52224
	ds_read_b128 v[196:199], v141 offset:53248
	ds_read_b128 v[200:203], v141 offset:54272
	ds_read_b128 v[204:207], v141 offset:55296
	ds_read_b128 v[208:211], v141 offset:56320
	buffer_load_dwordx4 v138, s[16:19], s77 offen lds
	s_add_i32 s77, s76, 0x80080
	s_mov_b32 m0, s51
	s_add_i32 s74, s74, 0x80080
	buffer_load_dwordx4 v138, s[16:19], s77 offen lds
	s_add_i32 s77, s76, 0x100080
	s_mov_b32 m0, s54
	s_add_i32 s76, s76, 0x180080
	buffer_load_dwordx4 v138, s[16:19], s77 offen lds
	s_mov_b32 m0, s55
	s_nop 0
	buffer_load_dwordx4 v138, s[16:19], s76 offen lds
	s_mov_b32 m0, s52
	s_nop 0
	buffer_load_dwordx4 v137, s[12:15], s75 offen lds
	s_mov_b32 m0, s53
	s_nop 0
	buffer_load_dwordx4 v137, s[12:15], s74 offen lds
	s_waitcnt vmcnt(8)
	s_waitcnt lgkmcnt(0)
	s_setprio 1
	v_mfma_f32_16x16x32_bf16 v[62:65], v[148:151], v[180:183], v[62:65]
	s_barrier
	v_mfma_f32_16x16x32_bf16 v[62:65], v[152:155], v[184:187], v[62:65]
	v_mfma_f32_16x16x32_bf16 v[54:57], v[156:159], v[180:183], v[54:57]
	v_mfma_f32_16x16x32_bf16 v[54:57], v[160:163], v[184:187], v[54:57]
	v_mfma_f32_16x16x32_bf16 v[38:41], v[156:159], v[188:191], v[38:41]
	v_mfma_f32_16x16x32_bf16 v[38:41], v[160:163], v[192:195], v[38:41]
	v_mfma_f32_16x16x32_bf16 v[46:49], v[148:151], v[188:191], v[46:49]
	v_mfma_f32_16x16x32_bf16 v[46:49], v[152:155], v[192:195], v[46:49]
	v_mfma_f32_16x16x32_bf16 v[58:61], v[164:167], v[180:183], v[58:61]
	v_mfma_f32_16x16x32_bf16 v[58:61], v[168:171], v[184:187], v[58:61]
	v_mfma_f32_16x16x32_bf16 v[50:53], v[172:175], v[180:183], v[50:53]
	v_mfma_f32_16x16x32_bf16 v[50:53], v[176:179], v[184:187], v[50:53]
	v_mfma_f32_16x16x32_bf16 v[34:37], v[172:175], v[188:191], v[34:37]
	v_mfma_f32_16x16x32_bf16 v[34:37], v[176:179], v[192:195], v[34:37]
	v_mfma_f32_16x16x32_bf16 v[42:45], v[164:167], v[188:191], v[42:45]
	v_mfma_f32_16x16x32_bf16 v[42:45], v[168:171], v[192:195], v[42:45]
	v_mfma_f32_16x16x32_bf16 v[30:33], v[148:151], v[196:199], v[30:33]
	v_mfma_f32_16x16x32_bf16 v[30:33], v[152:155], v[200:203], v[30:33]
	v_mfma_f32_16x16x32_bf16 v[22:25], v[156:159], v[196:199], v[22:25]
	v_mfma_f32_16x16x32_bf16 v[22:25], v[160:163], v[200:203], v[22:25]
	v_mfma_f32_16x16x32_bf16 v[6:9], v[156:159], v[204:207], v[6:9]
	v_mfma_f32_16x16x32_bf16 v[6:9], v[160:163], v[208:211], v[6:9]
	v_mfma_f32_16x16x32_bf16 v[14:17], v[148:151], v[204:207], v[14:17]
	v_mfma_f32_16x16x32_bf16 v[14:17], v[152:155], v[208:211], v[14:17]
	v_mfma_f32_16x16x32_bf16 v[26:29], v[164:167], v[196:199], v[26:29]
	v_mfma_f32_16x16x32_bf16 v[26:29], v[168:171], v[200:203], v[26:29]
	v_mfma_f32_16x16x32_bf16 v[18:21], v[172:175], v[196:199], v[18:21]
	v_mfma_f32_16x16x32_bf16 v[18:21], v[176:179], v[200:203], v[18:21]
	v_mfma_f32_16x16x32_bf16 v[2:5], v[172:175], v[204:207], v[2:5]
	v_mfma_f32_16x16x32_bf16 v[2:5], v[176:179], v[208:211], v[2:5]
	v_mfma_f32_16x16x32_bf16 v[10:13], v[164:167], v[204:207], v[10:13]
	v_mfma_f32_16x16x32_bf16 v[10:13], v[168:171], v[208:211], v[10:13]
	s_setprio 0
	s_barrier
	s_add_i32 s73, s73, 2
	s_addk_i32 s71, 0x100
	s_addk_i32 s72, 0x100
	s_cmp_ge_i32 s73, s3
	s_cbranch_scc0 .LBB0_642
	s_and_b64 vcc, exec, s[42:43]
	s_cbranch_vccz .LBB0_645

.LBB0_799:
	ds_read_b128 v[134:137], v210
	ds_read_b128 v[138:141], v210 offset:1024
	ds_read_b128 v[142:145], v210 offset:2048
	ds_read_b128 v[148:151], v210 offset:3072
	ds_read_b128 v[152:155], v211
	ds_read_b128 v[156:159], v211 offset:1024
	ds_read_b128 v[160:163], v211 offset:2048
	ds_read_b128 v[164:167], v211 offset:3072
	s_add_i32 s18, s77, 0xffbf8080
	s_cmp_eq_u32 s62, s79
	s_cselect_b32 s80, s6, s18
	s_cselect_b32 s82, s7, s78
	s_or_b32 s81, s80, 0x80
	s_add_i32 s18, s77, 0xffea8000
	s_mov_b32 m0, s63
	ds_read_b128 v[168:171], v212
	ds_read_b128 v[172:175], v212 offset:1024
	ds_read_b128 v[176:179], v212 offset:2048
	ds_read_b128 v[180:183], v212 offset:3072
	ds_read_b128 v[184:187], v212 offset:4096
	ds_read_b128 v[188:191], v212 offset:5120
	ds_read_b128 v[192:195], v212 offset:6144
	ds_read_b128 v[196:199], v212 offset:7168
	buffer_load_dwordx4 v208, s[12:15], s18 offen lds
	s_mov_b32 m0, s66
	s_nop 0
	buffer_load_dwordx4 v208, s[12:15], s77 offen lds
	s_waitcnt vmcnt(8)
	s_waitcnt lgkmcnt(0)
	s_setprio 1
	v_mfma_f32_16x16x32_bf16 v[126:129], v[134:137], v[168:171], v[126:129]
	s_barrier
	v_mfma_f32_16x16x32_bf16 v[126:129], v[138:141], v[172:175], v[126:129]
	v_mfma_f32_16x16x32_bf16 v[122:125], v[142:145], v[168:171], v[122:125]
	v_mfma_f32_16x16x32_bf16 v[122:125], v[148:151], v[172:175], v[122:125]
	v_mfma_f32_16x16x32_bf16 v[114:117], v[142:145], v[176:179], v[114:117]
	v_mfma_f32_16x16x32_bf16 v[114:117], v[148:151], v[180:183], v[114:117]
	v_mfma_f32_16x16x32_bf16 v[118:121], v[134:137], v[176:179], v[118:121]
	v_mfma_f32_16x16x32_bf16 v[118:121], v[138:141], v[180:183], v[118:121]
	v_mfma_f32_16x16x32_bf16 v[110:113], v[152:155], v[168:171], v[110:113]
	v_mfma_f32_16x16x32_bf16 v[110:113], v[156:159], v[172:175], v[110:113]
	v_mfma_f32_16x16x32_bf16 v[102:105], v[160:163], v[168:171], v[102:105]
	v_mfma_f32_16x16x32_bf16 v[102:105], v[164:167], v[172:175], v[102:105]
	v_mfma_f32_16x16x32_bf16 v[86:89], v[160:163], v[176:179], v[86:89]
	v_mfma_f32_16x16x32_bf16 v[86:89], v[164:167], v[180:183], v[86:89]
	v_mfma_f32_16x16x32_bf16 v[94:97], v[152:155], v[176:179], v[94:97]
	v_mfma_f32_16x16x32_bf16 v[94:97], v[156:159], v[180:183], v[94:97]
	v_mfma_f32_16x16x32_bf16 v[106:109], v[134:137], v[184:187], v[106:109]
	v_mfma_f32_16x16x32_bf16 v[106:109], v[138:141], v[188:191], v[106:109]
	v_mfma_f32_16x16x32_bf16 v[98:101], v[142:145], v[184:187], v[98:101]
	v_mfma_f32_16x16x32_bf16 v[98:101], v[148:151], v[188:191], v[98:101]
	v_mfma_f32_16x16x32_bf16 v[82:85], v[142:145], v[192:195], v[82:85]
	v_mfma_f32_16x16x32_bf16 v[82:85], v[148:151], v[196:199], v[82:85]
	v_mfma_f32_16x16x32_bf16 v[90:93], v[134:137], v[192:195], v[90:93]
	v_mfma_f32_16x16x32_bf16 v[90:93], v[138:141], v[196:199], v[90:93]
	v_mfma_f32_16x16x32_bf16 v[78:81], v[152:155], v[184:187], v[78:81]
	v_mfma_f32_16x16x32_bf16 v[78:81], v[156:159], v[188:191], v[78:81]
	v_mfma_f32_16x16x32_bf16 v[74:77], v[160:163], v[184:187], v[74:77]
	v_mfma_f32_16x16x32_bf16 v[74:77], v[164:167], v[188:191], v[74:77]
	v_mfma_f32_16x16x32_bf16 v[66:69], v[160:163], v[192:195], v[66:69]
	v_mfma_f32_16x16x32_bf16 v[66:69], v[164:167], v[196:199], v[66:69]
	v_mfma_f32_16x16x32_bf16 v[70:73], v[152:155], v[192:195], v[70:73]
	v_mfma_f32_16x16x32_bf16 v[70:73], v[156:159], v[196:199], v[70:73]
	s_setprio 0
	s_barrier
	s_mov_b32 m0, s25
	s_mov_b32 s18, s14
	s_mov_b32 s19, s15
	ds_read_b128 v[168:171], v212 offset:16384
	ds_read_b128 v[172:175], v212 offset:17408
	ds_read_b128 v[176:179], v212 offset:18432
	ds_read_b128 v[180:183], v212 offset:19456
	ds_read_b128 v[184:187], v212 offset:20480
	ds_read_b128 v[188:191], v212 offset:21504
	ds_read_b128 v[192:195], v212 offset:22528
	ds_read_b128 v[196:199], v212 offset:23552
	buffer_load_dwordx4 v209, s[16:19], s82 offen lds
	s_add_i32 s83, s82, 0x158000
	s_mov_b32 m0, s27
	s_nop 0
	buffer_load_dwordx4 v209, s[16:19], s83 offen lds
	s_add_i32 s83, s82, 0x2b0000
	s_mov_b32 m0, s30
	s_nop 0
	buffer_load_dwordx4 v209, s[16:19], s83 offen lds
	s_add_i32 s83, s82, 0x408000
	s_mov_b32 m0, s31
	s_nop 0
	buffer_load_dwordx4 v209, s[16:19], s83 offen lds
	s_mov_b32 m0, s21
	s_add_i32 s83, s80, 0x158000
	buffer_load_dwordx4 v208, s[12:15], s80 offen lds
	s_mov_b32 m0, s48
	s_nop 0
	buffer_load_dwordx4 v208, s[12:15], s83 offen lds
	s_waitcnt vmcnt(8)
	s_waitcnt lgkmcnt(0)
	s_setprio 1
	v_mfma_f32_16x16x32_bf16 v[62:65], v[134:137], v[168:171], v[62:65]
	s_barrier
	v_mfma_f32_16x16x32_bf16 v[62:65], v[138:141], v[172:175], v[62:65]
	v_mfma_f32_16x16x32_bf16 v[58:61], v[142:145], v[168:171], v[58:61]
	v_mfma_f32_16x16x32_bf16 v[58:61], v[148:151], v[172:175], v[58:61]
	v_mfma_f32_16x16x32_bf16 v[50:53], v[142:145], v[176:179], v[50:53]
	v_mfma_f32_16x16x32_bf16 v[50:53], v[148:151], v[180:183], v[50:53]
	v_mfma_f32_16x16x32_bf16 v[54:57], v[134:137], v[176:179], v[54:57]
	v_mfma_f32_16x16x32_bf16 v[54:57], v[138:141], v[180:183], v[54:57]
	v_mfma_f32_16x16x32_bf16 v[46:49], v[152:155], v[168:171], v[46:49]
	v_mfma_f32_16x16x32_bf16 v[46:49], v[156:159], v[172:175], v[46:49]
	v_mfma_f32_16x16x32_bf16 v[38:41], v[160:163], v[168:171], v[38:41]
	v_mfma_f32_16x16x32_bf16 v[38:41], v[164:167], v[172:175], v[38:41]
	v_mfma_f32_16x16x32_bf16 v[22:25], v[160:163], v[176:179], v[22:25]
	v_mfma_f32_16x16x32_bf16 v[22:25], v[164:167], v[180:183], v[22:25]
	v_mfma_f32_16x16x32_bf16 v[30:33], v[152:155], v[176:179], v[30:33]
	v_mfma_f32_16x16x32_bf16 v[30:33], v[156:159], v[180:183], v[30:33]
	v_mfma_f32_16x16x32_bf16 v[42:45], v[134:137], v[184:187], v[42:45]
	v_mfma_f32_16x16x32_bf16 v[42:45], v[138:141], v[188:191], v[42:45]
	v_mfma_f32_16x16x32_bf16 v[34:37], v[142:145], v[184:187], v[34:37]
	v_mfma_f32_16x16x32_bf16 v[34:37], v[148:151], v[188:191], v[34:37]
	v_mfma_f32_16x16x32_bf16 v[18:21], v[142:145], v[192:195], v[18:21]
	v_mfma_f32_16x16x32_bf16 v[18:21], v[148:151], v[196:199], v[18:21]
	v_mfma_f32_16x16x32_bf16 v[26:29], v[134:137], v[192:195], v[26:29]
	v_mfma_f32_16x16x32_bf16 v[26:29], v[138:141], v[196:199], v[26:29]
	v_mfma_f32_16x16x32_bf16 v[14:17], v[152:155], v[184:187], v[14:17]
	v_mfma_f32_16x16x32_bf16 v[14:17], v[156:159], v[188:191], v[14:17]
	v_mfma_f32_16x16x32_bf16 v[10:13], v[160:163], v[184:187], v[10:13]
	v_mfma_f32_16x16x32_bf16 v[10:13], v[164:167], v[188:191], v[10:13]
	v_mfma_f32_16x16x32_bf16 v[2:5], v[160:163], v[192:195], v[2:5]
	v_mfma_f32_16x16x32_bf16 v[2:5], v[164:167], v[196:199], v[2:5]
	v_mfma_f32_16x16x32_bf16 v[6:9], v[152:155], v[192:195], v[6:9]
	v_mfma_f32_16x16x32_bf16 v[6:9], v[156:159], v[196:199], v[6:9]
	s_setprio 0
	s_barrier
	ds_read_b128 v[134:137], v213
	ds_read_b128 v[138:141], v213 offset:1024
	ds_read_b128 v[142:145], v213 offset:2048
	ds_read_b128 v[148:151], v213 offset:3072
	ds_read_b128 v[152:155], v214
	ds_read_b128 v[156:159], v214 offset:1024
	ds_read_b128 v[160:163], v214 offset:2048
	ds_read_b128 v[164:167], v214 offset:3072
	s_mov_b32 m0, s49
	s_add_i32 s83, s80, 0x2b0000
	ds_read_b128 v[168:171], v212 offset:32768
	ds_read_b128 v[172:175], v212 offset:33792
	ds_read_b128 v[176:179], v212 offset:34816
	ds_read_b128 v[180:183], v212 offset:35840
	ds_read_b128 v[184:187], v212 offset:36864
	ds_read_b128 v[188:191], v212 offset:37888
	ds_read_b128 v[192:195], v212 offset:38912
	ds_read_b128 v[196:199], v212 offset:39936
	buffer_load_dwordx4 v208, s[12:15], s83 offen lds
	s_add_i32 s83, s80, 0x408000
	s_mov_b32 m0, s50
	s_nop 0
	buffer_load_dwordx4 v208, s[12:15], s83 offen lds
	s_waitcnt vmcnt(8)
	s_waitcnt lgkmcnt(0)
	s_setprio 1
	v_mfma_f32_16x16x32_bf16 v[126:129], v[134:137], v[168:171], v[126:129]
	s_barrier
	v_mfma_f32_16x16x32_bf16 v[126:129], v[138:141], v[172:175], v[126:129]
	v_mfma_f32_16x16x32_bf16 v[122:125], v[142:145], v[168:171], v[122:125]
	v_mfma_f32_16x16x32_bf16 v[122:125], v[148:151], v[172:175], v[122:125]
	v_mfma_f32_16x16x32_bf16 v[114:117], v[142:145], v[176:179], v[114:117]
	v_mfma_f32_16x16x32_bf16 v[114:117], v[148:151], v[180:183], v[114:117]
	v_mfma_f32_16x16x32_bf16 v[118:121], v[134:137], v[176:179], v[118:121]
	v_mfma_f32_16x16x32_bf16 v[118:121], v[138:141], v[180:183], v[118:121]
	v_mfma_f32_16x16x32_bf16 v[110:113], v[152:155], v[168:171], v[110:113]
	v_mfma_f32_16x16x32_bf16 v[110:113], v[156:159], v[172:175], v[110:113]
	v_mfma_f32_16x16x32_bf16 v[102:105], v[160:163], v[168:171], v[102:105]
	v_mfma_f32_16x16x32_bf16 v[102:105], v[164:167], v[172:175], v[102:105]
	v_mfma_f32_16x16x32_bf16 v[86:89], v[160:163], v[176:179], v[86:89]
	v_mfma_f32_16x16x32_bf16 v[86:89], v[164:167], v[180:183], v[86:89]
	v_mfma_f32_16x16x32_bf16 v[94:97], v[152:155], v[176:179], v[94:97]
	v_mfma_f32_16x16x32_bf16 v[94:97], v[156:159], v[180:183], v[94:97]
	v_mfma_f32_16x16x32_bf16 v[106:109], v[134:137], v[184:187], v[106:109]
	v_mfma_f32_16x16x32_bf16 v[106:109], v[138:141], v[188:191], v[106:109]
	v_mfma_f32_16x16x32_bf16 v[98:101], v[142:145], v[184:187], v[98:101]
	v_mfma_f32_16x16x32_bf16 v[98:101], v[148:151], v[188:191], v[98:101]
	v_mfma_f32_16x16x32_bf16 v[82:85], v[142:145], v[192:195], v[82:85]
	v_mfma_f32_16x16x32_bf16 v[82:85], v[148:151], v[196:199], v[82:85]
	v_mfma_f32_16x16x32_bf16 v[90:93], v[134:137], v[192:195], v[90:93]
	v_mfma_f32_16x16x32_bf16 v[90:93], v[138:141], v[196:199], v[90:93]
	v_mfma_f32_16x16x32_bf16 v[78:81], v[152:155], v[184:187], v[78:81]
	v_mfma_f32_16x16x32_bf16 v[78:81], v[156:159], v[188:191], v[78:81]
	v_mfma_f32_16x16x32_bf16 v[74:77], v[160:163], v[184:187], v[74:77]
	v_mfma_f32_16x16x32_bf16 v[74:77], v[164:167], v[188:191], v[74:77]
	v_mfma_f32_16x16x32_bf16 v[66:69], v[160:163], v[192:195], v[66:69]
	v_mfma_f32_16x16x32_bf16 v[66:69], v[164:167], v[196:199], v[66:69]
	v_mfma_f32_16x16x32_bf16 v[70:73], v[152:155], v[192:195], v[70:73]
	v_mfma_f32_16x16x32_bf16 v[70:73], v[156:159], v[196:199], v[70:73]
	s_setprio 0
	s_barrier
	s_mov_b32 m0, s54
	s_or_b32 s83, s82, 0x80
	ds_read_b128 v[168:171], v212 offset:49152
	ds_read_b128 v[172:175], v212 offset:50176
	ds_read_b128 v[176:179], v212 offset:51200
	ds_read_b128 v[180:183], v212 offset:52224
	ds_read_b128 v[184:187], v212 offset:53248
	ds_read_b128 v[188:191], v212 offset:54272
	ds_read_b128 v[192:195], v212 offset:55296
	ds_read_b128 v[196:199], v212 offset:56320
	buffer_load_dwordx4 v209, s[16:19], s83 offen lds
	s_add_i32 s83, s82, 0x158080
	s_mov_b32 m0, s55
	s_add_i32 s80, s80, 0x158080
	buffer_load_dwordx4 v209, s[16:19], s83 offen lds
	s_add_i32 s83, s82, 0x2b0080
	s_mov_b32 m0, s58
	s_add_i32 s82, s82, 0x408080
	buffer_load_dwordx4 v209, s[16:19], s83 offen lds
	s_mov_b32 m0, s59
	s_nop 0
	buffer_load_dwordx4 v209, s[16:19], s82 offen lds
	s_mov_b32 m0, s56
	s_nop 0
	buffer_load_dwordx4 v208, s[12:15], s81 offen lds
	s_mov_b32 m0, s57
	s_nop 0
	buffer_load_dwordx4 v208, s[12:15], s80 offen lds
	s_waitcnt vmcnt(8)
	s_waitcnt lgkmcnt(0)
	s_setprio 1
	v_mfma_f32_16x16x32_bf16 v[62:65], v[134:137], v[168:171], v[62:65]
	s_barrier
	v_mfma_f32_16x16x32_bf16 v[62:65], v[138:141], v[172:175], v[62:65]
	v_mfma_f32_16x16x32_bf16 v[58:61], v[142:145], v[168:171], v[58:61]
	v_mfma_f32_16x16x32_bf16 v[58:61], v[148:151], v[172:175], v[58:61]
	v_mfma_f32_16x16x32_bf16 v[50:53], v[142:145], v[176:179], v[50:53]
	v_mfma_f32_16x16x32_bf16 v[50:53], v[148:151], v[180:183], v[50:53]
	v_mfma_f32_16x16x32_bf16 v[54:57], v[134:137], v[176:179], v[54:57]
	v_mfma_f32_16x16x32_bf16 v[54:57], v[138:141], v[180:183], v[54:57]
	v_mfma_f32_16x16x32_bf16 v[46:49], v[152:155], v[168:171], v[46:49]
	v_mfma_f32_16x16x32_bf16 v[46:49], v[156:159], v[172:175], v[46:49]
	v_mfma_f32_16x16x32_bf16 v[38:41], v[160:163], v[168:171], v[38:41]
	v_mfma_f32_16x16x32_bf16 v[38:41], v[164:167], v[172:175], v[38:41]
	v_mfma_f32_16x16x32_bf16 v[22:25], v[160:163], v[176:179], v[22:25]
	v_mfma_f32_16x16x32_bf16 v[22:25], v[164:167], v[180:183], v[22:25]
	v_mfma_f32_16x16x32_bf16 v[30:33], v[152:155], v[176:179], v[30:33]
	v_mfma_f32_16x16x32_bf16 v[30:33], v[156:159], v[180:183], v[30:33]
	v_mfma_f32_16x16x32_bf16 v[42:45], v[134:137], v[184:187], v[42:45]
	v_mfma_f32_16x16x32_bf16 v[42:45], v[138:141], v[188:191], v[42:45]
	v_mfma_f32_16x16x32_bf16 v[34:37], v[142:145], v[184:187], v[34:37]
	v_mfma_f32_16x16x32_bf16 v[34:37], v[148:151], v[188:191], v[34:37]
	v_mfma_f32_16x16x32_bf16 v[18:21], v[142:145], v[192:195], v[18:21]
	v_mfma_f32_16x16x32_bf16 v[18:21], v[148:151], v[196:199], v[18:21]
	v_mfma_f32_16x16x32_bf16 v[26:29], v[134:137], v[192:195], v[26:29]
	v_mfma_f32_16x16x32_bf16 v[26:29], v[138:141], v[196:199], v[26:29]
	v_mfma_f32_16x16x32_bf16 v[14:17], v[152:155], v[184:187], v[14:17]
	v_mfma_f32_16x16x32_bf16 v[14:17], v[156:159], v[188:191], v[14:17]
	v_mfma_f32_16x16x32_bf16 v[10:13], v[160:163], v[184:187], v[10:13]
	v_mfma_f32_16x16x32_bf16 v[10:13], v[164:167], v[188:191], v[10:13]
	v_mfma_f32_16x16x32_bf16 v[2:5], v[160:163], v[192:195], v[2:5]
	v_mfma_f32_16x16x32_bf16 v[2:5], v[164:167], v[196:199], v[2:5]
	v_mfma_f32_16x16x32_bf16 v[6:9], v[152:155], v[192:195], v[6:9]
	v_mfma_f32_16x16x32_bf16 v[6:9], v[156:159], v[196:199], v[6:9]
	s_setprio 0
	s_barrier
	s_add_i32 s79, s79, 2
	s_addk_i32 s77, 0x100
	s_addk_i32 s78, 0x100
	s_cmp_ge_i32 s79, s3
	s_cbranch_scc0 .LBB0_799
	v_pk_mul_f32 v[184:185], v[128:129], 0.5 op_sel_hi:[1,0]
	v_pk_mul_f32 v[186:187], v[126:127], 0.5 op_sel_hi:[1,0]
	v_pk_mul_f32 v[188:189], v[124:125], 0.5 op_sel_hi:[1,0]
	v_pk_mul_f32 v[190:191], v[122:123], 0.5 op_sel_hi:[1,0]
	v_pk_mul_f32 v[198:199], v[112:113], 0.5 op_sel_hi:[1,0]
	v_pk_mul_f32 v[196:197], v[110:111], 0.5 op_sel_hi:[1,0]
	v_pk_mul_f32 v[194:195], v[104:105], 0.5 op_sel_hi:[1,0]
	v_pk_mul_f32 v[192:193], v[102:103], 0.5 op_sel_hi:[1,0]
	v_pk_mul_f32 v[182:183], v[120:121], 0.5 op_sel_hi:[1,0]
	v_pk_mul_f32 v[180:181], v[118:119], 0.5 op_sel_hi:[1,0]
	v_pk_mul_f32 v[178:179], v[116:117], 0.5 op_sel_hi:[1,0]
	v_pk_mul_f32 v[176:177], v[114:115], 0.5 op_sel_hi:[1,0]
	v_pk_mul_f32 v[172:173], v[96:97], 0.5 op_sel_hi:[1,0]
	v_pk_mul_f32 v[170:171], v[94:95], 0.5 op_sel_hi:[1,0]
	v_pk_mul_f32 v[168:169], v[88:89], 0.5 op_sel_hi:[1,0]
	v_pk_mul_f32 v[166:167], v[86:87], 0.5 op_sel_hi:[1,0]
	v_pk_mul_f32 v[164:165], v[108:109], 0.5 op_sel_hi:[1,0]
	v_pk_mul_f32 v[162:163], v[106:107], 0.5 op_sel_hi:[1,0]
	v_pk_mul_f32 v[160:161], v[100:101], 0.5 op_sel_hi:[1,0]
	v_pk_mul_f32 v[158:159], v[98:99], 0.5 op_sel_hi:[1,0]
	v_pk_mul_f32 v[156:157], v[80:81], 0.5 op_sel_hi:[1,0]
	v_pk_mul_f32 v[154:155], v[78:79], 0.5 op_sel_hi:[1,0]
	v_pk_mul_f32 v[152:153], v[76:77], 0.5 op_sel_hi:[1,0]
	v_pk_mul_f32 v[150:151], v[74:75], 0.5 op_sel_hi:[1,0]
	v_pk_mul_f32 v[144:145], v[92:93], 0.5 op_sel_hi:[1,0]
	v_pk_mul_f32 v[142:143], v[90:91], 0.5 op_sel_hi:[1,0]
	v_pk_mul_f32 v[140:141], v[84:85], 0.5 op_sel_hi:[1,0]
	v_pk_mul_f32 v[138:139], v[82:83], 0.5 op_sel_hi:[1,0]
	v_pk_mul_f32 v[136:137], v[72:73], 0.5 op_sel_hi:[1,0]
	v_pk_mul_f32 v[134:135], v[70:71], 0.5 op_sel_hi:[1,0]
	v_pk_mul_f32 v[128:129], v[68:69], 0.5 op_sel_hi:[1,0]
	v_pk_mul_f32 v[126:127], v[66:67], 0.5 op_sel_hi:[1,0]
	v_pk_mul_f32 v[122:123], v[64:65], 0.5 op_sel_hi:[1,0]
	v_pk_mul_f32 v[120:121], v[62:63], 0.5 op_sel_hi:[1,0]
	v_pk_mul_f32 v[118:119], v[60:61], 0.5 op_sel_hi:[1,0]
	v_pk_mul_f32 v[116:117], v[58:59], 0.5 op_sel_hi:[1,0]
	v_pk_mul_f32 v[112:113], v[48:49], 0.5 op_sel_hi:[1,0]
	v_pk_mul_f32 v[110:111], v[46:47], 0.5 op_sel_hi:[1,0]
	v_pk_mul_f32 v[108:109], v[40:41], 0.5 op_sel_hi:[1,0]
	v_pk_mul_f32 v[106:107], v[38:39], 0.5 op_sel_hi:[1,0]
	v_pk_mul_f32 v[104:105], v[56:57], 0.5 op_sel_hi:[1,0]
	v_pk_mul_f32 v[102:103], v[54:55], 0.5 op_sel_hi:[1,0]
	v_pk_mul_f32 v[100:101], v[52:53], 0.5 op_sel_hi:[1,0]
	v_pk_mul_f32 v[98:99], v[50:51], 0.5 op_sel_hi:[1,0]
	v_pk_mul_f32 v[96:97], v[32:33], 0.5 op_sel_hi:[1,0]
	v_pk_mul_f32 v[94:95], v[30:31], 0.5 op_sel_hi:[1,0]
	v_pk_mul_f32 v[92:93], v[24:25], 0.5 op_sel_hi:[1,0]
	v_pk_mul_f32 v[90:91], v[22:23], 0.5 op_sel_hi:[1,0]
	v_pk_mul_f32 v[88:89], v[44:45], 0.5 op_sel_hi:[1,0]
	v_pk_mul_f32 v[86:87], v[42:43], 0.5 op_sel_hi:[1,0]
	v_pk_mul_f32 v[84:85], v[36:37], 0.5 op_sel_hi:[1,0]
	v_pk_mul_f32 v[82:83], v[34:35], 0.5 op_sel_hi:[1,0]
	v_pk_mul_f32 v[80:81], v[16:17], 0.5 op_sel_hi:[1,0]
	v_pk_mul_f32 v[78:79], v[14:15], 0.5 op_sel_hi:[1,0]
	v_pk_mul_f32 v[76:77], v[12:13], 0.5 op_sel_hi:[1,0]
	v_pk_mul_f32 v[74:75], v[10:11], 0.5 op_sel_hi:[1,0]
	v_pk_mul_f32 v[72:73], v[28:29], 0.5 op_sel_hi:[1,0]
	v_pk_mul_f32 v[70:71], v[26:27], 0.5 op_sel_hi:[1,0]
	v_pk_mul_f32 v[68:69], v[20:21], 0.5 op_sel_hi:[1,0]
	v_pk_mul_f32 v[66:67], v[18:19], 0.5 op_sel_hi:[1,0]
	v_pk_mul_f32 v[64:65], v[8:9], 0.5 op_sel_hi:[1,0]
	v_pk_mul_f32 v[62:63], v[6:7], 0.5 op_sel_hi:[1,0]
	v_pk_mul_f32 v[60:61], v[4:5], 0.5 op_sel_hi:[1,0]
	v_pk_mul_f32 v[58:59], v[2:3], 0.5 op_sel_hi:[1,0]
	s_and_b64 vcc, exec, s[38:39]
	s_cbranch_vccz .LBB0_802

.LBB0_892:
	ds_read_b128 v[130:133], v172
	ds_read_b128 v[134:137], v172 offset:1024
	ds_read_b128 v[148:151], v172 offset:2048
	ds_read_b128 v[152:155], v172 offset:3072
	ds_read_b128 v[156:159], v173
	ds_read_b128 v[160:163], v173 offset:1024
	ds_read_b128 v[164:167], v173 offset:2048
	ds_read_b128 v[180:183], v173 offset:3072
	s_add_i32 s18, s8, 0xffe80080
	s_cmp_eq_u32 s77, s52
	s_cselect_b32 s53, s6, s18
	s_cselect_b32 s58, s7, s9
	s_or_b32 s57, s53, 0x80
	s_add_i32 s18, s8, 0xfff80000
	s_mov_b32 m0, s78
	ds_read_b128 v[184:187], v174
	ds_read_b128 v[188:191], v174 offset:1024
	ds_read_b128 v[192:195], v174 offset:2048
	ds_read_b128 v[196:199], v174 offset:3072
	ds_read_b128 v[200:203], v174 offset:4096
	ds_read_b128 v[204:207], v174 offset:5120
	ds_read_b128 v[208:211], v174 offset:6144
	ds_read_b128 v[212:215], v174 offset:7168
	buffer_load_dwordx4 v170, s[12:15], s18 offen lds
	s_mov_b32 m0, s79
	s_nop 0
	buffer_load_dwordx4 v170, s[12:15], s8 offen lds
	s_waitcnt vmcnt(8)
	s_waitcnt lgkmcnt(0)
	s_setprio 1
	v_mfma_f32_16x16x32_bf16 v[126:129], v[130:133], v[184:187], v[126:129]
	s_barrier
	v_mfma_f32_16x16x32_bf16 v[126:129], v[134:137], v[188:191], v[126:129]
	v_mfma_f32_16x16x32_bf16 v[118:121], v[148:151], v[184:187], v[118:121]
	v_mfma_f32_16x16x32_bf16 v[118:121], v[152:155], v[188:191], v[118:121]
	v_mfma_f32_16x16x32_bf16 v[102:105], v[148:151], v[192:195], v[102:105]
	v_mfma_f32_16x16x32_bf16 v[102:105], v[152:155], v[196:199], v[102:105]
	v_mfma_f32_16x16x32_bf16 v[110:113], v[130:133], v[192:195], v[110:113]
	v_mfma_f32_16x16x32_bf16 v[110:113], v[134:137], v[196:199], v[110:113]
	v_mfma_f32_16x16x32_bf16 v[122:125], v[156:159], v[184:187], v[122:125]
	v_mfma_f32_16x16x32_bf16 v[122:125], v[160:163], v[188:191], v[122:125]
	v_mfma_f32_16x16x32_bf16 v[114:117], v[164:167], v[184:187], v[114:117]
	v_mfma_f32_16x16x32_bf16 v[114:117], v[180:183], v[188:191], v[114:117]
	v_mfma_f32_16x16x32_bf16 v[98:101], v[164:167], v[192:195], v[98:101]
	v_mfma_f32_16x16x32_bf16 v[98:101], v[180:183], v[196:199], v[98:101]
	v_mfma_f32_16x16x32_bf16 v[106:109], v[156:159], v[192:195], v[106:109]
	v_mfma_f32_16x16x32_bf16 v[106:109], v[160:163], v[196:199], v[106:109]
	v_mfma_f32_16x16x32_bf16 v[94:97], v[130:133], v[200:203], v[94:97]
	v_mfma_f32_16x16x32_bf16 v[94:97], v[134:137], v[204:207], v[94:97]
	v_mfma_f32_16x16x32_bf16 v[90:93], v[148:151], v[200:203], v[90:93]
	v_mfma_f32_16x16x32_bf16 v[90:93], v[152:155], v[204:207], v[90:93]
	v_mfma_f32_16x16x32_bf16 v[70:73], v[148:151], v[208:211], v[70:73]
	v_mfma_f32_16x16x32_bf16 v[70:73], v[152:155], v[212:215], v[70:73]
	v_mfma_f32_16x16x32_bf16 v[78:81], v[130:133], v[208:211], v[78:81]
	v_mfma_f32_16x16x32_bf16 v[78:81], v[134:137], v[212:215], v[78:81]
	v_mfma_f32_16x16x32_bf16 v[86:89], v[156:159], v[200:203], v[86:89]
	v_mfma_f32_16x16x32_bf16 v[86:89], v[160:163], v[204:207], v[86:89]
	v_mfma_f32_16x16x32_bf16 v[82:85], v[164:167], v[200:203], v[82:85]
	v_mfma_f32_16x16x32_bf16 v[82:85], v[180:183], v[204:207], v[82:85]
	v_mfma_f32_16x16x32_bf16 v[66:69], v[164:167], v[208:211], v[66:69]
	v_mfma_f32_16x16x32_bf16 v[66:69], v[180:183], v[212:215], v[66:69]
	v_mfma_f32_16x16x32_bf16 v[74:77], v[156:159], v[208:211], v[74:77]
	v_mfma_f32_16x16x32_bf16 v[74:77], v[160:163], v[212:215], v[74:77]
	s_setprio 0
	s_barrier
	s_mov_b32 m0, s27
	s_mov_b32 s18, s14
	s_mov_b32 s19, s15
	ds_read_b128 v[184:187], v174 offset:16384
	ds_read_b128 v[188:191], v174 offset:17408
	ds_read_b128 v[192:195], v174 offset:18432
	ds_read_b128 v[196:199], v174 offset:19456
	ds_read_b128 v[200:203], v174 offset:20480
	ds_read_b128 v[204:207], v174 offset:21504
	ds_read_b128 v[208:211], v174 offset:22528
	ds_read_b128 v[212:215], v174 offset:23552
	buffer_load_dwordx4 v171, s[16:19], s58 offen lds
	s_add_i32 s59, s58, 0x80000
	s_mov_b32 m0, s60
	s_nop 0
	buffer_load_dwordx4 v171, s[16:19], s59 offen lds
	s_add_i32 s59, s58, 0x100000
	s_mov_b32 m0, s61
	s_nop 0
	buffer_load_dwordx4 v171, s[16:19], s59 offen lds
	s_add_i32 s59, s58, 0x180000
	s_mov_b32 m0, s62
	s_nop 0
	buffer_load_dwordx4 v171, s[16:19], s59 offen lds
	s_mov_b32 m0, s25
	s_add_i32 s59, s53, 0x80000
	buffer_load_dwordx4 v170, s[12:15], s53 offen lds
	s_mov_b32 m0, s63
	s_nop 0
	buffer_load_dwordx4 v170, s[12:15], s59 offen lds
	s_waitcnt vmcnt(8)
	s_waitcnt lgkmcnt(0)
	s_setprio 1
	v_mfma_f32_16x16x32_bf16 v[62:65], v[130:133], v[184:187], v[62:65]
	s_barrier
	v_mfma_f32_16x16x32_bf16 v[62:65], v[134:137], v[188:191], v[62:65]
	v_mfma_f32_16x16x32_bf16 v[54:57], v[148:151], v[184:187], v[54:57]
	v_mfma_f32_16x16x32_bf16 v[54:57], v[152:155], v[188:191], v[54:57]
	v_mfma_f32_16x16x32_bf16 v[38:41], v[148:151], v[192:195], v[38:41]
	v_mfma_f32_16x16x32_bf16 v[38:41], v[152:155], v[196:199], v[38:41]
	v_mfma_f32_16x16x32_bf16 v[46:49], v[130:133], v[192:195], v[46:49]
	v_mfma_f32_16x16x32_bf16 v[46:49], v[134:137], v[196:199], v[46:49]
	v_mfma_f32_16x16x32_bf16 v[58:61], v[156:159], v[184:187], v[58:61]
	v_mfma_f32_16x16x32_bf16 v[58:61], v[160:163], v[188:191], v[58:61]
	v_mfma_f32_16x16x32_bf16 v[50:53], v[164:167], v[184:187], v[50:53]
	v_mfma_f32_16x16x32_bf16 v[50:53], v[180:183], v[188:191], v[50:53]
	v_mfma_f32_16x16x32_bf16 v[34:37], v[164:167], v[192:195], v[34:37]
	v_mfma_f32_16x16x32_bf16 v[34:37], v[180:183], v[196:199], v[34:37]
	v_mfma_f32_16x16x32_bf16 v[42:45], v[156:159], v[192:195], v[42:45]
	v_mfma_f32_16x16x32_bf16 v[42:45], v[160:163], v[196:199], v[42:45]
	v_mfma_f32_16x16x32_bf16 v[30:33], v[130:133], v[200:203], v[30:33]
	v_mfma_f32_16x16x32_bf16 v[30:33], v[134:137], v[204:207], v[30:33]
	v_mfma_f32_16x16x32_bf16 v[22:25], v[148:151], v[200:203], v[22:25]
	v_mfma_f32_16x16x32_bf16 v[22:25], v[152:155], v[204:207], v[22:25]
	v_mfma_f32_16x16x32_bf16 v[6:9], v[148:151], v[208:211], v[6:9]
	v_mfma_f32_16x16x32_bf16 v[6:9], v[152:155], v[212:215], v[6:9]
	v_mfma_f32_16x16x32_bf16 v[14:17], v[130:133], v[208:211], v[14:17]
	v_mfma_f32_16x16x32_bf16 v[14:17], v[134:137], v[212:215], v[14:17]
	v_mfma_f32_16x16x32_bf16 v[26:29], v[156:159], v[200:203], v[26:29]
	v_mfma_f32_16x16x32_bf16 v[26:29], v[160:163], v[204:207], v[26:29]
	v_mfma_f32_16x16x32_bf16 v[18:21], v[164:167], v[200:203], v[18:21]
	v_mfma_f32_16x16x32_bf16 v[18:21], v[180:183], v[204:207], v[18:21]
	v_mfma_f32_16x16x32_bf16 v[2:5], v[164:167], v[208:211], v[2:5]
	v_mfma_f32_16x16x32_bf16 v[2:5], v[180:183], v[212:215], v[2:5]
	v_mfma_f32_16x16x32_bf16 v[10:13], v[156:159], v[208:211], v[10:13]
	v_mfma_f32_16x16x32_bf16 v[10:13], v[160:163], v[212:215], v[10:13]
	s_setprio 0
	s_barrier
	ds_read_b128 v[130:133], v175
	ds_read_b128 v[134:137], v175 offset:1024
	ds_read_b128 v[148:151], v175 offset:2048
	ds_read_b128 v[152:155], v175 offset:3072
	ds_read_b128 v[156:159], v176
	ds_read_b128 v[160:163], v176 offset:1024
	ds_read_b128 v[164:167], v176 offset:2048
	ds_read_b128 v[180:183], v176 offset:3072
	s_mov_b32 m0, s64
	s_add_i32 s59, s53, 0x100000
	ds_read_b128 v[184:187], v174 offset:32768
	ds_read_b128 v[188:191], v174 offset:33792
	ds_read_b128 v[192:195], v174 offset:34816
	ds_read_b128 v[196:199], v174 offset:35840
	ds_read_b128 v[200:203], v174 offset:36864
	ds_read_b128 v[204:207], v174 offset:37888
	ds_read_b128 v[208:211], v174 offset:38912
	ds_read_b128 v[212:215], v174 offset:39936
	buffer_load_dwordx4 v170, s[12:15], s59 offen lds
	s_add_i32 s59, s53, 0x180000
	s_mov_b32 m0, s65
	s_nop 0
	buffer_load_dwordx4 v170, s[12:15], s59 offen lds
	s_waitcnt vmcnt(8)
	s_waitcnt lgkmcnt(0)
	s_setprio 1
	v_mfma_f32_16x16x32_bf16 v[126:129], v[130:133], v[184:187], v[126:129]
	s_barrier
	v_mfma_f32_16x16x32_bf16 v[126:129], v[134:137], v[188:191], v[126:129]
	v_mfma_f32_16x16x32_bf16 v[118:121], v[148:151], v[184:187], v[118:121]
	v_mfma_f32_16x16x32_bf16 v[118:121], v[152:155], v[188:191], v[118:121]
	v_mfma_f32_16x16x32_bf16 v[102:105], v[148:151], v[192:195], v[102:105]
	v_mfma_f32_16x16x32_bf16 v[102:105], v[152:155], v[196:199], v[102:105]
	v_mfma_f32_16x16x32_bf16 v[110:113], v[130:133], v[192:195], v[110:113]
	v_mfma_f32_16x16x32_bf16 v[110:113], v[134:137], v[196:199], v[110:113]
	v_mfma_f32_16x16x32_bf16 v[122:125], v[156:159], v[184:187], v[122:125]
	v_mfma_f32_16x16x32_bf16 v[122:125], v[160:163], v[188:191], v[122:125]
	v_mfma_f32_16x16x32_bf16 v[114:117], v[164:167], v[184:187], v[114:117]
	v_mfma_f32_16x16x32_bf16 v[114:117], v[180:183], v[188:191], v[114:117]
	v_mfma_f32_16x16x32_bf16 v[98:101], v[164:167], v[192:195], v[98:101]
	v_mfma_f32_16x16x32_bf16 v[98:101], v[180:183], v[196:199], v[98:101]
	v_mfma_f32_16x16x32_bf16 v[106:109], v[156:159], v[192:195], v[106:109]
	v_mfma_f32_16x16x32_bf16 v[106:109], v[160:163], v[196:199], v[106:109]
	v_mfma_f32_16x16x32_bf16 v[94:97], v[130:133], v[200:203], v[94:97]
	v_mfma_f32_16x16x32_bf16 v[94:97], v[134:137], v[204:207], v[94:97]
	v_mfma_f32_16x16x32_bf16 v[90:93], v[148:151], v[200:203], v[90:93]
	v_mfma_f32_16x16x32_bf16 v[90:93], v[152:155], v[204:207], v[90:93]
	v_mfma_f32_16x16x32_bf16 v[70:73], v[148:151], v[208:211], v[70:73]
	v_mfma_f32_16x16x32_bf16 v[70:73], v[152:155], v[212:215], v[70:73]
	v_mfma_f32_16x16x32_bf16 v[78:81], v[130:133], v[208:211], v[78:81]
	v_mfma_f32_16x16x32_bf16 v[78:81], v[134:137], v[212:215], v[78:81]
	v_mfma_f32_16x16x32_bf16 v[86:89], v[156:159], v[200:203], v[86:89]
	v_mfma_f32_16x16x32_bf16 v[86:89], v[160:163], v[204:207], v[86:89]
	v_mfma_f32_16x16x32_bf16 v[82:85], v[164:167], v[200:203], v[82:85]
	v_mfma_f32_16x16x32_bf16 v[82:85], v[180:183], v[204:207], v[82:85]
	v_mfma_f32_16x16x32_bf16 v[66:69], v[164:167], v[208:211], v[66:69]
	v_mfma_f32_16x16x32_bf16 v[66:69], v[180:183], v[212:215], v[66:69]
	v_mfma_f32_16x16x32_bf16 v[74:77], v[156:159], v[208:211], v[74:77]
	v_mfma_f32_16x16x32_bf16 v[74:77], v[160:163], v[212:215], v[74:77]
	s_setprio 0
	s_barrier
	s_mov_b32 m0, s70
	s_or_b32 s59, s58, 0x80
	ds_read_b128 v[184:187], v174 offset:49152
	ds_read_b128 v[188:191], v174 offset:50176
	ds_read_b128 v[192:195], v174 offset:51200
	ds_read_b128 v[196:199], v174 offset:52224
	ds_read_b128 v[200:203], v174 offset:53248
	ds_read_b128 v[204:207], v174 offset:54272
	ds_read_b128 v[208:211], v174 offset:55296
	ds_read_b128 v[212:215], v174 offset:56320
	buffer_load_dwordx4 v171, s[16:19], s59 offen lds
	s_add_i32 s59, s58, 0x80080
	s_mov_b32 m0, s71
	s_add_i32 s53, s53, 0x80080
	buffer_load_dwordx4 v171, s[16:19], s59 offen lds
	s_add_i32 s59, s58, 0x100080
	s_mov_b32 m0, s74
	s_add_i32 s58, s58, 0x180080
	buffer_load_dwordx4 v171, s[16:19], s59 offen lds
	s_mov_b32 m0, s75
	s_nop 0
	buffer_load_dwordx4 v171, s[16:19], s58 offen lds
	s_mov_b32 m0, s72
	s_nop 0
	buffer_load_dwordx4 v170, s[12:15], s57 offen lds
	s_mov_b32 m0, s73
	s_nop 0
	buffer_load_dwordx4 v170, s[12:15], s53 offen lds
	s_waitcnt vmcnt(8)
	s_waitcnt lgkmcnt(0)
	s_setprio 1
	v_mfma_f32_16x16x32_bf16 v[62:65], v[130:133], v[184:187], v[62:65]
	s_barrier
	v_mfma_f32_16x16x32_bf16 v[62:65], v[134:137], v[188:191], v[62:65]
	v_mfma_f32_16x16x32_bf16 v[54:57], v[148:151], v[184:187], v[54:57]
	v_mfma_f32_16x16x32_bf16 v[54:57], v[152:155], v[188:191], v[54:57]
	v_mfma_f32_16x16x32_bf16 v[38:41], v[148:151], v[192:195], v[38:41]
	v_mfma_f32_16x16x32_bf16 v[38:41], v[152:155], v[196:199], v[38:41]
	v_mfma_f32_16x16x32_bf16 v[46:49], v[130:133], v[192:195], v[46:49]
	v_mfma_f32_16x16x32_bf16 v[46:49], v[134:137], v[196:199], v[46:49]
	v_mfma_f32_16x16x32_bf16 v[58:61], v[156:159], v[184:187], v[58:61]
	v_mfma_f32_16x16x32_bf16 v[58:61], v[160:163], v[188:191], v[58:61]
	v_mfma_f32_16x16x32_bf16 v[50:53], v[164:167], v[184:187], v[50:53]
	v_mfma_f32_16x16x32_bf16 v[50:53], v[180:183], v[188:191], v[50:53]
	v_mfma_f32_16x16x32_bf16 v[34:37], v[164:167], v[192:195], v[34:37]
	v_mfma_f32_16x16x32_bf16 v[34:37], v[180:183], v[196:199], v[34:37]
	v_mfma_f32_16x16x32_bf16 v[42:45], v[156:159], v[192:195], v[42:45]
	v_mfma_f32_16x16x32_bf16 v[42:45], v[160:163], v[196:199], v[42:45]
	v_mfma_f32_16x16x32_bf16 v[30:33], v[130:133], v[200:203], v[30:33]
	v_mfma_f32_16x16x32_bf16 v[30:33], v[134:137], v[204:207], v[30:33]
	v_mfma_f32_16x16x32_bf16 v[22:25], v[148:151], v[200:203], v[22:25]
	v_mfma_f32_16x16x32_bf16 v[22:25], v[152:155], v[204:207], v[22:25]
	v_mfma_f32_16x16x32_bf16 v[6:9], v[148:151], v[208:211], v[6:9]
	v_mfma_f32_16x16x32_bf16 v[6:9], v[152:155], v[212:215], v[6:9]
	v_mfma_f32_16x16x32_bf16 v[14:17], v[130:133], v[208:211], v[14:17]
	v_mfma_f32_16x16x32_bf16 v[14:17], v[134:137], v[212:215], v[14:17]
	v_mfma_f32_16x16x32_bf16 v[26:29], v[156:159], v[200:203], v[26:29]
	v_mfma_f32_16x16x32_bf16 v[26:29], v[160:163], v[204:207], v[26:29]
	v_mfma_f32_16x16x32_bf16 v[18:21], v[164:167], v[200:203], v[18:21]
	v_mfma_f32_16x16x32_bf16 v[18:21], v[180:183], v[204:207], v[18:21]
	v_mfma_f32_16x16x32_bf16 v[2:5], v[164:167], v[208:211], v[2:5]
	v_mfma_f32_16x16x32_bf16 v[2:5], v[180:183], v[212:215], v[2:5]
	v_mfma_f32_16x16x32_bf16 v[10:13], v[156:159], v[208:211], v[10:13]
	v_mfma_f32_16x16x32_bf16 v[10:13], v[160:163], v[212:215], v[10:13]
	s_setprio 0
	s_barrier
	s_add_i32 s52, s52, 2
	s_addk_i32 s8, 0x100
	s_addk_i32 s9, 0x100
	s_cmp_ge_i32 s52, s21
	s_cbranch_scc0 .LBB0_892
	s_and_b64 vcc, exec, s[48:49]
	s_cbranch_vccz .LBB0_895

.LBB0_1020:
	v_add_u32_e32 v142, 0x10000, v162
	v_add_u32_e32 v150, 0x14000, v162
	ds_read_b128 v[130:133], v142
	ds_read_b128 v[134:137], v142 offset:1024
	ds_read_b128 v[138:141], v142 offset:2048
	ds_read_b128 v[142:145], v142 offset:3072
	ds_read_b128 v[154:157], v150
	ds_read_b128 v[164:167], v150 offset:1024
	ds_read_b128 v[168:171], v150 offset:2048
	ds_read_b128 v[172:175], v150 offset:3072
	s_add_i32 s90, s6, 0x100
	s_add_i32 s7, s88, s6
	s_cmp_eq_u32 s81, s89
	s_cselect_b32 s91, 0, s90
	s_cselect_b32 s93, s87, s7
	s_add_i32 s91, s91, s70
	s_or_b32 s92, s91, 0x80
	s_add_i32 s6, s3, s6
	s_mov_b32 m0, s82
	s_add_i32 s7, s6, 0x20080
	ds_read_b128 v[176:179], v163
	ds_read_b128 v[180:183], v163 offset:1024
	ds_read_b128 v[184:187], v163 offset:2048
	ds_read_b128 v[188:191], v163 offset:3072
	ds_read_b128 v[192:195], v163 offset:4096
	ds_read_b128 v[196:199], v163 offset:5120
	ds_read_b128 v[200:203], v163 offset:6144
	ds_read_b128 v[204:207], v163 offset:7168
	buffer_load_dwordx4 v161, s[12:15], s7 offen lds
	s_add_i32 s6, s6, 0x30080
	s_mov_b32 m0, s83
	s_nop 0
	buffer_load_dwordx4 v161, s[12:15], s6 offen lds
	s_waitcnt vmcnt(8)
	s_waitcnt lgkmcnt(0)
	s_setprio 1
	v_mfma_f32_16x16x32_bf16 v[126:129], v[130:133], v[176:179], v[126:129]
	s_barrier
	v_mfma_f32_16x16x32_bf16 v[126:129], v[134:137], v[180:183], v[126:129]
	v_mfma_f32_16x16x32_bf16 v[122:125], v[138:141], v[176:179], v[122:125]
	v_mfma_f32_16x16x32_bf16 v[122:125], v[142:145], v[180:183], v[122:125]
	v_mfma_f32_16x16x32_bf16 v[106:109], v[138:141], v[184:187], v[106:109]
	v_mfma_f32_16x16x32_bf16 v[106:109], v[142:145], v[188:191], v[106:109]
	v_mfma_f32_16x16x32_bf16 v[110:113], v[130:133], v[184:187], v[110:113]
	v_mfma_f32_16x16x32_bf16 v[110:113], v[134:137], v[188:191], v[110:113]
	v_mfma_f32_16x16x32_bf16 v[118:121], v[154:157], v[176:179], v[118:121]
	v_mfma_f32_16x16x32_bf16 v[118:121], v[164:167], v[180:183], v[118:121]
	v_mfma_f32_16x16x32_bf16 v[114:117], v[168:171], v[176:179], v[114:117]
	v_mfma_f32_16x16x32_bf16 v[114:117], v[172:175], v[180:183], v[114:117]
	v_mfma_f32_16x16x32_bf16 v[98:101], v[168:171], v[184:187], v[98:101]
	v_mfma_f32_16x16x32_bf16 v[98:101], v[172:175], v[188:191], v[98:101]
	v_mfma_f32_16x16x32_bf16 v[102:105], v[154:157], v[184:187], v[102:105]
	v_mfma_f32_16x16x32_bf16 v[102:105], v[164:167], v[188:191], v[102:105]
	v_mfma_f32_16x16x32_bf16 v[94:97], v[130:133], v[192:195], v[94:97]
	v_mfma_f32_16x16x32_bf16 v[94:97], v[134:137], v[196:199], v[94:97]
	v_mfma_f32_16x16x32_bf16 v[90:93], v[138:141], v[192:195], v[90:93]
	v_mfma_f32_16x16x32_bf16 v[90:93], v[142:145], v[196:199], v[90:93]
	v_mfma_f32_16x16x32_bf16 v[74:77], v[138:141], v[200:203], v[74:77]
	v_mfma_f32_16x16x32_bf16 v[74:77], v[142:145], v[204:207], v[74:77]
	v_mfma_f32_16x16x32_bf16 v[78:81], v[130:133], v[200:203], v[78:81]
	v_mfma_f32_16x16x32_bf16 v[78:81], v[134:137], v[204:207], v[78:81]
	v_mfma_f32_16x16x32_bf16 v[86:89], v[154:157], v[192:195], v[86:89]
	v_mfma_f32_16x16x32_bf16 v[86:89], v[164:167], v[196:199], v[86:89]
	v_mfma_f32_16x16x32_bf16 v[82:85], v[168:171], v[192:195], v[82:85]
	v_mfma_f32_16x16x32_bf16 v[82:85], v[172:175], v[196:199], v[82:85]
	v_mfma_f32_16x16x32_bf16 v[66:69], v[168:171], v[200:203], v[66:69]
	v_mfma_f32_16x16x32_bf16 v[66:69], v[172:175], v[204:207], v[66:69]
	v_mfma_f32_16x16x32_bf16 v[70:73], v[154:157], v[200:203], v[70:73]
	v_mfma_f32_16x16x32_bf16 v[70:73], v[164:167], v[204:207], v[70:73]
	s_setprio 0
	s_barrier
	s_mov_b32 m0, s66
	s_mov_b32 s6, s14
	s_mov_b32 s7, s15
	ds_read_b128 v[176:179], v163 offset:16384
	ds_read_b128 v[180:183], v163 offset:17408
	ds_read_b128 v[184:187], v163 offset:18432
	ds_read_b128 v[188:191], v163 offset:19456
	ds_read_b128 v[192:195], v163 offset:20480
	ds_read_b128 v[196:199], v163 offset:21504
	ds_read_b128 v[200:203], v163 offset:22528
	ds_read_b128 v[204:207], v163 offset:23552
	buffer_load_dwordx4 v160, s[4:7], s93 offen lds
	s_add_i32 s94, s93, 0x10000
	s_mov_b32 m0, s67
	s_nop 0
	buffer_load_dwordx4 v160, s[4:7], s94 offen lds
	s_add_i32 s94, s93, 0x20000
	s_mov_b32 m0, s68
	s_nop 0
	buffer_load_dwordx4 v160, s[4:7], s94 offen lds
	s_add_i32 s94, s93, 0x30000
	s_mov_b32 m0, s69
	s_nop 0
	buffer_load_dwordx4 v160, s[4:7], s94 offen lds
	s_mov_b32 m0, s65
	s_add_i32 s94, s91, 0x10000
	buffer_load_dwordx4 v161, s[12:15], s91 offen lds
	s_mov_b32 m0, s71
	s_nop 0
	buffer_load_dwordx4 v161, s[12:15], s94 offen lds
	s_waitcnt vmcnt(8)
	s_waitcnt lgkmcnt(0)
	s_setprio 1
	v_mfma_f32_16x16x32_bf16 v[62:65], v[130:133], v[176:179], v[62:65]
	s_barrier
	v_mfma_f32_16x16x32_bf16 v[62:65], v[134:137], v[180:183], v[62:65]
	v_mfma_f32_16x16x32_bf16 v[58:61], v[138:141], v[176:179], v[58:61]
	v_mfma_f32_16x16x32_bf16 v[58:61], v[142:145], v[180:183], v[58:61]
	v_mfma_f32_16x16x32_bf16 v[42:45], v[138:141], v[184:187], v[42:45]
	v_mfma_f32_16x16x32_bf16 v[42:45], v[142:145], v[188:191], v[42:45]
	v_mfma_f32_16x16x32_bf16 v[46:49], v[130:133], v[184:187], v[46:49]
	v_mfma_f32_16x16x32_bf16 v[46:49], v[134:137], v[188:191], v[46:49]
	v_mfma_f32_16x16x32_bf16 v[54:57], v[154:157], v[176:179], v[54:57]
	v_mfma_f32_16x16x32_bf16 v[54:57], v[164:167], v[180:183], v[54:57]
	v_mfma_f32_16x16x32_bf16 v[50:53], v[168:171], v[176:179], v[50:53]
	v_mfma_f32_16x16x32_bf16 v[50:53], v[172:175], v[180:183], v[50:53]
	v_mfma_f32_16x16x32_bf16 v[34:37], v[168:171], v[184:187], v[34:37]
	v_mfma_f32_16x16x32_bf16 v[34:37], v[172:175], v[188:191], v[34:37]
	v_mfma_f32_16x16x32_bf16 v[38:41], v[154:157], v[184:187], v[38:41]
	v_mfma_f32_16x16x32_bf16 v[38:41], v[164:167], v[188:191], v[38:41]
	v_mfma_f32_16x16x32_bf16 v[30:33], v[130:133], v[192:195], v[30:33]
	v_mfma_f32_16x16x32_bf16 v[30:33], v[134:137], v[196:199], v[30:33]
	v_mfma_f32_16x16x32_bf16 v[26:29], v[138:141], v[192:195], v[26:29]
	v_mfma_f32_16x16x32_bf16 v[26:29], v[142:145], v[196:199], v[26:29]
	v_mfma_f32_16x16x32_bf16 v[10:13], v[138:141], v[200:203], v[10:13]
	v_mfma_f32_16x16x32_bf16 v[10:13], v[142:145], v[204:207], v[10:13]
	v_mfma_f32_16x16x32_bf16 v[14:17], v[130:133], v[200:203], v[14:17]
	v_mfma_f32_16x16x32_bf16 v[14:17], v[134:137], v[204:207], v[14:17]
	v_mfma_f32_16x16x32_bf16 v[22:25], v[154:157], v[192:195], v[22:25]
	v_mfma_f32_16x16x32_bf16 v[22:25], v[164:167], v[196:199], v[22:25]
	v_mfma_f32_16x16x32_bf16 v[18:21], v[168:171], v[192:195], v[18:21]
	v_mfma_f32_16x16x32_bf16 v[18:21], v[172:175], v[196:199], v[18:21]
	v_mfma_f32_16x16x32_bf16 v[2:5], v[168:171], v[200:203], v[2:5]
	v_mfma_f32_16x16x32_bf16 v[2:5], v[172:175], v[204:207], v[2:5]
	v_mfma_f32_16x16x32_bf16 v[6:9], v[154:157], v[200:203], v[6:9]
	v_mfma_f32_16x16x32_bf16 v[6:9], v[164:167], v[204:207], v[6:9]
	s_setprio 0
	s_barrier
	v_add_u32_e32 v142, 0x18000, v162
	v_add_u32_e32 v150, 0x1c000, v162
	ds_read_b128 v[130:133], v142
	ds_read_b128 v[134:137], v142 offset:1024
	ds_read_b128 v[138:141], v142 offset:2048
	ds_read_b128 v[142:145], v142 offset:3072
	ds_read_b128 v[154:157], v150
	ds_read_b128 v[164:167], v150 offset:1024
	ds_read_b128 v[168:171], v150 offset:2048
	ds_read_b128 v[172:175], v150 offset:3072
	s_mov_b32 m0, s72
	s_add_i32 s94, s91, 0x20000
	ds_read_b128 v[176:179], v163 offset:32768
	ds_read_b128 v[180:183], v163 offset:33792
	ds_read_b128 v[184:187], v163 offset:34816
	ds_read_b128 v[188:191], v163 offset:35840
	ds_read_b128 v[192:195], v163 offset:36864
	ds_read_b128 v[196:199], v163 offset:37888
	ds_read_b128 v[200:203], v163 offset:38912
	ds_read_b128 v[204:207], v163 offset:39936
	buffer_load_dwordx4 v161, s[12:15], s94 offen lds
	s_add_i32 s94, s91, 0x30000
	s_mov_b32 m0, s73
	s_nop 0
	buffer_load_dwordx4 v161, s[12:15], s94 offen lds
	s_waitcnt vmcnt(8)
	s_waitcnt lgkmcnt(0)
	s_setprio 1
	v_mfma_f32_16x16x32_bf16 v[126:129], v[130:133], v[176:179], v[126:129]
	s_barrier
	v_mfma_f32_16x16x32_bf16 v[126:129], v[134:137], v[180:183], v[126:129]
	v_mfma_f32_16x16x32_bf16 v[122:125], v[138:141], v[176:179], v[122:125]
	v_mfma_f32_16x16x32_bf16 v[122:125], v[142:145], v[180:183], v[122:125]
	v_mfma_f32_16x16x32_bf16 v[106:109], v[138:141], v[184:187], v[106:109]
	v_mfma_f32_16x16x32_bf16 v[106:109], v[142:145], v[188:191], v[106:109]
	v_mfma_f32_16x16x32_bf16 v[110:113], v[130:133], v[184:187], v[110:113]
	v_mfma_f32_16x16x32_bf16 v[110:113], v[134:137], v[188:191], v[110:113]
	v_mfma_f32_16x16x32_bf16 v[118:121], v[154:157], v[176:179], v[118:121]
	v_mfma_f32_16x16x32_bf16 v[118:121], v[164:167], v[180:183], v[118:121]
	v_mfma_f32_16x16x32_bf16 v[114:117], v[168:171], v[176:179], v[114:117]
	v_mfma_f32_16x16x32_bf16 v[114:117], v[172:175], v[180:183], v[114:117]
	v_mfma_f32_16x16x32_bf16 v[98:101], v[168:171], v[184:187], v[98:101]
	v_mfma_f32_16x16x32_bf16 v[98:101], v[172:175], v[188:191], v[98:101]
	v_mfma_f32_16x16x32_bf16 v[102:105], v[154:157], v[184:187], v[102:105]
	v_mfma_f32_16x16x32_bf16 v[102:105], v[164:167], v[188:191], v[102:105]
	v_mfma_f32_16x16x32_bf16 v[94:97], v[130:133], v[192:195], v[94:97]
	v_mfma_f32_16x16x32_bf16 v[94:97], v[134:137], v[196:199], v[94:97]
	v_mfma_f32_16x16x32_bf16 v[90:93], v[138:141], v[192:195], v[90:93]
	v_mfma_f32_16x16x32_bf16 v[90:93], v[142:145], v[196:199], v[90:93]
	v_mfma_f32_16x16x32_bf16 v[74:77], v[138:141], v[200:203], v[74:77]
	v_mfma_f32_16x16x32_bf16 v[74:77], v[142:145], v[204:207], v[74:77]
	v_mfma_f32_16x16x32_bf16 v[78:81], v[130:133], v[200:203], v[78:81]
	v_mfma_f32_16x16x32_bf16 v[78:81], v[134:137], v[204:207], v[78:81]
	v_mfma_f32_16x16x32_bf16 v[86:89], v[154:157], v[192:195], v[86:89]
	v_mfma_f32_16x16x32_bf16 v[86:89], v[164:167], v[196:199], v[86:89]
	v_mfma_f32_16x16x32_bf16 v[82:85], v[168:171], v[192:195], v[82:85]
	v_mfma_f32_16x16x32_bf16 v[82:85], v[172:175], v[196:199], v[82:85]
	v_mfma_f32_16x16x32_bf16 v[66:69], v[168:171], v[200:203], v[66:69]
	v_mfma_f32_16x16x32_bf16 v[66:69], v[172:175], v[204:207], v[66:69]
	v_mfma_f32_16x16x32_bf16 v[70:73], v[154:157], v[200:203], v[70:73]
	v_mfma_f32_16x16x32_bf16 v[70:73], v[164:167], v[204:207], v[70:73]
	s_setprio 0
	s_barrier
	s_mov_b32 m0, s74
	s_or_b32 s94, s93, 0x80
	ds_read_b128 v[176:179], v163 offset:49152
	ds_read_b128 v[180:183], v163 offset:50176
	ds_read_b128 v[184:187], v163 offset:51200
	ds_read_b128 v[188:191], v163 offset:52224
	ds_read_b128 v[192:195], v163 offset:53248
	ds_read_b128 v[196:199], v163 offset:54272
	ds_read_b128 v[200:203], v163 offset:55296
	ds_read_b128 v[204:207], v163 offset:56320
	buffer_load_dwordx4 v160, s[4:7], s94 offen lds
	s_add_i32 s94, s93, 0x10080
	s_mov_b32 m0, s75
	s_add_i32 s91, s91, 0x10080
	buffer_load_dwordx4 v160, s[4:7], s94 offen lds
	s_add_i32 s94, s93, 0x20080
	s_mov_b32 m0, s78
	s_add_i32 s93, s93, 0x30080
	buffer_load_dwordx4 v160, s[4:7], s94 offen lds
	s_mov_b32 m0, s79
	s_nop 0
	buffer_load_dwordx4 v160, s[4:7], s93 offen lds
	s_mov_b32 m0, s76
	s_nop 0
	buffer_load_dwordx4 v161, s[12:15], s92 offen lds
	s_mov_b32 m0, s77
	s_nop 0
	buffer_load_dwordx4 v161, s[12:15], s91 offen lds
	s_waitcnt vmcnt(8)
	s_waitcnt lgkmcnt(0)
	s_setprio 1
	v_mfma_f32_16x16x32_bf16 v[62:65], v[130:133], v[176:179], v[62:65]
	s_barrier
	v_mfma_f32_16x16x32_bf16 v[62:65], v[134:137], v[180:183], v[62:65]
	v_mfma_f32_16x16x32_bf16 v[58:61], v[138:141], v[176:179], v[58:61]
	v_mfma_f32_16x16x32_bf16 v[58:61], v[142:145], v[180:183], v[58:61]
	v_mfma_f32_16x16x32_bf16 v[42:45], v[138:141], v[184:187], v[42:45]
	v_mfma_f32_16x16x32_bf16 v[42:45], v[142:145], v[188:191], v[42:45]
	v_mfma_f32_16x16x32_bf16 v[46:49], v[130:133], v[184:187], v[46:49]
	v_mfma_f32_16x16x32_bf16 v[46:49], v[134:137], v[188:191], v[46:49]
	v_mfma_f32_16x16x32_bf16 v[54:57], v[154:157], v[176:179], v[54:57]
	v_mfma_f32_16x16x32_bf16 v[54:57], v[164:167], v[180:183], v[54:57]
	v_mfma_f32_16x16x32_bf16 v[50:53], v[168:171], v[176:179], v[50:53]
	v_mfma_f32_16x16x32_bf16 v[50:53], v[172:175], v[180:183], v[50:53]
	v_mfma_f32_16x16x32_bf16 v[34:37], v[168:171], v[184:187], v[34:37]
	v_mfma_f32_16x16x32_bf16 v[34:37], v[172:175], v[188:191], v[34:37]
	v_mfma_f32_16x16x32_bf16 v[38:41], v[154:157], v[184:187], v[38:41]
	v_mfma_f32_16x16x32_bf16 v[38:41], v[164:167], v[188:191], v[38:41]
	v_mfma_f32_16x16x32_bf16 v[30:33], v[130:133], v[192:195], v[30:33]
	v_mfma_f32_16x16x32_bf16 v[30:33], v[134:137], v[196:199], v[30:33]
	v_mfma_f32_16x16x32_bf16 v[26:29], v[138:141], v[192:195], v[26:29]
	v_mfma_f32_16x16x32_bf16 v[26:29], v[142:145], v[196:199], v[26:29]
	v_mfma_f32_16x16x32_bf16 v[10:13], v[138:141], v[200:203], v[10:13]
	v_mfma_f32_16x16x32_bf16 v[10:13], v[142:145], v[204:207], v[10:13]
	v_mfma_f32_16x16x32_bf16 v[14:17], v[130:133], v[200:203], v[14:17]
	v_mfma_f32_16x16x32_bf16 v[14:17], v[134:137], v[204:207], v[14:17]
	v_mfma_f32_16x16x32_bf16 v[22:25], v[154:157], v[192:195], v[22:25]
	v_mfma_f32_16x16x32_bf16 v[22:25], v[164:167], v[196:199], v[22:25]
	v_mfma_f32_16x16x32_bf16 v[18:21], v[168:171], v[192:195], v[18:21]
	v_mfma_f32_16x16x32_bf16 v[18:21], v[172:175], v[196:199], v[18:21]
	v_mfma_f32_16x16x32_bf16 v[2:5], v[168:171], v[200:203], v[2:5]
	v_mfma_f32_16x16x32_bf16 v[2:5], v[172:175], v[204:207], v[2:5]
	v_mfma_f32_16x16x32_bf16 v[6:9], v[154:157], v[200:203], v[6:9]
	v_mfma_f32_16x16x32_bf16 v[6:9], v[164:167], v[204:207], v[6:9]
	s_setprio 0
	s_barrier
	s_add_i32 s89, s89, 2
	s_cmp_ge_i32 s89, s63
	s_mov_b32 s6, s90
	s_cbranch_scc0 .LBB0_1020
	s_and_b64 vcc, exec, s[54:55]
	s_cbranch_vccz .LBB0_1023

.LBB0_1035:
	ds_read_b128 v[140:143], v134
	ds_read_b128 v[148:151], v134 offset:1024
	ds_read_b128 v[152:155], v134 offset:2048
	ds_read_b128 v[156:159], v134 offset:3072
	ds_read_b128 v[160:163], v135
	ds_read_b128 v[164:167], v135 offset:1024
	ds_read_b128 v[168:171], v135 offset:2048
	ds_read_b128 v[172:175], v135 offset:3072
	s_add_i32 s73, s70, 0xfffb8080
	s_cmp_eq_u32 s53, s72
	s_cselect_b32 s73, s68, s73
	s_cselect_b32 s75, s69, s71
	s_add_i32 s74, s73, 0x80
	s_add_i32 s76, s70, 0xfffe8000
	s_mov_b32 m0, s54
	ds_read_b128 v[176:179], v136
	ds_read_b128 v[180:183], v136 offset:1024
	ds_read_b128 v[184:187], v136 offset:2048
	ds_read_b128 v[188:191], v136 offset:3072
	ds_read_b128 v[192:195], v136 offset:4096
	ds_read_b128 v[196:199], v136 offset:5120
	ds_read_b128 v[200:203], v136 offset:6144
	ds_read_b128 v[204:207], v136 offset:7168
	buffer_load_dwordx4 v132, s[12:15], s76 offen lds
	s_mov_b32 m0, s55
	s_nop 0
	buffer_load_dwordx4 v132, s[12:15], s70 offen lds
	s_waitcnt vmcnt(8)
	s_waitcnt lgkmcnt(0)
	s_setprio 1
	v_mfma_f32_16x16x32_bf16 v[126:129], v[140:143], v[176:179], v[126:129]
	s_barrier
	v_mfma_f32_16x16x32_bf16 v[126:129], v[148:151], v[180:183], v[126:129]
	v_mfma_f32_16x16x32_bf16 v[122:125], v[152:155], v[176:179], v[122:125]
	v_mfma_f32_16x16x32_bf16 v[122:125], v[156:159], v[180:183], v[122:125]
	v_mfma_f32_16x16x32_bf16 v[106:109], v[152:155], v[184:187], v[106:109]
	v_mfma_f32_16x16x32_bf16 v[106:109], v[156:159], v[188:191], v[106:109]
	v_mfma_f32_16x16x32_bf16 v[110:113], v[140:143], v[184:187], v[110:113]
	v_mfma_f32_16x16x32_bf16 v[110:113], v[148:151], v[188:191], v[110:113]
	v_mfma_f32_16x16x32_bf16 v[118:121], v[160:163], v[176:179], v[118:121]
	v_mfma_f32_16x16x32_bf16 v[118:121], v[164:167], v[180:183], v[118:121]
	v_mfma_f32_16x16x32_bf16 v[114:117], v[168:171], v[176:179], v[114:117]
	v_mfma_f32_16x16x32_bf16 v[114:117], v[172:175], v[180:183], v[114:117]
	v_mfma_f32_16x16x32_bf16 v[98:101], v[168:171], v[184:187], v[98:101]
	v_mfma_f32_16x16x32_bf16 v[98:101], v[172:175], v[188:191], v[98:101]
	v_mfma_f32_16x16x32_bf16 v[102:105], v[160:163], v[184:187], v[102:105]
	v_mfma_f32_16x16x32_bf16 v[102:105], v[164:167], v[188:191], v[102:105]
	v_mfma_f32_16x16x32_bf16 v[94:97], v[140:143], v[192:195], v[94:97]
	v_mfma_f32_16x16x32_bf16 v[94:97], v[148:151], v[196:199], v[94:97]
	v_mfma_f32_16x16x32_bf16 v[90:93], v[152:155], v[192:195], v[90:93]
	v_mfma_f32_16x16x32_bf16 v[90:93], v[156:159], v[196:199], v[90:93]
	v_mfma_f32_16x16x32_bf16 v[74:77], v[152:155], v[200:203], v[74:77]
	v_mfma_f32_16x16x32_bf16 v[74:77], v[156:159], v[204:207], v[74:77]
	v_mfma_f32_16x16x32_bf16 v[78:81], v[140:143], v[200:203], v[78:81]
	v_mfma_f32_16x16x32_bf16 v[78:81], v[148:151], v[204:207], v[78:81]
	v_mfma_f32_16x16x32_bf16 v[86:89], v[160:163], v[192:195], v[86:89]
	v_mfma_f32_16x16x32_bf16 v[86:89], v[164:167], v[196:199], v[86:89]
	v_mfma_f32_16x16x32_bf16 v[82:85], v[168:171], v[192:195], v[82:85]
	v_mfma_f32_16x16x32_bf16 v[82:85], v[172:175], v[196:199], v[82:85]
	v_mfma_f32_16x16x32_bf16 v[66:69], v[168:171], v[200:203], v[66:69]
	v_mfma_f32_16x16x32_bf16 v[66:69], v[172:175], v[204:207], v[66:69]
	v_mfma_f32_16x16x32_bf16 v[70:73], v[160:163], v[200:203], v[70:73]
	v_mfma_f32_16x16x32_bf16 v[70:73], v[164:167], v[204:207], v[70:73]
	s_setprio 0
	s_barrier
	s_mov_b32 m0, s30
	ds_read_b128 v[176:179], v136 offset:16384
	ds_read_b128 v[180:183], v136 offset:17408
	ds_read_b128 v[184:187], v136 offset:18432
	ds_read_b128 v[188:191], v136 offset:19456
	ds_read_b128 v[192:195], v136 offset:20480
	ds_read_b128 v[196:199], v136 offset:21504
	ds_read_b128 v[200:203], v136 offset:22528
	ds_read_b128 v[204:207], v136 offset:23552
	buffer_load_dwordx4 v133, s[16:19], s75 offen lds
	s_add_i32 s76, s75, 0x200000
	s_mov_b32 m0, s31
	s_nop 0
	buffer_load_dwordx4 v133, s[16:19], s76 offen lds
	s_add_i32 s76, s75, 0x400000
	s_mov_b32 m0, s35
	s_nop 0
	buffer_load_dwordx4 v133, s[16:19], s76 offen lds
	s_add_i32 s76, s75, 0x600000
	s_mov_b32 m0, s42
	s_nop 0
	buffer_load_dwordx4 v133, s[16:19], s76 offen lds
	s_mov_b32 m0, s27
	s_add_i32 s76, s73, 0x18000
	buffer_load_dwordx4 v132, s[12:15], s73 offen lds
	s_mov_b32 m0, s43
	s_nop 0
	buffer_load_dwordx4 v132, s[12:15], s76 offen lds
	s_waitcnt vmcnt(8)
	s_waitcnt lgkmcnt(0)
	s_setprio 1
	v_mfma_f32_16x16x32_bf16 v[62:65], v[140:143], v[176:179], v[62:65]
	s_barrier
	v_mfma_f32_16x16x32_bf16 v[62:65], v[148:151], v[180:183], v[62:65]
	v_mfma_f32_16x16x32_bf16 v[58:61], v[152:155], v[176:179], v[58:61]
	v_mfma_f32_16x16x32_bf16 v[58:61], v[156:159], v[180:183], v[58:61]
	v_mfma_f32_16x16x32_bf16 v[42:45], v[152:155], v[184:187], v[42:45]
	v_mfma_f32_16x16x32_bf16 v[42:45], v[156:159], v[188:191], v[42:45]
	v_mfma_f32_16x16x32_bf16 v[46:49], v[140:143], v[184:187], v[46:49]
	v_mfma_f32_16x16x32_bf16 v[46:49], v[148:151], v[188:191], v[46:49]
	v_mfma_f32_16x16x32_bf16 v[54:57], v[160:163], v[176:179], v[54:57]
	v_mfma_f32_16x16x32_bf16 v[54:57], v[164:167], v[180:183], v[54:57]
	v_mfma_f32_16x16x32_bf16 v[50:53], v[168:171], v[176:179], v[50:53]
	v_mfma_f32_16x16x32_bf16 v[50:53], v[172:175], v[180:183], v[50:53]
	v_mfma_f32_16x16x32_bf16 v[34:37], v[168:171], v[184:187], v[34:37]
	v_mfma_f32_16x16x32_bf16 v[34:37], v[172:175], v[188:191], v[34:37]
	v_mfma_f32_16x16x32_bf16 v[38:41], v[160:163], v[184:187], v[38:41]
	v_mfma_f32_16x16x32_bf16 v[38:41], v[164:167], v[188:191], v[38:41]
	v_mfma_f32_16x16x32_bf16 v[30:33], v[140:143], v[192:195], v[30:33]
	v_mfma_f32_16x16x32_bf16 v[30:33], v[148:151], v[196:199], v[30:33]
	v_mfma_f32_16x16x32_bf16 v[26:29], v[152:155], v[192:195], v[26:29]
	v_mfma_f32_16x16x32_bf16 v[26:29], v[156:159], v[196:199], v[26:29]
	v_mfma_f32_16x16x32_bf16 v[10:13], v[152:155], v[200:203], v[10:13]
	v_mfma_f32_16x16x32_bf16 v[10:13], v[156:159], v[204:207], v[10:13]
	v_mfma_f32_16x16x32_bf16 v[14:17], v[140:143], v[200:203], v[14:17]
	v_mfma_f32_16x16x32_bf16 v[14:17], v[148:151], v[204:207], v[14:17]
	v_mfma_f32_16x16x32_bf16 v[22:25], v[160:163], v[192:195], v[22:25]
	v_mfma_f32_16x16x32_bf16 v[22:25], v[164:167], v[196:199], v[22:25]
	v_mfma_f32_16x16x32_bf16 v[18:21], v[168:171], v[192:195], v[18:21]
	v_mfma_f32_16x16x32_bf16 v[18:21], v[172:175], v[196:199], v[18:21]
	v_mfma_f32_16x16x32_bf16 v[2:5], v[168:171], v[200:203], v[2:5]
	v_mfma_f32_16x16x32_bf16 v[2:5], v[172:175], v[204:207], v[2:5]
	v_mfma_f32_16x16x32_bf16 v[6:9], v[160:163], v[200:203], v[6:9]
	v_mfma_f32_16x16x32_bf16 v[6:9], v[164:167], v[204:207], v[6:9]
	s_setprio 0
	s_barrier
	ds_read_b128 v[140:143], v137
	ds_read_b128 v[148:151], v137 offset:1024
	ds_read_b128 v[152:155], v137 offset:2048
	ds_read_b128 v[156:159], v137 offset:3072
	ds_read_b128 v[160:163], v138
	ds_read_b128 v[164:167], v138 offset:1024
	ds_read_b128 v[168:171], v138 offset:2048
	ds_read_b128 v[172:175], v138 offset:3072
	s_mov_b32 m0, s44
	s_add_i32 s76, s73, 0x30000
	ds_read_b128 v[176:179], v136 offset:32768
	ds_read_b128 v[180:183], v136 offset:33792
	ds_read_b128 v[184:187], v136 offset:34816
	ds_read_b128 v[188:191], v136 offset:35840
	ds_read_b128 v[192:195], v136 offset:36864
	ds_read_b128 v[196:199], v136 offset:37888
	ds_read_b128 v[200:203], v136 offset:38912
	ds_read_b128 v[204:207], v136 offset:39936
	buffer_load_dwordx4 v132, s[12:15], s76 offen lds
	s_add_i32 s76, s73, 0x48000
	s_mov_b32 m0, s45
	s_nop 0
	buffer_load_dwordx4 v132, s[12:15], s76 offen lds
	s_waitcnt vmcnt(8)
	s_waitcnt lgkmcnt(0)
	s_setprio 1
	v_mfma_f32_16x16x32_bf16 v[126:129], v[140:143], v[176:179], v[126:129]
	s_barrier
	v_mfma_f32_16x16x32_bf16 v[126:129], v[148:151], v[180:183], v[126:129]
	v_mfma_f32_16x16x32_bf16 v[122:125], v[152:155], v[176:179], v[122:125]
	v_mfma_f32_16x16x32_bf16 v[122:125], v[156:159], v[180:183], v[122:125]
	v_mfma_f32_16x16x32_bf16 v[106:109], v[152:155], v[184:187], v[106:109]
	v_mfma_f32_16x16x32_bf16 v[106:109], v[156:159], v[188:191], v[106:109]
	v_mfma_f32_16x16x32_bf16 v[110:113], v[140:143], v[184:187], v[110:113]
	v_mfma_f32_16x16x32_bf16 v[110:113], v[148:151], v[188:191], v[110:113]
	v_mfma_f32_16x16x32_bf16 v[118:121], v[160:163], v[176:179], v[118:121]
	v_mfma_f32_16x16x32_bf16 v[118:121], v[164:167], v[180:183], v[118:121]
	v_mfma_f32_16x16x32_bf16 v[114:117], v[168:171], v[176:179], v[114:117]
	v_mfma_f32_16x16x32_bf16 v[114:117], v[172:175], v[180:183], v[114:117]
	v_mfma_f32_16x16x32_bf16 v[98:101], v[168:171], v[184:187], v[98:101]
	v_mfma_f32_16x16x32_bf16 v[98:101], v[172:175], v[188:191], v[98:101]
	v_mfma_f32_16x16x32_bf16 v[102:105], v[160:163], v[184:187], v[102:105]
	v_mfma_f32_16x16x32_bf16 v[102:105], v[164:167], v[188:191], v[102:105]
	v_mfma_f32_16x16x32_bf16 v[94:97], v[140:143], v[192:195], v[94:97]
	v_mfma_f32_16x16x32_bf16 v[94:97], v[148:151], v[196:199], v[94:97]
	v_mfma_f32_16x16x32_bf16 v[90:93], v[152:155], v[192:195], v[90:93]
	v_mfma_f32_16x16x32_bf16 v[90:93], v[156:159], v[196:199], v[90:93]
	v_mfma_f32_16x16x32_bf16 v[74:77], v[152:155], v[200:203], v[74:77]
	v_mfma_f32_16x16x32_bf16 v[74:77], v[156:159], v[204:207], v[74:77]
	v_mfma_f32_16x16x32_bf16 v[78:81], v[140:143], v[200:203], v[78:81]
	v_mfma_f32_16x16x32_bf16 v[78:81], v[148:151], v[204:207], v[78:81]
	v_mfma_f32_16x16x32_bf16 v[86:89], v[160:163], v[192:195], v[86:89]
	v_mfma_f32_16x16x32_bf16 v[86:89], v[164:167], v[196:199], v[86:89]
	v_mfma_f32_16x16x32_bf16 v[82:85], v[168:171], v[192:195], v[82:85]
	v_mfma_f32_16x16x32_bf16 v[82:85], v[172:175], v[196:199], v[82:85]
	v_mfma_f32_16x16x32_bf16 v[66:69], v[168:171], v[200:203], v[66:69]
	v_mfma_f32_16x16x32_bf16 v[66:69], v[172:175], v[204:207], v[66:69]
	v_mfma_f32_16x16x32_bf16 v[70:73], v[160:163], v[200:203], v[70:73]
	v_mfma_f32_16x16x32_bf16 v[70:73], v[164:167], v[204:207], v[70:73]
	s_setprio 0
	s_barrier
	s_mov_b32 m0, s46
	s_add_i32 s76, s75, 0x80
	ds_read_b128 v[176:179], v136 offset:49152
	ds_read_b128 v[180:183], v136 offset:50176
	ds_read_b128 v[184:187], v136 offset:51200
	ds_read_b128 v[188:191], v136 offset:52224
	ds_read_b128 v[192:195], v136 offset:53248
	ds_read_b128 v[196:199], v136 offset:54272
	ds_read_b128 v[200:203], v136 offset:55296
	ds_read_b128 v[204:207], v136 offset:56320
	buffer_load_dwordx4 v133, s[16:19], s76 offen lds
	s_add_i32 s76, s75, 0x200080
	s_mov_b32 m0, s47
	s_add_i32 s73, s73, 0x18080
	buffer_load_dwordx4 v133, s[16:19], s76 offen lds
	s_add_i32 s76, s75, 0x400080
	s_mov_b32 m0, s50
	s_add_i32 s75, s75, 0x600080
	buffer_load_dwordx4 v133, s[16:19], s76 offen lds
	s_mov_b32 m0, s51
	s_nop 0
	buffer_load_dwordx4 v133, s[16:19], s75 offen lds
	s_mov_b32 m0, s48
	s_nop 0
	buffer_load_dwordx4 v132, s[12:15], s74 offen lds
	s_mov_b32 m0, s49
	s_nop 0
	buffer_load_dwordx4 v132, s[12:15], s73 offen lds
	s_waitcnt vmcnt(8)
	s_waitcnt lgkmcnt(0)
	s_setprio 1
	v_mfma_f32_16x16x32_bf16 v[62:65], v[140:143], v[176:179], v[62:65]
	s_barrier
	v_mfma_f32_16x16x32_bf16 v[62:65], v[148:151], v[180:183], v[62:65]
	v_mfma_f32_16x16x32_bf16 v[58:61], v[152:155], v[176:179], v[58:61]
	v_mfma_f32_16x16x32_bf16 v[58:61], v[156:159], v[180:183], v[58:61]
	v_mfma_f32_16x16x32_bf16 v[42:45], v[152:155], v[184:187], v[42:45]
	v_mfma_f32_16x16x32_bf16 v[42:45], v[156:159], v[188:191], v[42:45]
	v_mfma_f32_16x16x32_bf16 v[46:49], v[140:143], v[184:187], v[46:49]
	v_mfma_f32_16x16x32_bf16 v[46:49], v[148:151], v[188:191], v[46:49]
	v_mfma_f32_16x16x32_bf16 v[54:57], v[160:163], v[176:179], v[54:57]
	v_mfma_f32_16x16x32_bf16 v[54:57], v[164:167], v[180:183], v[54:57]
	v_mfma_f32_16x16x32_bf16 v[50:53], v[168:171], v[176:179], v[50:53]
	v_mfma_f32_16x16x32_bf16 v[50:53], v[172:175], v[180:183], v[50:53]
	v_mfma_f32_16x16x32_bf16 v[34:37], v[168:171], v[184:187], v[34:37]
	v_mfma_f32_16x16x32_bf16 v[34:37], v[172:175], v[188:191], v[34:37]
	v_mfma_f32_16x16x32_bf16 v[38:41], v[160:163], v[184:187], v[38:41]
	v_mfma_f32_16x16x32_bf16 v[38:41], v[164:167], v[188:191], v[38:41]
	v_mfma_f32_16x16x32_bf16 v[30:33], v[140:143], v[192:195], v[30:33]
	v_mfma_f32_16x16x32_bf16 v[30:33], v[148:151], v[196:199], v[30:33]
	v_mfma_f32_16x16x32_bf16 v[26:29], v[152:155], v[192:195], v[26:29]
	v_mfma_f32_16x16x32_bf16 v[26:29], v[156:159], v[196:199], v[26:29]
	v_mfma_f32_16x16x32_bf16 v[10:13], v[152:155], v[200:203], v[10:13]
	v_mfma_f32_16x16x32_bf16 v[10:13], v[156:159], v[204:207], v[10:13]
	v_mfma_f32_16x16x32_bf16 v[14:17], v[140:143], v[200:203], v[14:17]
	v_mfma_f32_16x16x32_bf16 v[14:17], v[148:151], v[204:207], v[14:17]
	v_mfma_f32_16x16x32_bf16 v[22:25], v[160:163], v[192:195], v[22:25]
	v_mfma_f32_16x16x32_bf16 v[22:25], v[164:167], v[196:199], v[22:25]
	v_mfma_f32_16x16x32_bf16 v[18:21], v[168:171], v[192:195], v[18:21]
	v_mfma_f32_16x16x32_bf16 v[18:21], v[172:175], v[196:199], v[18:21]
	v_mfma_f32_16x16x32_bf16 v[2:5], v[168:171], v[200:203], v[2:5]
	v_mfma_f32_16x16x32_bf16 v[2:5], v[172:175], v[204:207], v[2:5]
	v_mfma_f32_16x16x32_bf16 v[6:9], v[160:163], v[200:203], v[6:9]
	v_mfma_f32_16x16x32_bf16 v[6:9], v[164:167], v[204:207], v[6:9]
	s_setprio 0
	s_barrier
	s_add_i32 s72, s72, 2
	s_addk_i32 s70, 0x100
	s_addk_i32 s71, 0x100
	s_cmp_ge_i32 s72, s21
	s_cbranch_scc0 .LBB0_1035

.LBB0_1050:
	ds_read_b128 v[132:135], v142
	ds_read_b128 v[136:139], v142 offset:1024
	ds_read_b128 v[148:151], v142 offset:2048
	ds_read_b128 v[152:155], v142 offset:3072
	ds_read_b128 v[156:159], v143
	ds_read_b128 v[160:163], v143 offset:1024
	ds_read_b128 v[164:167], v143 offset:2048
	ds_read_b128 v[168:171], v143 offset:3072
	s_add_i32 s18, s61, 0xfff40080
	s_cmp_eq_u32 s54, s62
	s_cselect_b32 s64, s35, s18
	s_add_i32 s63, s64, 0x80
	s_add_i32 s18, s61, 0xfffc0000
	s_mov_b32 m0, s55
	ds_read_b128 v[172:175], v144
	ds_read_b128 v[176:179], v144 offset:1024
	ds_read_b128 v[180:183], v144 offset:2048
	ds_read_b128 v[184:187], v144 offset:3072
	ds_read_b128 v[188:191], v144 offset:4096
	ds_read_b128 v[192:195], v144 offset:5120
	ds_read_b128 v[196:199], v144 offset:6144
	ds_read_b128 v[200:203], v144 offset:7168
	buffer_load_dwordx4 v140, s[12:15], s18 offen lds
	s_mov_b32 m0, s56
	s_nop 0
	buffer_load_dwordx4 v140, s[12:15], s61 offen lds
	s_waitcnt vmcnt(8)
	s_waitcnt lgkmcnt(0)
	s_setprio 1
	v_mfma_f32_16x16x32_bf16 v[126:129], v[132:135], v[172:175], v[126:129]
	s_barrier
	v_mfma_f32_16x16x32_bf16 v[126:129], v[136:139], v[176:179], v[126:129]
	v_mfma_f32_16x16x32_bf16 v[122:125], v[148:151], v[172:175], v[122:125]
	v_mfma_f32_16x16x32_bf16 v[122:125], v[152:155], v[176:179], v[122:125]
	v_mfma_f32_16x16x32_bf16 v[106:109], v[148:151], v[180:183], v[106:109]
	v_mfma_f32_16x16x32_bf16 v[106:109], v[152:155], v[184:187], v[106:109]
	v_mfma_f32_16x16x32_bf16 v[110:113], v[132:135], v[180:183], v[110:113]
	v_mfma_f32_16x16x32_bf16 v[110:113], v[136:139], v[184:187], v[110:113]
	v_mfma_f32_16x16x32_bf16 v[118:121], v[156:159], v[172:175], v[118:121]
	v_mfma_f32_16x16x32_bf16 v[118:121], v[160:163], v[176:179], v[118:121]
	v_mfma_f32_16x16x32_bf16 v[114:117], v[164:167], v[172:175], v[114:117]
	v_mfma_f32_16x16x32_bf16 v[114:117], v[168:171], v[176:179], v[114:117]
	v_mfma_f32_16x16x32_bf16 v[98:101], v[164:167], v[180:183], v[98:101]
	v_mfma_f32_16x16x32_bf16 v[98:101], v[168:171], v[184:187], v[98:101]
	v_mfma_f32_16x16x32_bf16 v[102:105], v[156:159], v[180:183], v[102:105]
	v_mfma_f32_16x16x32_bf16 v[102:105], v[160:163], v[184:187], v[102:105]
	v_mfma_f32_16x16x32_bf16 v[94:97], v[132:135], v[188:191], v[94:97]
	v_mfma_f32_16x16x32_bf16 v[94:97], v[136:139], v[192:195], v[94:97]
	v_mfma_f32_16x16x32_bf16 v[90:93], v[148:151], v[188:191], v[90:93]
	v_mfma_f32_16x16x32_bf16 v[90:93], v[152:155], v[192:195], v[90:93]
	v_mfma_f32_16x16x32_bf16 v[74:77], v[148:151], v[196:199], v[74:77]
	v_mfma_f32_16x16x32_bf16 v[74:77], v[152:155], v[200:203], v[74:77]
	v_mfma_f32_16x16x32_bf16 v[78:81], v[132:135], v[196:199], v[78:81]
	v_mfma_f32_16x16x32_bf16 v[78:81], v[136:139], v[200:203], v[78:81]
	v_mfma_f32_16x16x32_bf16 v[86:89], v[156:159], v[188:191], v[86:89]
	v_mfma_f32_16x16x32_bf16 v[86:89], v[160:163], v[192:195], v[86:89]
	v_mfma_f32_16x16x32_bf16 v[82:85], v[164:167], v[188:191], v[82:85]
	v_mfma_f32_16x16x32_bf16 v[82:85], v[168:171], v[192:195], v[82:85]
	v_mfma_f32_16x16x32_bf16 v[66:69], v[164:167], v[196:199], v[66:69]
	v_mfma_f32_16x16x32_bf16 v[66:69], v[168:171], v[200:203], v[66:69]
	v_mfma_f32_16x16x32_bf16 v[70:73], v[156:159], v[196:199], v[70:73]
	v_mfma_f32_16x16x32_bf16 v[70:73], v[160:163], v[200:203], v[70:73]
	s_setprio 0
	s_barrier
	s_mov_b32 m0, s25
	s_mov_b32 s18, s14
	s_mov_b32 s19, s15
	ds_read_b128 v[172:175], v144 offset:16384
	ds_read_b128 v[176:179], v144 offset:17408
	ds_read_b128 v[180:183], v144 offset:18432
	ds_read_b128 v[184:187], v144 offset:19456
	ds_read_b128 v[188:191], v144 offset:20480
	ds_read_b128 v[192:195], v144 offset:21504
	ds_read_b128 v[196:199], v144 offset:22528
	ds_read_b128 v[200:203], v144 offset:23552
	buffer_load_dwordx4 v141, s[16:19], s64 offen lds
	s_add_i32 s65, s64, 0x40000
	s_mov_b32 m0, s27
	s_add_i32 s66, s64, 0x80000
	buffer_load_dwordx4 v141, s[16:19], s65 offen lds
	s_mov_b32 m0, s30
	s_add_i32 s67, s64, 0xc0000
	buffer_load_dwordx4 v141, s[16:19], s66 offen lds
	s_mov_b32 m0, s31
	s_nop 0
	buffer_load_dwordx4 v141, s[16:19], s67 offen lds
	s_mov_b32 m0, s21
	s_nop 0
	buffer_load_dwordx4 v140, s[12:15], s64 offen lds
	s_mov_b32 m0, s38
	s_nop 0
	buffer_load_dwordx4 v140, s[12:15], s65 offen lds
	s_waitcnt vmcnt(8)
	s_waitcnt lgkmcnt(0)
	s_setprio 1
	v_mfma_f32_16x16x32_bf16 v[62:65], v[132:135], v[172:175], v[62:65]
	s_barrier
	v_mfma_f32_16x16x32_bf16 v[62:65], v[136:139], v[176:179], v[62:65]
	v_mfma_f32_16x16x32_bf16 v[58:61], v[148:151], v[172:175], v[58:61]
	v_mfma_f32_16x16x32_bf16 v[58:61], v[152:155], v[176:179], v[58:61]
	v_mfma_f32_16x16x32_bf16 v[42:45], v[148:151], v[180:183], v[42:45]
	v_mfma_f32_16x16x32_bf16 v[42:45], v[152:155], v[184:187], v[42:45]
	v_mfma_f32_16x16x32_bf16 v[46:49], v[132:135], v[180:183], v[46:49]
	v_mfma_f32_16x16x32_bf16 v[46:49], v[136:139], v[184:187], v[46:49]
	v_mfma_f32_16x16x32_bf16 v[54:57], v[156:159], v[172:175], v[54:57]
	v_mfma_f32_16x16x32_bf16 v[54:57], v[160:163], v[176:179], v[54:57]
	v_mfma_f32_16x16x32_bf16 v[50:53], v[164:167], v[172:175], v[50:53]
	v_mfma_f32_16x16x32_bf16 v[50:53], v[168:171], v[176:179], v[50:53]
	v_mfma_f32_16x16x32_bf16 v[34:37], v[164:167], v[180:183], v[34:37]
	v_mfma_f32_16x16x32_bf16 v[34:37], v[168:171], v[184:187], v[34:37]
	v_mfma_f32_16x16x32_bf16 v[38:41], v[156:159], v[180:183], v[38:41]
	v_mfma_f32_16x16x32_bf16 v[38:41], v[160:163], v[184:187], v[38:41]
	v_mfma_f32_16x16x32_bf16 v[30:33], v[132:135], v[188:191], v[30:33]
	v_mfma_f32_16x16x32_bf16 v[30:33], v[136:139], v[192:195], v[30:33]
	v_mfma_f32_16x16x32_bf16 v[26:29], v[148:151], v[188:191], v[26:29]
	v_mfma_f32_16x16x32_bf16 v[26:29], v[152:155], v[192:195], v[26:29]
	v_mfma_f32_16x16x32_bf16 v[10:13], v[148:151], v[196:199], v[10:13]
	v_mfma_f32_16x16x32_bf16 v[10:13], v[152:155], v[200:203], v[10:13]
	v_mfma_f32_16x16x32_bf16 v[14:17], v[132:135], v[196:199], v[14:17]
	v_mfma_f32_16x16x32_bf16 v[14:17], v[136:139], v[200:203], v[14:17]
	v_mfma_f32_16x16x32_bf16 v[22:25], v[156:159], v[188:191], v[22:25]
	v_mfma_f32_16x16x32_bf16 v[22:25], v[160:163], v[192:195], v[22:25]
	v_mfma_f32_16x16x32_bf16 v[18:21], v[164:167], v[188:191], v[18:21]
	v_mfma_f32_16x16x32_bf16 v[18:21], v[168:171], v[192:195], v[18:21]
	v_mfma_f32_16x16x32_bf16 v[2:5], v[164:167], v[196:199], v[2:5]
	v_mfma_f32_16x16x32_bf16 v[2:5], v[168:171], v[200:203], v[2:5]
	v_mfma_f32_16x16x32_bf16 v[6:9], v[156:159], v[196:199], v[6:9]
	v_mfma_f32_16x16x32_bf16 v[6:9], v[160:163], v[200:203], v[6:9]
	s_setprio 0
	s_barrier
	ds_read_b128 v[132:135], v145
	ds_read_b128 v[136:139], v145 offset:1024
	ds_read_b128 v[148:151], v145 offset:2048
	ds_read_b128 v[152:155], v145 offset:3072
	ds_read_b128 v[156:159], v147
	ds_read_b128 v[160:163], v147 offset:1024
	ds_read_b128 v[164:167], v147 offset:2048
	ds_read_b128 v[168:171], v147 offset:3072
	s_mov_b32 m0, s39
	ds_read_b128 v[172:175], v144 offset:32768
	ds_read_b128 v[176:179], v144 offset:33792
	ds_read_b128 v[180:183], v144 offset:34816
	ds_read_b128 v[184:187], v144 offset:35840
	ds_read_b128 v[188:191], v144 offset:36864
	ds_read_b128 v[192:195], v144 offset:37888
	ds_read_b128 v[196:199], v144 offset:38912
	ds_read_b128 v[200:203], v144 offset:39936
	buffer_load_dwordx4 v140, s[12:15], s66 offen lds
	s_mov_b32 m0, s40
	s_nop 0
	buffer_load_dwordx4 v140, s[12:15], s67 offen lds
	s_waitcnt vmcnt(8)
	s_waitcnt lgkmcnt(0)
	s_setprio 1
	v_mfma_f32_16x16x32_bf16 v[126:129], v[132:135], v[172:175], v[126:129]
	s_barrier
	v_mfma_f32_16x16x32_bf16 v[126:129], v[136:139], v[176:179], v[126:129]
	v_mfma_f32_16x16x32_bf16 v[122:125], v[148:151], v[172:175], v[122:125]
	v_mfma_f32_16x16x32_bf16 v[122:125], v[152:155], v[176:179], v[122:125]
	v_mfma_f32_16x16x32_bf16 v[106:109], v[148:151], v[180:183], v[106:109]
	v_mfma_f32_16x16x32_bf16 v[106:109], v[152:155], v[184:187], v[106:109]
	v_mfma_f32_16x16x32_bf16 v[110:113], v[132:135], v[180:183], v[110:113]
	v_mfma_f32_16x16x32_bf16 v[110:113], v[136:139], v[184:187], v[110:113]
	v_mfma_f32_16x16x32_bf16 v[118:121], v[156:159], v[172:175], v[118:121]
	v_mfma_f32_16x16x32_bf16 v[118:121], v[160:163], v[176:179], v[118:121]
	v_mfma_f32_16x16x32_bf16 v[114:117], v[164:167], v[172:175], v[114:117]
	v_mfma_f32_16x16x32_bf16 v[114:117], v[168:171], v[176:179], v[114:117]
	v_mfma_f32_16x16x32_bf16 v[98:101], v[164:167], v[180:183], v[98:101]
	v_mfma_f32_16x16x32_bf16 v[98:101], v[168:171], v[184:187], v[98:101]
	v_mfma_f32_16x16x32_bf16 v[102:105], v[156:159], v[180:183], v[102:105]
	v_mfma_f32_16x16x32_bf16 v[102:105], v[160:163], v[184:187], v[102:105]
	v_mfma_f32_16x16x32_bf16 v[94:97], v[132:135], v[188:191], v[94:97]
	v_mfma_f32_16x16x32_bf16 v[94:97], v[136:139], v[192:195], v[94:97]
	v_mfma_f32_16x16x32_bf16 v[90:93], v[148:151], v[188:191], v[90:93]
	v_mfma_f32_16x16x32_bf16 v[90:93], v[152:155], v[192:195], v[90:93]
	v_mfma_f32_16x16x32_bf16 v[74:77], v[148:151], v[196:199], v[74:77]
	v_mfma_f32_16x16x32_bf16 v[74:77], v[152:155], v[200:203], v[74:77]
	v_mfma_f32_16x16x32_bf16 v[78:81], v[132:135], v[196:199], v[78:81]
	v_mfma_f32_16x16x32_bf16 v[78:81], v[136:139], v[200:203], v[78:81]
	v_mfma_f32_16x16x32_bf16 v[86:89], v[156:159], v[188:191], v[86:89]
	v_mfma_f32_16x16x32_bf16 v[86:89], v[160:163], v[192:195], v[86:89]
	v_mfma_f32_16x16x32_bf16 v[82:85], v[164:167], v[188:191], v[82:85]
	v_mfma_f32_16x16x32_bf16 v[82:85], v[168:171], v[192:195], v[82:85]
	v_mfma_f32_16x16x32_bf16 v[66:69], v[164:167], v[196:199], v[66:69]
	v_mfma_f32_16x16x32_bf16 v[66:69], v[168:171], v[200:203], v[66:69]
	v_mfma_f32_16x16x32_bf16 v[70:73], v[156:159], v[196:199], v[70:73]
	v_mfma_f32_16x16x32_bf16 v[70:73], v[160:163], v[200:203], v[70:73]
	s_setprio 0
	s_barrier
	s_mov_b32 m0, s48
	ds_read_b128 v[172:175], v144 offset:49152
	ds_read_b128 v[176:179], v144 offset:50176
	ds_read_b128 v[180:183], v144 offset:51200
	ds_read_b128 v[184:187], v144 offset:52224
	ds_read_b128 v[188:191], v144 offset:53248
	ds_read_b128 v[192:195], v144 offset:54272
	ds_read_b128 v[196:199], v144 offset:55296
	ds_read_b128 v[200:203], v144 offset:56320
	buffer_load_dwordx4 v141, s[16:19], s63 offen lds
	s_add_i32 s65, s64, 0x40080
	s_mov_b32 m0, s49
	s_add_i32 s66, s64, 0x80080
	buffer_load_dwordx4 v141, s[16:19], s65 offen lds
	s_mov_b32 m0, s52
	s_add_i32 s64, s64, 0xc0080
	buffer_load_dwordx4 v141, s[16:19], s66 offen lds
	s_mov_b32 m0, s53
	s_nop 0
	buffer_load_dwordx4 v141, s[16:19], s64 offen lds
	s_mov_b32 m0, s50
	s_nop 0
	buffer_load_dwordx4 v140, s[12:15], s63 offen lds
	s_mov_b32 m0, s51
	s_nop 0
	buffer_load_dwordx4 v140, s[12:15], s65 offen lds
	s_waitcnt vmcnt(8)
	s_waitcnt lgkmcnt(0)
	s_setprio 1
	v_mfma_f32_16x16x32_bf16 v[62:65], v[132:135], v[172:175], v[62:65]
	s_barrier
	v_mfma_f32_16x16x32_bf16 v[62:65], v[136:139], v[176:179], v[62:65]
	v_mfma_f32_16x16x32_bf16 v[58:61], v[148:151], v[172:175], v[58:61]
	v_mfma_f32_16x16x32_bf16 v[58:61], v[152:155], v[176:179], v[58:61]
	v_mfma_f32_16x16x32_bf16 v[42:45], v[148:151], v[180:183], v[42:45]
	v_mfma_f32_16x16x32_bf16 v[42:45], v[152:155], v[184:187], v[42:45]
	v_mfma_f32_16x16x32_bf16 v[46:49], v[132:135], v[180:183], v[46:49]
	v_mfma_f32_16x16x32_bf16 v[46:49], v[136:139], v[184:187], v[46:49]
	v_mfma_f32_16x16x32_bf16 v[54:57], v[156:159], v[172:175], v[54:57]
	v_mfma_f32_16x16x32_bf16 v[54:57], v[160:163], v[176:179], v[54:57]
	v_mfma_f32_16x16x32_bf16 v[50:53], v[164:167], v[172:175], v[50:53]
	v_mfma_f32_16x16x32_bf16 v[50:53], v[168:171], v[176:179], v[50:53]
	v_mfma_f32_16x16x32_bf16 v[34:37], v[164:167], v[180:183], v[34:37]
	v_mfma_f32_16x16x32_bf16 v[34:37], v[168:171], v[184:187], v[34:37]
	v_mfma_f32_16x16x32_bf16 v[38:41], v[156:159], v[180:183], v[38:41]
	v_mfma_f32_16x16x32_bf16 v[38:41], v[160:163], v[184:187], v[38:41]
	v_mfma_f32_16x16x32_bf16 v[30:33], v[132:135], v[188:191], v[30:33]
	v_mfma_f32_16x16x32_bf16 v[30:33], v[136:139], v[192:195], v[30:33]
	v_mfma_f32_16x16x32_bf16 v[26:29], v[148:151], v[188:191], v[26:29]
	v_mfma_f32_16x16x32_bf16 v[26:29], v[152:155], v[192:195], v[26:29]
	v_mfma_f32_16x16x32_bf16 v[10:13], v[148:151], v[196:199], v[10:13]
	v_mfma_f32_16x16x32_bf16 v[10:13], v[152:155], v[200:203], v[10:13]
	v_mfma_f32_16x16x32_bf16 v[14:17], v[132:135], v[196:199], v[14:17]
	v_mfma_f32_16x16x32_bf16 v[14:17], v[136:139], v[200:203], v[14:17]
	v_mfma_f32_16x16x32_bf16 v[22:25], v[156:159], v[188:191], v[22:25]
	v_mfma_f32_16x16x32_bf16 v[22:25], v[160:163], v[192:195], v[22:25]
	v_mfma_f32_16x16x32_bf16 v[18:21], v[164:167], v[188:191], v[18:21]
	v_mfma_f32_16x16x32_bf16 v[18:21], v[168:171], v[192:195], v[18:21]
	v_mfma_f32_16x16x32_bf16 v[2:5], v[164:167], v[196:199], v[2:5]
	v_mfma_f32_16x16x32_bf16 v[2:5], v[168:171], v[200:203], v[2:5]
	v_mfma_f32_16x16x32_bf16 v[6:9], v[156:159], v[196:199], v[6:9]
	v_mfma_f32_16x16x32_bf16 v[6:9], v[160:163], v[200:203], v[6:9]
	s_setprio 0
	s_barrier
	s_add_i32 s62, s62, 2
	s_addk_i32 s61, 0x100
	s_cmp_ge_i32 s62, s3
	s_cbranch_scc0 .LBB0_1050

.LBB0_1181:
	v_add_u32_e32 v2, 0x10000, v232
	ds_read_b128 v[134:137], v2
	ds_read_b128 v[138:141], v2 offset:1024
	ds_read_b128 v[142:145], v2 offset:2048
	ds_read_b128 v[146:149], v2 offset:3072
	v_add_u32_e32 v2, 0x14000, v232
	ds_read_b128 v[150:153], v2
	ds_read_b128 v[154:157], v2 offset:1024
	ds_read_b128 v[158:161], v2 offset:2048
	ds_read_b128 v[162:165], v2 offset:3072
	s_add_i32 s50, s47, s90
	s_and_b64 s[18:19], exec, s[18:19]
	s_cselect_b32 s51, s88, s50
	s_add_i32 s50, s92, 0x80
	s_or_b32 s52, s51, 0x80
	s_add_i32 s18, s89, s93
	s_add_i32 s94, s94, 0x1bfffc80
	s_cmp_lt_u32 s91, 8
	s_cselect_b32 s18, s18, s94
	s_mov_b32 m0, s74
	s_add_i32 s19, s18, 0x80000
	ds_read_b128 v[166:169], v233
	ds_read_b128 v[170:173], v233 offset:1024
	ds_read_b128 v[174:177], v233 offset:2048
	ds_read_b128 v[178:181], v233 offset:3072
	ds_read_b128 v[182:185], v233 offset:4096
	ds_read_b128 v[186:189], v233 offset:5120
	ds_read_b128 v[190:193], v233 offset:6144
	ds_read_b128 v[194:197], v233 offset:7168
	buffer_load_dwordx4 v230, s[12:15], s19 offen lds
	s_add_i32 s18, s18, 0xc0000
	s_mov_b32 m0, s75
	s_nop 0
	buffer_load_dwordx4 v230, s[12:15], s18 offen lds
	s_waitcnt vmcnt(8)
	s_waitcnt lgkmcnt(0)
	s_setprio 1
	v_mfma_f32_16x16x32_bf16 v[130:133], v[134:137], v[166:169], v[130:133]
	s_barrier
	v_mfma_f32_16x16x32_bf16 v[130:133], v[138:141], v[170:173], v[130:133]
	v_mfma_f32_16x16x32_bf16 v[126:129], v[142:145], v[166:169], v[126:129]
	v_mfma_f32_16x16x32_bf16 v[126:129], v[146:149], v[170:173], v[126:129]
	v_mfma_f32_16x16x32_bf16 v[110:113], v[142:145], v[174:177], v[110:113]
	v_mfma_f32_16x16x32_bf16 v[110:113], v[146:149], v[178:181], v[110:113]
	v_mfma_f32_16x16x32_bf16 v[114:117], v[134:137], v[174:177], v[114:117]
	v_mfma_f32_16x16x32_bf16 v[114:117], v[138:141], v[178:181], v[114:117]
	v_mfma_f32_16x16x32_bf16 v[122:125], v[150:153], v[166:169], v[122:125]
	v_mfma_f32_16x16x32_bf16 v[122:125], v[154:157], v[170:173], v[122:125]
	v_mfma_f32_16x16x32_bf16 v[118:121], v[158:161], v[166:169], v[118:121]
	v_mfma_f32_16x16x32_bf16 v[118:121], v[162:165], v[170:173], v[118:121]
	v_mfma_f32_16x16x32_bf16 v[102:105], v[158:161], v[174:177], v[102:105]
	v_mfma_f32_16x16x32_bf16 v[102:105], v[162:165], v[178:181], v[102:105]
	v_mfma_f32_16x16x32_bf16 v[106:109], v[150:153], v[174:177], v[106:109]
	v_mfma_f32_16x16x32_bf16 v[106:109], v[154:157], v[178:181], v[106:109]
	v_mfma_f32_16x16x32_bf16 v[98:101], v[134:137], v[182:185], v[98:101]
	v_mfma_f32_16x16x32_bf16 v[98:101], v[138:141], v[186:189], v[98:101]
	v_mfma_f32_16x16x32_bf16 v[94:97], v[142:145], v[182:185], v[94:97]
	v_mfma_f32_16x16x32_bf16 v[94:97], v[146:149], v[186:189], v[94:97]
	v_mfma_f32_16x16x32_bf16 v[78:81], v[142:145], v[190:193], v[78:81]
	v_mfma_f32_16x16x32_bf16 v[78:81], v[146:149], v[194:197], v[78:81]
	v_mfma_f32_16x16x32_bf16 v[82:85], v[134:137], v[190:193], v[82:85]
	v_mfma_f32_16x16x32_bf16 v[82:85], v[138:141], v[194:197], v[82:85]
	v_mfma_f32_16x16x32_bf16 v[90:93], v[150:153], v[182:185], v[90:93]
	v_mfma_f32_16x16x32_bf16 v[90:93], v[154:157], v[186:189], v[90:93]
	v_mfma_f32_16x16x32_bf16 v[86:89], v[158:161], v[182:185], v[86:89]
	v_mfma_f32_16x16x32_bf16 v[86:89], v[162:165], v[186:189], v[86:89]
	v_mfma_f32_16x16x32_bf16 v[70:73], v[158:161], v[190:193], v[70:73]
	v_mfma_f32_16x16x32_bf16 v[70:73], v[162:165], v[194:197], v[70:73]
	v_mfma_f32_16x16x32_bf16 v[74:77], v[150:153], v[190:193], v[74:77]
	v_mfma_f32_16x16x32_bf16 v[74:77], v[154:157], v[194:197], v[74:77]
	s_setprio 0
	s_barrier
	s_mov_b32 m0, s27
	s_mov_b32 s18, s14
	s_mov_b32 s19, s15
	ds_read_b128 v[166:169], v233 offset:16384
	ds_read_b128 v[170:173], v233 offset:17408
	ds_read_b128 v[174:177], v233 offset:18432
	ds_read_b128 v[178:181], v233 offset:19456
	ds_read_b128 v[182:185], v233 offset:20480
	ds_read_b128 v[186:189], v233 offset:21504
	ds_read_b128 v[190:193], v233 offset:22528
	ds_read_b128 v[194:197], v233 offset:23552
	buffer_load_dwordx4 v231, s[16:19], s51 offen lds
	s_add_i32 s53, s51, 0x18000
	s_mov_b32 m0, s30
	s_nop 0
	buffer_load_dwordx4 v231, s[16:19], s53 offen lds
	s_add_i32 s53, s51, 0x30000
	s_mov_b32 m0, s31
	s_nop 0
	buffer_load_dwordx4 v231, s[16:19], s53 offen lds
	s_add_i32 s53, s51, 0x48000
	s_mov_b32 m0, s54
	s_nop 0
	buffer_load_dwordx4 v231, s[16:19], s53 offen lds
	s_mov_b32 m0, s25
	s_add_i32 s53, s92, 0x40000
	buffer_load_dwordx4 v230, s[12:15], s92 offen lds
	s_mov_b32 m0, s55
	s_nop 0
	buffer_load_dwordx4 v230, s[12:15], s53 offen lds
	s_waitcnt vmcnt(8)
	s_waitcnt lgkmcnt(0)
	s_setprio 1
	v_mfma_f32_16x16x32_bf16 v[66:69], v[134:137], v[166:169], v[66:69]
	s_barrier
	v_mfma_f32_16x16x32_bf16 v[62:65], v[142:145], v[166:169], v[62:65]
	v_mfma_f32_16x16x32_bf16 v[50:53], v[134:137], v[174:177], v[50:53]
	v_mfma_f32_16x16x32_bf16 v[46:49], v[142:145], v[174:177], v[46:49]
	v_mfma_f32_16x16x32_bf16 v[34:37], v[134:137], v[182:185], v[34:37]
	v_mfma_f32_16x16x32_bf16 v[30:33], v[142:145], v[182:185], v[30:33]
	v_mfma_f32_16x16x32_bf16 v[18:21], v[134:137], v[190:193], v[18:21]
	v_mfma_f32_16x16x32_bf16 v[14:17], v[142:145], v[190:193], v[14:17]
	v_mfma_f32_16x16x32_bf16 v[58:61], v[150:153], v[166:169], v[58:61]
	v_mfma_f32_16x16x32_bf16 v[54:57], v[158:161], v[166:169], v[54:57]
	v_mfma_f32_16x16x32_bf16 v[42:45], v[150:153], v[174:177], v[42:45]
	v_mfma_f32_16x16x32_bf16 v[38:41], v[158:161], v[174:177], v[38:41]
	v_mfma_f32_16x16x32_bf16 v[26:29], v[150:153], v[182:185], v[26:29]
	v_mfma_f32_16x16x32_bf16 v[22:25], v[158:161], v[182:185], v[22:25]
	v_mfma_f32_16x16x32_bf16 v[10:13], v[150:153], v[190:193], v[10:13]
	v_mfma_f32_16x16x32_bf16 v[4:7], v[158:161], v[190:193], v[6:9]
	v_mfma_f32_16x16x32_bf16 v[66:69], v[138:141], v[170:173], v[66:69]
	v_mfma_f32_16x16x32_bf16 v[62:65], v[146:149], v[170:173], v[62:65]
	v_mfma_f32_16x16x32_bf16 v[50:53], v[138:141], v[178:181], v[50:53]
	v_mfma_f32_16x16x32_bf16 v[46:49], v[146:149], v[178:181], v[46:49]
	v_mfma_f32_16x16x32_bf16 v[34:37], v[138:141], v[186:189], v[34:37]
	v_mfma_f32_16x16x32_bf16 v[30:33], v[146:149], v[186:189], v[30:33]
	v_mfma_f32_16x16x32_bf16 v[18:21], v[138:141], v[194:197], v[18:21]
	v_mfma_f32_16x16x32_bf16 v[14:17], v[146:149], v[194:197], v[14:17]
	v_mfma_f32_16x16x32_bf16 v[58:61], v[154:157], v[170:173], v[58:61]
	v_mfma_f32_16x16x32_bf16 v[54:57], v[162:165], v[170:173], v[54:57]
	v_mfma_f32_16x16x32_bf16 v[42:45], v[154:157], v[178:181], v[42:45]
	v_mfma_f32_16x16x32_bf16 v[38:41], v[162:165], v[178:181], v[38:41]
	v_mfma_f32_16x16x32_bf16 v[26:29], v[154:157], v[186:189], v[26:29]
	v_mfma_f32_16x16x32_bf16 v[22:25], v[162:165], v[186:189], v[22:25]
	v_mfma_f32_16x16x32_bf16 v[10:13], v[154:157], v[194:197], v[10:13]
	v_mfma_f32_16x16x32_bf16 v[4:7], v[162:165], v[194:197], v[4:7]
	s_setprio 0
	s_barrier
	v_add_u32_e32 v2, 0x18000, v232
	ds_read_b128 v[134:137], v2
	ds_read_b128 v[138:141], v2 offset:1024
	ds_read_b128 v[142:145], v2 offset:2048
	ds_read_b128 v[146:149], v2 offset:3072
	v_add_u32_e32 v2, 0x1c000, v232
	ds_read_b128 v[150:153], v2
	ds_read_b128 v[154:157], v2 offset:1024
	ds_read_b128 v[158:161], v2 offset:2048
	ds_read_b128 v[162:165], v2 offset:3072
	s_mov_b32 m0, s56
	s_add_i32 s53, s92, 0x80000
	ds_read_b128 v[166:169], v233 offset:32768
	ds_read_b128 v[170:173], v233 offset:33792
	ds_read_b128 v[174:177], v233 offset:34816
	ds_read_b128 v[178:181], v233 offset:35840
	ds_read_b128 v[182:185], v233 offset:36864
	ds_read_b128 v[186:189], v233 offset:37888
	ds_read_b128 v[190:193], v233 offset:38912
	ds_read_b128 v[194:197], v233 offset:39936
	buffer_load_dwordx4 v230, s[12:15], s53 offen lds
	s_add_i32 s53, s92, 0xc0000
	s_mov_b32 m0, s57
	s_nop 0
	buffer_load_dwordx4 v230, s[12:15], s53 offen lds
	s_waitcnt vmcnt(8)
	s_waitcnt lgkmcnt(0)
	s_setprio 1
	v_mfma_f32_16x16x32_bf16 v[130:133], v[134:137], v[166:169], v[130:133]
	s_barrier
	v_mfma_f32_16x16x32_bf16 v[130:133], v[138:141], v[170:173], v[130:133]
	v_mfma_f32_16x16x32_bf16 v[126:129], v[142:145], v[166:169], v[126:129]
	v_mfma_f32_16x16x32_bf16 v[126:129], v[146:149], v[170:173], v[126:129]
	v_mfma_f32_16x16x32_bf16 v[110:113], v[142:145], v[174:177], v[110:113]
	v_mfma_f32_16x16x32_bf16 v[110:113], v[146:149], v[178:181], v[110:113]
	v_mfma_f32_16x16x32_bf16 v[114:117], v[134:137], v[174:177], v[114:117]
	v_mfma_f32_16x16x32_bf16 v[114:117], v[138:141], v[178:181], v[114:117]
	v_mfma_f32_16x16x32_bf16 v[122:125], v[150:153], v[166:169], v[122:125]
	v_mfma_f32_16x16x32_bf16 v[122:125], v[154:157], v[170:173], v[122:125]
	v_mfma_f32_16x16x32_bf16 v[118:121], v[158:161], v[166:169], v[118:121]
	v_mfma_f32_16x16x32_bf16 v[118:121], v[162:165], v[170:173], v[118:121]
	v_mfma_f32_16x16x32_bf16 v[102:105], v[158:161], v[174:177], v[102:105]
	v_mfma_f32_16x16x32_bf16 v[102:105], v[162:165], v[178:181], v[102:105]
	v_mfma_f32_16x16x32_bf16 v[106:109], v[150:153], v[174:177], v[106:109]
	v_mfma_f32_16x16x32_bf16 v[106:109], v[154:157], v[178:181], v[106:109]
	v_mfma_f32_16x16x32_bf16 v[98:101], v[134:137], v[182:185], v[98:101]
	v_mfma_f32_16x16x32_bf16 v[98:101], v[138:141], v[186:189], v[98:101]
	v_mfma_f32_16x16x32_bf16 v[94:97], v[142:145], v[182:185], v[94:97]
	v_mfma_f32_16x16x32_bf16 v[94:97], v[146:149], v[186:189], v[94:97]
	v_mfma_f32_16x16x32_bf16 v[78:81], v[142:145], v[190:193], v[78:81]
	v_mfma_f32_16x16x32_bf16 v[78:81], v[146:149], v[194:197], v[78:81]
	v_mfma_f32_16x16x32_bf16 v[82:85], v[134:137], v[190:193], v[82:85]
	v_mfma_f32_16x16x32_bf16 v[82:85], v[138:141], v[194:197], v[82:85]
	v_mfma_f32_16x16x32_bf16 v[90:93], v[150:153], v[182:185], v[90:93]
	v_mfma_f32_16x16x32_bf16 v[90:93], v[154:157], v[186:189], v[90:93]
	v_mfma_f32_16x16x32_bf16 v[86:89], v[158:161], v[182:185], v[86:89]
	v_mfma_f32_16x16x32_bf16 v[86:89], v[162:165], v[186:189], v[86:89]
	v_mfma_f32_16x16x32_bf16 v[70:73], v[158:161], v[190:193], v[70:73]
	v_mfma_f32_16x16x32_bf16 v[70:73], v[162:165], v[194:197], v[70:73]
	v_mfma_f32_16x16x32_bf16 v[74:77], v[150:153], v[190:193], v[74:77]
	v_mfma_f32_16x16x32_bf16 v[74:77], v[154:157], v[194:197], v[74:77]
	s_setprio 0
	s_barrier
	s_mov_b32 m0, s64
	ds_read_b128 v[166:169], v233 offset:49152
	ds_read_b128 v[170:173], v233 offset:50176
	ds_read_b128 v[174:177], v233 offset:51200
	ds_read_b128 v[178:181], v233 offset:52224
	ds_read_b128 v[182:185], v233 offset:53248
	ds_read_b128 v[186:189], v233 offset:54272
	ds_read_b128 v[190:193], v233 offset:55296
	ds_read_b128 v[194:197], v233 offset:56320
	buffer_load_dwordx4 v231, s[16:19], s52 offen lds
	s_add_i32 s52, s51, 0x18080
	s_mov_b32 m0, s65
	s_nop 0
	buffer_load_dwordx4 v231, s[16:19], s52 offen lds
	s_add_i32 s52, s51, 0x30080
	s_mov_b32 m0, s68
	s_add_i32 s51, s51, 0x48080
	buffer_load_dwordx4 v231, s[16:19], s52 offen lds
	s_mov_b32 m0, s69
	s_nop 0
	buffer_load_dwordx4 v231, s[16:19], s51 offen lds
	s_mov_b32 m0, s66
	s_add_i32 s18, s92, 0x40080
	buffer_load_dwordx4 v230, s[12:15], s50 offen lds
	s_mov_b32 m0, s67
	s_nop 0
	buffer_load_dwordx4 v230, s[12:15], s18 offen lds
	s_waitcnt vmcnt(8)
	s_waitcnt lgkmcnt(0)
	s_setprio 1
	v_mfma_f32_16x16x32_bf16 v[66:69], v[134:137], v[166:169], v[66:69]
	s_barrier
	v_mfma_f32_16x16x32_bf16 v[62:65], v[142:145], v[166:169], v[62:65]
	v_mfma_f32_16x16x32_bf16 v[50:53], v[134:137], v[174:177], v[50:53]
	v_mfma_f32_16x16x32_bf16 v[46:49], v[142:145], v[174:177], v[46:49]
	v_mfma_f32_16x16x32_bf16 v[34:37], v[134:137], v[182:185], v[34:37]
	v_mfma_f32_16x16x32_bf16 v[30:33], v[142:145], v[182:185], v[30:33]
	v_mfma_f32_16x16x32_bf16 v[18:21], v[134:137], v[190:193], v[18:21]
	v_mfma_f32_16x16x32_bf16 v[14:17], v[142:145], v[190:193], v[14:17]
	v_mfma_f32_16x16x32_bf16 v[58:61], v[150:153], v[166:169], v[58:61]
	v_mfma_f32_16x16x32_bf16 v[54:57], v[158:161], v[166:169], v[54:57]
	v_mfma_f32_16x16x32_bf16 v[42:45], v[150:153], v[174:177], v[42:45]
	v_mfma_f32_16x16x32_bf16 v[38:41], v[158:161], v[174:177], v[38:41]
	v_mfma_f32_16x16x32_bf16 v[26:29], v[150:153], v[182:185], v[26:29]
	v_mfma_f32_16x16x32_bf16 v[22:25], v[158:161], v[182:185], v[22:25]
	v_mfma_f32_16x16x32_bf16 v[8:11], v[150:153], v[190:193], v[10:13]
	v_mfma_f32_16x16x32_bf16 v[4:7], v[158:161], v[190:193], v[4:7]
	v_mfma_f32_16x16x32_bf16 v[66:69], v[138:141], v[170:173], v[66:69]
	v_mfma_f32_16x16x32_bf16 v[62:65], v[146:149], v[170:173], v[62:65]
	v_mfma_f32_16x16x32_bf16 v[50:53], v[138:141], v[178:181], v[50:53]
	v_mfma_f32_16x16x32_bf16 v[46:49], v[146:149], v[178:181], v[46:49]
	v_mfma_f32_16x16x32_bf16 v[34:37], v[138:141], v[186:189], v[34:37]
	v_mfma_f32_16x16x32_bf16 v[30:33], v[146:149], v[186:189], v[30:33]
	v_mfma_f32_16x16x32_bf16 v[18:21], v[138:141], v[194:197], v[18:21]
	v_mfma_f32_16x16x32_bf16 v[14:17], v[146:149], v[194:197], v[14:17]
	v_mfma_f32_16x16x32_bf16 v[58:61], v[154:157], v[170:173], v[58:61]
	v_mfma_f32_16x16x32_bf16 v[54:57], v[162:165], v[170:173], v[54:57]
	v_mfma_f32_16x16x32_bf16 v[42:45], v[154:157], v[178:181], v[42:45]
	v_mfma_f32_16x16x32_bf16 v[38:41], v[162:165], v[178:181], v[38:41]
	v_mfma_f32_16x16x32_bf16 v[26:29], v[154:157], v[186:189], v[26:29]
	v_mfma_f32_16x16x32_bf16 v[22:25], v[162:165], v[186:189], v[22:25]
	v_mfma_f32_16x16x32_bf16 v[10:13], v[154:157], v[194:197], v[8:11]
	v_mfma_f32_16x16x32_bf16 v[6:9], v[162:165], v[194:197], v[4:7]
	s_setprio 0
	s_barrier
	s_add_i32 s91, s91, 2
	s_addk_i32 s90, 0x100
	s_cmp_ge_i32 s91, s3
	s_cbranch_scc1 .LBB0_1193

.LBB0_1290:
	ds_read_b128 v[106:109], v224
	ds_read_b128 v[118:121], v224 offset:1024
	ds_read_b128 v[130:133], v224 offset:2048
	ds_read_b128 v[138:141], v224 offset:3072
	ds_read_b128 v[146:149], v225
	ds_read_b128 v[150:153], v225 offset:1024
	ds_read_b128 v[154:157], v225 offset:2048
	ds_read_b128 v[158:161], v225 offset:3072
	s_add_i32 s18, s72, 0xffe80080
	s_cmp_eq_u32 s56, s74
	s_cselect_b32 s75, s6, s18
	s_cselect_b32 s77, s7, s73
	s_or_b32 s76, s75, 0x80
	s_add_i32 s18, s72, 0xfff80000
	s_mov_b32 m0, s57
	ds_read_b128 v[162:165], v226
	ds_read_b128 v[166:169], v226 offset:1024
	ds_read_b128 v[170:173], v226 offset:2048
	ds_read_b128 v[174:177], v226 offset:3072
	ds_read_b128 v[178:181], v226 offset:4096
	ds_read_b128 v[182:185], v226 offset:5120
	ds_read_b128 v[190:193], v226 offset:6144
	ds_read_b128 v[194:197], v226 offset:7168
	buffer_load_dwordx4 v222, s[12:15], s18 offen lds
	s_mov_b32 m0, s60
	s_nop 0
	buffer_load_dwordx4 v222, s[12:15], s72 offen lds
	s_waitcnt vmcnt(8)
	s_waitcnt lgkmcnt(0)
	s_setprio 1
	v_mfma_f32_16x16x32_bf16 v[142:145], v[106:109], v[162:165], v[142:145]
	s_barrier
	v_mfma_f32_16x16x32_bf16 v[142:145], v[118:121], v[166:169], v[142:145]
	v_mfma_f32_16x16x32_bf16 v[134:137], v[130:133], v[162:165], v[134:137]
	v_mfma_f32_16x16x32_bf16 v[134:137], v[138:141], v[166:169], v[134:137]
	v_mfma_f32_16x16x32_bf16 v[110:113], v[130:133], v[170:173], v[110:113]
	v_mfma_f32_16x16x32_bf16 v[110:113], v[138:141], v[174:177], v[110:113]
	v_mfma_f32_16x16x32_bf16 v[114:117], v[106:109], v[170:173], v[114:117]
	v_mfma_f32_16x16x32_bf16 v[114:117], v[118:121], v[174:177], v[114:117]
	v_mfma_f32_16x16x32_bf16 v[126:129], v[146:149], v[162:165], v[126:129]
	v_mfma_f32_16x16x32_bf16 v[126:129], v[150:153], v[166:169], v[126:129]
	v_mfma_f32_16x16x32_bf16 v[122:125], v[154:157], v[162:165], v[122:125]
	v_mfma_f32_16x16x32_bf16 v[122:125], v[158:161], v[166:169], v[122:125]
	v_mfma_f32_16x16x32_bf16 v[98:101], v[154:157], v[170:173], v[98:101]
	v_mfma_f32_16x16x32_bf16 v[98:101], v[158:161], v[174:177], v[98:101]
	v_mfma_f32_16x16x32_bf16 v[102:105], v[146:149], v[170:173], v[102:105]
	v_mfma_f32_16x16x32_bf16 v[102:105], v[150:153], v[174:177], v[102:105]
	v_mfma_f32_16x16x32_bf16 v[94:97], v[106:109], v[178:181], v[94:97]
	v_mfma_f32_16x16x32_bf16 v[94:97], v[118:121], v[182:185], v[94:97]
	v_mfma_f32_16x16x32_bf16 v[90:93], v[130:133], v[178:181], v[90:93]
	v_mfma_f32_16x16x32_bf16 v[90:93], v[138:141], v[182:185], v[90:93]
	v_mfma_f32_16x16x32_bf16 v[74:77], v[130:133], v[190:193], v[74:77]
	v_mfma_f32_16x16x32_bf16 v[74:77], v[138:141], v[194:197], v[74:77]
	v_mfma_f32_16x16x32_bf16 v[78:81], v[106:109], v[190:193], v[78:81]
	v_mfma_f32_16x16x32_bf16 v[78:81], v[118:121], v[194:197], v[78:81]
	v_mfma_f32_16x16x32_bf16 v[86:89], v[146:149], v[178:181], v[86:89]
	v_mfma_f32_16x16x32_bf16 v[86:89], v[150:153], v[182:185], v[86:89]
	v_mfma_f32_16x16x32_bf16 v[82:85], v[154:157], v[178:181], v[82:85]
	v_mfma_f32_16x16x32_bf16 v[82:85], v[158:161], v[182:185], v[82:85]
	v_mfma_f32_16x16x32_bf16 v[66:69], v[154:157], v[190:193], v[66:69]
	v_mfma_f32_16x16x32_bf16 v[66:69], v[158:161], v[194:197], v[66:69]
	v_mfma_f32_16x16x32_bf16 v[70:73], v[146:149], v[190:193], v[70:73]
	v_mfma_f32_16x16x32_bf16 v[70:73], v[150:153], v[194:197], v[70:73]
	s_setprio 0
	s_barrier
	s_mov_b32 m0, s27
	s_mov_b32 s18, s14
	s_mov_b32 s19, s15
	ds_read_b128 v[162:165], v226 offset:16384
	ds_read_b128 v[166:169], v226 offset:17408
	ds_read_b128 v[170:173], v226 offset:18432
	ds_read_b128 v[174:177], v226 offset:19456
	ds_read_b128 v[178:181], v226 offset:20480
	ds_read_b128 v[182:185], v226 offset:21504
	ds_read_b128 v[190:193], v226 offset:22528
	ds_read_b128 v[194:197], v226 offset:23552
	buffer_load_dwordx4 v223, s[16:19], s77 offen lds
	s_add_i32 s78, s77, 0x80000
	s_mov_b32 m0, s30
	s_nop 0
	buffer_load_dwordx4 v223, s[16:19], s78 offen lds
	s_add_i32 s78, s77, 0x100000
	s_mov_b32 m0, s31
	s_nop 0
	buffer_load_dwordx4 v223, s[16:19], s78 offen lds
	s_add_i32 s78, s77, 0x180000
	s_mov_b32 m0, s41
	s_nop 0
	buffer_load_dwordx4 v223, s[16:19], s78 offen lds
	s_mov_b32 m0, s25
	s_add_i32 s78, s75, 0x80000
	buffer_load_dwordx4 v222, s[12:15], s75 offen lds
	s_mov_b32 m0, s42
	s_nop 0
	buffer_load_dwordx4 v222, s[12:15], s78 offen lds
	s_waitcnt vmcnt(8)
	s_waitcnt lgkmcnt(0)
	s_setprio 1
	v_mfma_f32_16x16x32_bf16 v[62:65], v[106:109], v[162:165], v[62:65]
	s_barrier
	v_mfma_f32_16x16x32_bf16 v[62:65], v[118:121], v[166:169], v[62:65]
	v_mfma_f32_16x16x32_bf16 v[58:61], v[130:133], v[162:165], v[58:61]
	v_mfma_f32_16x16x32_bf16 v[58:61], v[138:141], v[166:169], v[58:61]
	v_mfma_f32_16x16x32_bf16 v[42:45], v[130:133], v[170:173], v[42:45]
	v_mfma_f32_16x16x32_bf16 v[42:45], v[138:141], v[174:177], v[42:45]
	v_mfma_f32_16x16x32_bf16 v[46:49], v[106:109], v[170:173], v[46:49]
	v_mfma_f32_16x16x32_bf16 v[46:49], v[118:121], v[174:177], v[46:49]
	v_mfma_f32_16x16x32_bf16 v[54:57], v[146:149], v[162:165], v[54:57]
	v_mfma_f32_16x16x32_bf16 v[54:57], v[150:153], v[166:169], v[54:57]
	v_mfma_f32_16x16x32_bf16 v[50:53], v[154:157], v[162:165], v[50:53]
	v_mfma_f32_16x16x32_bf16 v[50:53], v[158:161], v[166:169], v[50:53]
	v_mfma_f32_16x16x32_bf16 v[34:37], v[154:157], v[170:173], v[34:37]
	v_mfma_f32_16x16x32_bf16 v[34:37], v[158:161], v[174:177], v[34:37]
	v_mfma_f32_16x16x32_bf16 v[38:41], v[146:149], v[170:173], v[38:41]
	v_mfma_f32_16x16x32_bf16 v[38:41], v[150:153], v[174:177], v[38:41]
	v_mfma_f32_16x16x32_bf16 v[30:33], v[106:109], v[178:181], v[30:33]
	v_mfma_f32_16x16x32_bf16 v[30:33], v[118:121], v[182:185], v[30:33]
	v_mfma_f32_16x16x32_bf16 v[26:29], v[130:133], v[178:181], v[26:29]
	v_mfma_f32_16x16x32_bf16 v[26:29], v[138:141], v[182:185], v[26:29]
	v_mfma_f32_16x16x32_bf16 v[10:13], v[130:133], v[190:193], v[10:13]
	v_mfma_f32_16x16x32_bf16 v[10:13], v[138:141], v[194:197], v[10:13]
	v_mfma_f32_16x16x32_bf16 v[14:17], v[106:109], v[190:193], v[14:17]
	v_mfma_f32_16x16x32_bf16 v[14:17], v[118:121], v[194:197], v[14:17]
	v_mfma_f32_16x16x32_bf16 v[22:25], v[146:149], v[178:181], v[22:25]
	v_mfma_f32_16x16x32_bf16 v[22:25], v[150:153], v[182:185], v[22:25]
	v_mfma_f32_16x16x32_bf16 v[18:21], v[154:157], v[178:181], v[18:21]
	v_mfma_f32_16x16x32_bf16 v[18:21], v[158:161], v[182:185], v[18:21]
	v_mfma_f32_16x16x32_bf16 v[2:5], v[154:157], v[190:193], v[2:5]
	v_mfma_f32_16x16x32_bf16 v[2:5], v[158:161], v[194:197], v[2:5]
	v_mfma_f32_16x16x32_bf16 v[6:9], v[146:149], v[190:193], v[6:9]
	v_mfma_f32_16x16x32_bf16 v[6:9], v[150:153], v[194:197], v[6:9]
	s_setprio 0
	s_barrier
	ds_read_b128 v[106:109], v227
	ds_read_b128 v[118:121], v227 offset:1024
	ds_read_b128 v[130:133], v227 offset:2048
	ds_read_b128 v[138:141], v227 offset:3072
	ds_read_b128 v[146:149], v228
	ds_read_b128 v[150:153], v228 offset:1024
	ds_read_b128 v[154:157], v228 offset:2048
	ds_read_b128 v[158:161], v228 offset:3072
	s_mov_b32 m0, s43
	s_add_i32 s78, s75, 0x100000
	ds_read_b128 v[162:165], v226 offset:32768
	ds_read_b128 v[166:169], v226 offset:33792
	ds_read_b128 v[170:173], v226 offset:34816
	ds_read_b128 v[174:177], v226 offset:35840
	ds_read_b128 v[178:181], v226 offset:36864
	ds_read_b128 v[182:185], v226 offset:37888
	ds_read_b128 v[190:193], v226 offset:38912
	ds_read_b128 v[194:197], v226 offset:39936
	buffer_load_dwordx4 v222, s[12:15], s78 offen lds
	s_add_i32 s78, s75, 0x180000
	s_mov_b32 m0, s44
	s_nop 0
	buffer_load_dwordx4 v222, s[12:15], s78 offen lds
	s_waitcnt vmcnt(8)
	s_waitcnt lgkmcnt(0)
	s_setprio 1
	v_mfma_f32_16x16x32_bf16 v[142:145], v[106:109], v[162:165], v[142:145]
	s_barrier
	v_mfma_f32_16x16x32_bf16 v[142:145], v[118:121], v[166:169], v[142:145]
	v_mfma_f32_16x16x32_bf16 v[134:137], v[130:133], v[162:165], v[134:137]
	v_mfma_f32_16x16x32_bf16 v[134:137], v[138:141], v[166:169], v[134:137]
	v_mfma_f32_16x16x32_bf16 v[110:113], v[130:133], v[170:173], v[110:113]
	v_mfma_f32_16x16x32_bf16 v[110:113], v[138:141], v[174:177], v[110:113]
	v_mfma_f32_16x16x32_bf16 v[114:117], v[106:109], v[170:173], v[114:117]
	v_mfma_f32_16x16x32_bf16 v[114:117], v[118:121], v[174:177], v[114:117]
	v_mfma_f32_16x16x32_bf16 v[126:129], v[146:149], v[162:165], v[126:129]
	v_mfma_f32_16x16x32_bf16 v[126:129], v[150:153], v[166:169], v[126:129]
	v_mfma_f32_16x16x32_bf16 v[122:125], v[154:157], v[162:165], v[122:125]
	v_mfma_f32_16x16x32_bf16 v[122:125], v[158:161], v[166:169], v[122:125]
	v_mfma_f32_16x16x32_bf16 v[98:101], v[154:157], v[170:173], v[98:101]
	v_mfma_f32_16x16x32_bf16 v[98:101], v[158:161], v[174:177], v[98:101]
	v_mfma_f32_16x16x32_bf16 v[102:105], v[146:149], v[170:173], v[102:105]
	v_mfma_f32_16x16x32_bf16 v[102:105], v[150:153], v[174:177], v[102:105]
	v_mfma_f32_16x16x32_bf16 v[94:97], v[106:109], v[178:181], v[94:97]
	v_mfma_f32_16x16x32_bf16 v[94:97], v[118:121], v[182:185], v[94:97]
	v_mfma_f32_16x16x32_bf16 v[90:93], v[130:133], v[178:181], v[90:93]
	v_mfma_f32_16x16x32_bf16 v[90:93], v[138:141], v[182:185], v[90:93]
	v_mfma_f32_16x16x32_bf16 v[74:77], v[130:133], v[190:193], v[74:77]
	v_mfma_f32_16x16x32_bf16 v[74:77], v[138:141], v[194:197], v[74:77]
	v_mfma_f32_16x16x32_bf16 v[78:81], v[106:109], v[190:193], v[78:81]
	v_mfma_f32_16x16x32_bf16 v[78:81], v[118:121], v[194:197], v[78:81]
	v_mfma_f32_16x16x32_bf16 v[86:89], v[146:149], v[178:181], v[86:89]
	v_mfma_f32_16x16x32_bf16 v[86:89], v[150:153], v[182:185], v[86:89]
	v_mfma_f32_16x16x32_bf16 v[82:85], v[154:157], v[178:181], v[82:85]
	v_mfma_f32_16x16x32_bf16 v[82:85], v[158:161], v[182:185], v[82:85]
	v_mfma_f32_16x16x32_bf16 v[66:69], v[154:157], v[190:193], v[66:69]
	v_mfma_f32_16x16x32_bf16 v[66:69], v[158:161], v[194:197], v[66:69]
	v_mfma_f32_16x16x32_bf16 v[70:73], v[146:149], v[190:193], v[70:73]
	v_mfma_f32_16x16x32_bf16 v[70:73], v[150:153], v[194:197], v[70:73]
	s_setprio 0
	s_barrier
	s_mov_b32 m0, s48
	s_or_b32 s78, s77, 0x80
	ds_read_b128 v[162:165], v226 offset:49152
	ds_read_b128 v[166:169], v226 offset:50176
	ds_read_b128 v[170:173], v226 offset:51200
	ds_read_b128 v[174:177], v226 offset:52224
	ds_read_b128 v[178:181], v226 offset:53248
	ds_read_b128 v[182:185], v226 offset:54272
	ds_read_b128 v[190:193], v226 offset:55296
	ds_read_b128 v[194:197], v226 offset:56320
	buffer_load_dwordx4 v223, s[16:19], s78 offen lds
	s_add_i32 s78, s77, 0x80080
	s_mov_b32 m0, s49
	s_add_i32 s75, s75, 0x80080
	buffer_load_dwordx4 v223, s[16:19], s78 offen lds
	s_add_i32 s78, s77, 0x100080
	s_mov_b32 m0, s52
	s_add_i32 s77, s77, 0x180080
	buffer_load_dwordx4 v223, s[16:19], s78 offen lds
	s_mov_b32 m0, s53
	s_nop 0
	buffer_load_dwordx4 v223, s[16:19], s77 offen lds
	s_mov_b32 m0, s50
	s_nop 0
	buffer_load_dwordx4 v222, s[12:15], s76 offen lds
	s_mov_b32 m0, s51
	s_nop 0
	buffer_load_dwordx4 v222, s[12:15], s75 offen lds
	s_waitcnt vmcnt(8)
	s_waitcnt lgkmcnt(0)
	s_setprio 1
	v_mfma_f32_16x16x32_bf16 v[62:65], v[106:109], v[162:165], v[62:65]
	s_barrier
	v_mfma_f32_16x16x32_bf16 v[62:65], v[118:121], v[166:169], v[62:65]
	v_mfma_f32_16x16x32_bf16 v[58:61], v[130:133], v[162:165], v[58:61]
	v_mfma_f32_16x16x32_bf16 v[58:61], v[138:141], v[166:169], v[58:61]
	v_mfma_f32_16x16x32_bf16 v[42:45], v[130:133], v[170:173], v[42:45]
	v_mfma_f32_16x16x32_bf16 v[42:45], v[138:141], v[174:177], v[42:45]
	v_mfma_f32_16x16x32_bf16 v[46:49], v[106:109], v[170:173], v[46:49]
	v_mfma_f32_16x16x32_bf16 v[46:49], v[118:121], v[174:177], v[46:49]
	v_mfma_f32_16x16x32_bf16 v[54:57], v[146:149], v[162:165], v[54:57]
	v_mfma_f32_16x16x32_bf16 v[54:57], v[150:153], v[166:169], v[54:57]
	v_mfma_f32_16x16x32_bf16 v[50:53], v[154:157], v[162:165], v[50:53]
	v_mfma_f32_16x16x32_bf16 v[50:53], v[158:161], v[166:169], v[50:53]
	v_mfma_f32_16x16x32_bf16 v[34:37], v[154:157], v[170:173], v[34:37]
	v_mfma_f32_16x16x32_bf16 v[34:37], v[158:161], v[174:177], v[34:37]
	v_mfma_f32_16x16x32_bf16 v[38:41], v[146:149], v[170:173], v[38:41]
	v_mfma_f32_16x16x32_bf16 v[38:41], v[150:153], v[174:177], v[38:41]
	v_mfma_f32_16x16x32_bf16 v[30:33], v[106:109], v[178:181], v[30:33]
	v_mfma_f32_16x16x32_bf16 v[30:33], v[118:121], v[182:185], v[30:33]
	v_mfma_f32_16x16x32_bf16 v[26:29], v[130:133], v[178:181], v[26:29]
	v_mfma_f32_16x16x32_bf16 v[26:29], v[138:141], v[182:185], v[26:29]
	v_mfma_f32_16x16x32_bf16 v[10:13], v[130:133], v[190:193], v[10:13]
	v_mfma_f32_16x16x32_bf16 v[10:13], v[138:141], v[194:197], v[10:13]
	v_mfma_f32_16x16x32_bf16 v[14:17], v[106:109], v[190:193], v[14:17]
	v_mfma_f32_16x16x32_bf16 v[14:17], v[118:121], v[194:197], v[14:17]
	v_mfma_f32_16x16x32_bf16 v[22:25], v[146:149], v[178:181], v[22:25]
	v_mfma_f32_16x16x32_bf16 v[22:25], v[150:153], v[182:185], v[22:25]
	v_mfma_f32_16x16x32_bf16 v[18:21], v[154:157], v[178:181], v[18:21]
	v_mfma_f32_16x16x32_bf16 v[18:21], v[158:161], v[182:185], v[18:21]
	v_mfma_f32_16x16x32_bf16 v[2:5], v[154:157], v[190:193], v[2:5]
	v_mfma_f32_16x16x32_bf16 v[2:5], v[158:161], v[194:197], v[2:5]
	v_mfma_f32_16x16x32_bf16 v[6:9], v[146:149], v[190:193], v[6:9]
	v_mfma_f32_16x16x32_bf16 v[6:9], v[150:153], v[194:197], v[6:9]
	s_setprio 0
	s_barrier
	s_add_i32 s74, s74, 2
	s_addk_i32 s72, 0x100
	s_addk_i32 s73, 0x100
	s_cmp_ge_i32 s74, s3
	s_cbranch_scc0 .LBB0_1290
	s_and_b64 vcc, exec, s[38:39]
	s_cbranch_vccz .LBB0_1293

.LBB0_1382:
	ds_read_b128 v[144:147], v138
	ds_read_b128 v[148:151], v138 offset:1024
	ds_read_b128 v[152:155], v138 offset:2048
	ds_read_b128 v[156:159], v138 offset:3072
	ds_read_b128 v[160:163], v139
	ds_read_b128 v[164:167], v139 offset:1024
	ds_read_b128 v[168:171], v139 offset:2048
	ds_read_b128 v[172:175], v139 offset:3072
	s_add_i32 s14, s74, 0xffe80080
	s_cmp_eq_u32 s61, s76
	s_cselect_b32 s77, s72, s14
	s_cselect_b32 s79, s73, s75
	s_or_b32 s78, s77, 0x80
	s_add_i32 s14, s74, 0xfff80000
	s_mov_b32 m0, s62
	ds_read_b128 v[176:179], v140
	ds_read_b128 v[180:183], v140 offset:1024
	ds_read_b128 v[184:187], v140 offset:2048
	ds_read_b128 v[188:191], v140 offset:3072
	ds_read_b128 v[192:195], v140 offset:4096
	ds_read_b128 v[196:199], v140 offset:5120
	ds_read_b128 v[200:203], v140 offset:6144
	ds_read_b128 v[204:207], v140 offset:7168
	buffer_load_dwordx4 v136, s[16:19], s14 offen lds
	s_mov_b32 m0, s63
	s_nop 0
	buffer_load_dwordx4 v136, s[16:19], s74 offen lds
	s_waitcnt vmcnt(8)
	s_waitcnt lgkmcnt(0)
	s_setprio 1
	v_mfma_f32_16x16x32_bf16 v[118:121], v[144:147], v[176:179], v[118:121]
	s_barrier
	v_mfma_f32_16x16x32_bf16 v[118:121], v[148:151], v[180:183], v[118:121]
	v_mfma_f32_16x16x32_bf16 v[114:117], v[152:155], v[176:179], v[114:117]
	v_mfma_f32_16x16x32_bf16 v[114:117], v[156:159], v[180:183], v[114:117]
	v_mfma_f32_16x16x32_bf16 v[102:105], v[152:155], v[184:187], v[102:105]
	v_mfma_f32_16x16x32_bf16 v[102:105], v[156:159], v[188:191], v[102:105]
	v_mfma_f32_16x16x32_bf16 v[110:113], v[144:147], v[184:187], v[110:113]
	v_mfma_f32_16x16x32_bf16 v[110:113], v[148:151], v[188:191], v[110:113]
	v_mfma_f32_16x16x32_bf16 v[126:129], v[160:163], v[176:179], v[126:129]
	v_mfma_f32_16x16x32_bf16 v[126:129], v[164:167], v[180:183], v[126:129]
	v_mfma_f32_16x16x32_bf16 v[122:125], v[168:171], v[176:179], v[122:125]
	v_mfma_f32_16x16x32_bf16 v[122:125], v[172:175], v[180:183], v[122:125]
	v_mfma_f32_16x16x32_bf16 v[98:101], v[168:171], v[184:187], v[98:101]
	v_mfma_f32_16x16x32_bf16 v[98:101], v[172:175], v[188:191], v[98:101]
	v_mfma_f32_16x16x32_bf16 v[106:109], v[160:163], v[184:187], v[106:109]
	v_mfma_f32_16x16x32_bf16 v[106:109], v[164:167], v[188:191], v[106:109]
	v_mfma_f32_16x16x32_bf16 v[94:97], v[144:147], v[192:195], v[94:97]
	v_mfma_f32_16x16x32_bf16 v[94:97], v[148:151], v[196:199], v[94:97]
	v_mfma_f32_16x16x32_bf16 v[86:89], v[152:155], v[192:195], v[86:89]
	v_mfma_f32_16x16x32_bf16 v[86:89], v[156:159], v[196:199], v[86:89]
	v_mfma_f32_16x16x32_bf16 v[66:69], v[152:155], v[200:203], v[66:69]
	v_mfma_f32_16x16x32_bf16 v[66:69], v[156:159], v[204:207], v[66:69]
	v_mfma_f32_16x16x32_bf16 v[78:81], v[144:147], v[200:203], v[78:81]
	v_mfma_f32_16x16x32_bf16 v[78:81], v[148:151], v[204:207], v[78:81]
	v_mfma_f32_16x16x32_bf16 v[90:93], v[160:163], v[192:195], v[90:93]
	v_mfma_f32_16x16x32_bf16 v[90:93], v[164:167], v[196:199], v[90:93]
	v_mfma_f32_16x16x32_bf16 v[82:85], v[168:171], v[192:195], v[82:85]
	v_mfma_f32_16x16x32_bf16 v[82:85], v[172:175], v[196:199], v[82:85]
	v_mfma_f32_16x16x32_bf16 v[70:73], v[168:171], v[200:203], v[70:73]
	v_mfma_f32_16x16x32_bf16 v[70:73], v[172:175], v[204:207], v[70:73]
	v_mfma_f32_16x16x32_bf16 v[74:77], v[160:163], v[200:203], v[74:77]
	v_mfma_f32_16x16x32_bf16 v[74:77], v[164:167], v[204:207], v[74:77]
	s_setprio 0
	s_barrier
	s_mov_b32 m0, s45
	s_mov_b32 s14, s18
	s_mov_b32 s15, s19
	ds_read_b128 v[176:179], v140 offset:16384
	ds_read_b128 v[180:183], v140 offset:17408
	ds_read_b128 v[184:187], v140 offset:18432
	ds_read_b128 v[188:191], v140 offset:19456
	ds_read_b128 v[192:195], v140 offset:20480
	ds_read_b128 v[196:199], v140 offset:21504
	ds_read_b128 v[200:203], v140 offset:22528
	ds_read_b128 v[204:207], v140 offset:23552
	buffer_load_dwordx4 v137, s[12:15], s79 offen lds
	s_add_i32 s80, s79, 0x80000
	s_mov_b32 m0, s46
	s_nop 0
	buffer_load_dwordx4 v137, s[12:15], s80 offen lds
	s_add_i32 s80, s79, 0x100000
	s_mov_b32 m0, s47
	s_nop 0
	buffer_load_dwordx4 v137, s[12:15], s80 offen lds
	s_add_i32 s80, s79, 0x180000
	s_mov_b32 m0, s48
	s_nop 0
	buffer_load_dwordx4 v137, s[12:15], s80 offen lds
	s_mov_b32 m0, s44
	s_add_i32 s80, s77, 0x80000
	buffer_load_dwordx4 v136, s[16:19], s77 offen lds
	s_mov_b32 m0, s49
	s_nop 0
	buffer_load_dwordx4 v136, s[16:19], s80 offen lds
	s_waitcnt vmcnt(8)
	s_waitcnt lgkmcnt(0)
	s_setprio 1
	v_mfma_f32_16x16x32_bf16 v[62:65], v[144:147], v[176:179], v[62:65]
	s_barrier
	v_mfma_f32_16x16x32_bf16 v[62:65], v[148:151], v[180:183], v[62:65]
	v_mfma_f32_16x16x32_bf16 v[54:57], v[152:155], v[176:179], v[54:57]
	v_mfma_f32_16x16x32_bf16 v[54:57], v[156:159], v[180:183], v[54:57]
	v_mfma_f32_16x16x32_bf16 v[38:41], v[152:155], v[184:187], v[38:41]
	v_mfma_f32_16x16x32_bf16 v[38:41], v[156:159], v[188:191], v[38:41]
	v_mfma_f32_16x16x32_bf16 v[46:49], v[144:147], v[184:187], v[46:49]
	v_mfma_f32_16x16x32_bf16 v[46:49], v[148:151], v[188:191], v[46:49]
	v_mfma_f32_16x16x32_bf16 v[58:61], v[160:163], v[176:179], v[58:61]
	v_mfma_f32_16x16x32_bf16 v[58:61], v[164:167], v[180:183], v[58:61]
	v_mfma_f32_16x16x32_bf16 v[50:53], v[168:171], v[176:179], v[50:53]
	v_mfma_f32_16x16x32_bf16 v[50:53], v[172:175], v[180:183], v[50:53]
	v_mfma_f32_16x16x32_bf16 v[34:37], v[168:171], v[184:187], v[34:37]
	v_mfma_f32_16x16x32_bf16 v[34:37], v[172:175], v[188:191], v[34:37]
	v_mfma_f32_16x16x32_bf16 v[42:45], v[160:163], v[184:187], v[42:45]
	v_mfma_f32_16x16x32_bf16 v[42:45], v[164:167], v[188:191], v[42:45]
	v_mfma_f32_16x16x32_bf16 v[30:33], v[144:147], v[192:195], v[30:33]
	v_mfma_f32_16x16x32_bf16 v[30:33], v[148:151], v[196:199], v[30:33]
	v_mfma_f32_16x16x32_bf16 v[22:25], v[152:155], v[192:195], v[22:25]
	v_mfma_f32_16x16x32_bf16 v[22:25], v[156:159], v[196:199], v[22:25]
	v_mfma_f32_16x16x32_bf16 v[6:9], v[152:155], v[200:203], v[6:9]
	v_mfma_f32_16x16x32_bf16 v[6:9], v[156:159], v[204:207], v[6:9]
	v_mfma_f32_16x16x32_bf16 v[14:17], v[144:147], v[200:203], v[14:17]
	v_mfma_f32_16x16x32_bf16 v[14:17], v[148:151], v[204:207], v[14:17]
	v_mfma_f32_16x16x32_bf16 v[26:29], v[160:163], v[192:195], v[26:29]
	v_mfma_f32_16x16x32_bf16 v[26:29], v[164:167], v[196:199], v[26:29]
	v_mfma_f32_16x16x32_bf16 v[18:21], v[168:171], v[192:195], v[18:21]
	v_mfma_f32_16x16x32_bf16 v[18:21], v[172:175], v[196:199], v[18:21]
	v_mfma_f32_16x16x32_bf16 v[2:5], v[168:171], v[200:203], v[2:5]
	v_mfma_f32_16x16x32_bf16 v[2:5], v[172:175], v[204:207], v[2:5]
	v_mfma_f32_16x16x32_bf16 v[10:13], v[160:163], v[200:203], v[10:13]
	v_mfma_f32_16x16x32_bf16 v[10:13], v[164:167], v[204:207], v[10:13]
	s_setprio 0
	s_barrier
	ds_read_b128 v[144:147], v141
	ds_read_b128 v[148:151], v141 offset:1024
	ds_read_b128 v[152:155], v141 offset:2048
	ds_read_b128 v[156:159], v141 offset:3072
	ds_read_b128 v[160:163], v142
	ds_read_b128 v[164:167], v142 offset:1024
	ds_read_b128 v[168:171], v142 offset:2048
	ds_read_b128 v[172:175], v142 offset:3072
	s_mov_b32 m0, s50
	s_add_i32 s80, s77, 0x100000
	ds_read_b128 v[176:179], v140 offset:32768
	ds_read_b128 v[180:183], v140 offset:33792
	ds_read_b128 v[184:187], v140 offset:34816
	ds_read_b128 v[188:191], v140 offset:35840
	ds_read_b128 v[192:195], v140 offset:36864
	ds_read_b128 v[196:199], v140 offset:37888
	ds_read_b128 v[200:203], v140 offset:38912
	ds_read_b128 v[204:207], v140 offset:39936
	buffer_load_dwordx4 v136, s[16:19], s80 offen lds
	s_add_i32 s80, s77, 0x180000
	s_mov_b32 m0, s51
	s_nop 0
	buffer_load_dwordx4 v136, s[16:19], s80 offen lds
	s_waitcnt vmcnt(8)
	s_waitcnt lgkmcnt(0)
	s_setprio 1
	v_mfma_f32_16x16x32_bf16 v[118:121], v[144:147], v[176:179], v[118:121]
	s_barrier
	v_mfma_f32_16x16x32_bf16 v[118:121], v[148:151], v[180:183], v[118:121]
	v_mfma_f32_16x16x32_bf16 v[114:117], v[152:155], v[176:179], v[114:117]
	v_mfma_f32_16x16x32_bf16 v[114:117], v[156:159], v[180:183], v[114:117]
	v_mfma_f32_16x16x32_bf16 v[102:105], v[152:155], v[184:187], v[102:105]
	v_mfma_f32_16x16x32_bf16 v[102:105], v[156:159], v[188:191], v[102:105]
	v_mfma_f32_16x16x32_bf16 v[110:113], v[144:147], v[184:187], v[110:113]
	v_mfma_f32_16x16x32_bf16 v[110:113], v[148:151], v[188:191], v[110:113]
	v_mfma_f32_16x16x32_bf16 v[126:129], v[160:163], v[176:179], v[126:129]
	v_mfma_f32_16x16x32_bf16 v[126:129], v[164:167], v[180:183], v[126:129]
	v_mfma_f32_16x16x32_bf16 v[122:125], v[168:171], v[176:179], v[122:125]
	v_mfma_f32_16x16x32_bf16 v[122:125], v[172:175], v[180:183], v[122:125]
	v_mfma_f32_16x16x32_bf16 v[98:101], v[168:171], v[184:187], v[98:101]
	v_mfma_f32_16x16x32_bf16 v[98:101], v[172:175], v[188:191], v[98:101]
	v_mfma_f32_16x16x32_bf16 v[106:109], v[160:163], v[184:187], v[106:109]
	v_mfma_f32_16x16x32_bf16 v[106:109], v[164:167], v[188:191], v[106:109]
	v_mfma_f32_16x16x32_bf16 v[94:97], v[144:147], v[192:195], v[94:97]
	v_mfma_f32_16x16x32_bf16 v[94:97], v[148:151], v[196:199], v[94:97]
	v_mfma_f32_16x16x32_bf16 v[86:89], v[152:155], v[192:195], v[86:89]
	v_mfma_f32_16x16x32_bf16 v[86:89], v[156:159], v[196:199], v[86:89]
	v_mfma_f32_16x16x32_bf16 v[66:69], v[152:155], v[200:203], v[66:69]
	v_mfma_f32_16x16x32_bf16 v[66:69], v[156:159], v[204:207], v[66:69]
	v_mfma_f32_16x16x32_bf16 v[78:81], v[144:147], v[200:203], v[78:81]
	v_mfma_f32_16x16x32_bf16 v[78:81], v[148:151], v[204:207], v[78:81]
	v_mfma_f32_16x16x32_bf16 v[90:93], v[160:163], v[192:195], v[90:93]
	v_mfma_f32_16x16x32_bf16 v[90:93], v[164:167], v[196:199], v[90:93]
	v_mfma_f32_16x16x32_bf16 v[82:85], v[168:171], v[192:195], v[82:85]
	v_mfma_f32_16x16x32_bf16 v[82:85], v[172:175], v[196:199], v[82:85]
	v_mfma_f32_16x16x32_bf16 v[70:73], v[168:171], v[200:203], v[70:73]
	v_mfma_f32_16x16x32_bf16 v[70:73], v[172:175], v[204:207], v[70:73]
	v_mfma_f32_16x16x32_bf16 v[74:77], v[160:163], v[200:203], v[74:77]
	v_mfma_f32_16x16x32_bf16 v[74:77], v[164:167], v[204:207], v[74:77]
	s_setprio 0
	s_barrier
	s_mov_b32 m0, s53
	s_or_b32 s80, s79, 0x80
	ds_read_b128 v[176:179], v140 offset:49152
	ds_read_b128 v[180:183], v140 offset:50176
	ds_read_b128 v[184:187], v140 offset:51200
	ds_read_b128 v[188:191], v140 offset:52224
	ds_read_b128 v[192:195], v140 offset:53248
	ds_read_b128 v[196:199], v140 offset:54272
	ds_read_b128 v[200:203], v140 offset:55296
	ds_read_b128 v[204:207], v140 offset:56320
	buffer_load_dwordx4 v137, s[12:15], s80 offen lds
	s_add_i32 s80, s79, 0x80080
	s_mov_b32 m0, s54
	s_add_i32 s77, s77, 0x80080
	buffer_load_dwordx4 v137, s[12:15], s80 offen lds
	s_add_i32 s80, s79, 0x100080
	s_mov_b32 m0, s57
	s_add_i32 s79, s79, 0x180080
	buffer_load_dwordx4 v137, s[12:15], s80 offen lds
	s_mov_b32 m0, s58
	s_nop 0
	buffer_load_dwordx4 v137, s[12:15], s79 offen lds
	s_mov_b32 m0, s55
	s_nop 0
	buffer_load_dwordx4 v136, s[16:19], s78 offen lds
	s_mov_b32 m0, s56
	s_nop 0
	buffer_load_dwordx4 v136, s[16:19], s77 offen lds
	s_waitcnt vmcnt(8)
	s_waitcnt lgkmcnt(0)
	s_setprio 1
	v_mfma_f32_16x16x32_bf16 v[62:65], v[144:147], v[176:179], v[62:65]
	s_barrier
	v_mfma_f32_16x16x32_bf16 v[62:65], v[148:151], v[180:183], v[62:65]
	v_mfma_f32_16x16x32_bf16 v[54:57], v[152:155], v[176:179], v[54:57]
	v_mfma_f32_16x16x32_bf16 v[54:57], v[156:159], v[180:183], v[54:57]
	v_mfma_f32_16x16x32_bf16 v[38:41], v[152:155], v[184:187], v[38:41]
	v_mfma_f32_16x16x32_bf16 v[38:41], v[156:159], v[188:191], v[38:41]
	v_mfma_f32_16x16x32_bf16 v[46:49], v[144:147], v[184:187], v[46:49]
	v_mfma_f32_16x16x32_bf16 v[46:49], v[148:151], v[188:191], v[46:49]
	v_mfma_f32_16x16x32_bf16 v[58:61], v[160:163], v[176:179], v[58:61]
	v_mfma_f32_16x16x32_bf16 v[58:61], v[164:167], v[180:183], v[58:61]
	v_mfma_f32_16x16x32_bf16 v[50:53], v[168:171], v[176:179], v[50:53]
	v_mfma_f32_16x16x32_bf16 v[50:53], v[172:175], v[180:183], v[50:53]
	v_mfma_f32_16x16x32_bf16 v[34:37], v[168:171], v[184:187], v[34:37]
	v_mfma_f32_16x16x32_bf16 v[34:37], v[172:175], v[188:191], v[34:37]
	v_mfma_f32_16x16x32_bf16 v[42:45], v[160:163], v[184:187], v[42:45]
	v_mfma_f32_16x16x32_bf16 v[42:45], v[164:167], v[188:191], v[42:45]
	v_mfma_f32_16x16x32_bf16 v[30:33], v[144:147], v[192:195], v[30:33]
	v_mfma_f32_16x16x32_bf16 v[30:33], v[148:151], v[196:199], v[30:33]
	v_mfma_f32_16x16x32_bf16 v[22:25], v[152:155], v[192:195], v[22:25]
	v_mfma_f32_16x16x32_bf16 v[22:25], v[156:159], v[196:199], v[22:25]
	v_mfma_f32_16x16x32_bf16 v[6:9], v[152:155], v[200:203], v[6:9]
	v_mfma_f32_16x16x32_bf16 v[6:9], v[156:159], v[204:207], v[6:9]
	v_mfma_f32_16x16x32_bf16 v[14:17], v[144:147], v[200:203], v[14:17]
	v_mfma_f32_16x16x32_bf16 v[14:17], v[148:151], v[204:207], v[14:17]
	v_mfma_f32_16x16x32_bf16 v[26:29], v[160:163], v[192:195], v[26:29]
	v_mfma_f32_16x16x32_bf16 v[26:29], v[164:167], v[196:199], v[26:29]
	v_mfma_f32_16x16x32_bf16 v[18:21], v[168:171], v[192:195], v[18:21]
	v_mfma_f32_16x16x32_bf16 v[18:21], v[172:175], v[196:199], v[18:21]
	v_mfma_f32_16x16x32_bf16 v[2:5], v[168:171], v[200:203], v[2:5]
	v_mfma_f32_16x16x32_bf16 v[2:5], v[172:175], v[204:207], v[2:5]
	v_mfma_f32_16x16x32_bf16 v[10:13], v[160:163], v[200:203], v[10:13]
	v_mfma_f32_16x16x32_bf16 v[10:13], v[164:167], v[204:207], v[10:13]
	s_setprio 0
	s_barrier
	s_add_i32 s76, s76, 2
	s_addk_i32 s74, 0x100
	s_addk_i32 s75, 0x100
	s_cmp_ge_i32 s76, s27
	s_cbranch_scc0 .LBB0_1382
	s_and_b64 vcc, exec, s[42:43]
	s_cbranch_vccz .LBB0_1385

.LBB0_1402:
	ds_read_b128 v[146:149], v138
	ds_read_b128 v[150:153], v138 offset:1024
	ds_read_b128 v[154:157], v138 offset:2048
	ds_read_b128 v[158:161], v138 offset:3072
	ds_read_b128 v[162:165], v139
	ds_read_b128 v[166:169], v139 offset:1024
	ds_read_b128 v[170:173], v139 offset:2048
	ds_read_b128 v[174:177], v139 offset:3072
	s_add_i32 s22, s75, 0xffe80080
	s_cmp_eq_u32 s62, s77
	s_cselect_b32 s78, s73, s22
	s_cselect_b32 s80, s74, s76
	s_or_b32 s79, s78, 0x80
	s_add_i32 s22, s75, 0xfff80000
	s_mov_b32 m0, s63
	ds_read_b128 v[178:181], v140
	ds_read_b128 v[182:185], v140 offset:1024
	ds_read_b128 v[186:189], v140 offset:2048
	ds_read_b128 v[190:193], v140 offset:3072
	ds_read_b128 v[194:197], v140 offset:4096
	ds_read_b128 v[198:201], v140 offset:5120
	ds_read_b128 v[202:205], v140 offset:6144
	ds_read_b128 v[206:209], v140 offset:7168
	buffer_load_dwordx4 v136, s[16:19], s22 offen lds
	s_mov_b32 m0, s64
	s_nop 0
	buffer_load_dwordx4 v136, s[16:19], s75 offen lds
	s_waitcnt vmcnt(8)
	s_waitcnt lgkmcnt(0)
	s_setprio 1
	v_mfma_f32_16x16x32_bf16 v[118:121], v[146:149], v[178:181], v[118:121]
	s_barrier
	v_mfma_f32_16x16x32_bf16 v[118:121], v[150:153], v[182:185], v[118:121]
	v_mfma_f32_16x16x32_bf16 v[114:117], v[154:157], v[178:181], v[114:117]
	v_mfma_f32_16x16x32_bf16 v[114:117], v[158:161], v[182:185], v[114:117]
	v_mfma_f32_16x16x32_bf16 v[102:105], v[154:157], v[186:189], v[102:105]
	v_mfma_f32_16x16x32_bf16 v[102:105], v[158:161], v[190:193], v[102:105]
	v_mfma_f32_16x16x32_bf16 v[110:113], v[146:149], v[186:189], v[110:113]
	v_mfma_f32_16x16x32_bf16 v[110:113], v[150:153], v[190:193], v[110:113]
	v_mfma_f32_16x16x32_bf16 v[126:129], v[162:165], v[178:181], v[126:129]
	v_mfma_f32_16x16x32_bf16 v[126:129], v[166:169], v[182:185], v[126:129]
	v_mfma_f32_16x16x32_bf16 v[122:125], v[170:173], v[178:181], v[122:125]
	v_mfma_f32_16x16x32_bf16 v[122:125], v[174:177], v[182:185], v[122:125]
	v_mfma_f32_16x16x32_bf16 v[98:101], v[170:173], v[186:189], v[98:101]
	v_mfma_f32_16x16x32_bf16 v[98:101], v[174:177], v[190:193], v[98:101]
	v_mfma_f32_16x16x32_bf16 v[106:109], v[162:165], v[186:189], v[106:109]
	v_mfma_f32_16x16x32_bf16 v[106:109], v[166:169], v[190:193], v[106:109]
	v_mfma_f32_16x16x32_bf16 v[94:97], v[146:149], v[194:197], v[94:97]
	v_mfma_f32_16x16x32_bf16 v[94:97], v[150:153], v[198:201], v[94:97]
	v_mfma_f32_16x16x32_bf16 v[86:89], v[154:157], v[194:197], v[86:89]
	v_mfma_f32_16x16x32_bf16 v[86:89], v[158:161], v[198:201], v[86:89]
	v_mfma_f32_16x16x32_bf16 v[66:69], v[154:157], v[202:205], v[66:69]
	v_mfma_f32_16x16x32_bf16 v[66:69], v[158:161], v[206:209], v[66:69]
	v_mfma_f32_16x16x32_bf16 v[78:81], v[146:149], v[202:205], v[78:81]
	v_mfma_f32_16x16x32_bf16 v[78:81], v[150:153], v[206:209], v[78:81]
	v_mfma_f32_16x16x32_bf16 v[90:93], v[162:165], v[194:197], v[90:93]
	v_mfma_f32_16x16x32_bf16 v[90:93], v[166:169], v[198:201], v[90:93]
	v_mfma_f32_16x16x32_bf16 v[82:85], v[170:173], v[194:197], v[82:85]
	v_mfma_f32_16x16x32_bf16 v[82:85], v[174:177], v[198:201], v[82:85]
	v_mfma_f32_16x16x32_bf16 v[70:73], v[170:173], v[202:205], v[70:73]
	v_mfma_f32_16x16x32_bf16 v[70:73], v[174:177], v[206:209], v[70:73]
	v_mfma_f32_16x16x32_bf16 v[74:77], v[162:165], v[202:205], v[74:77]
	v_mfma_f32_16x16x32_bf16 v[74:77], v[166:169], v[206:209], v[74:77]
	s_setprio 0
	s_barrier
	s_mov_b32 m0, s31
	s_mov_b32 s22, s18
	s_mov_b32 s23, s19
	ds_read_b128 v[178:181], v140 offset:16384
	ds_read_b128 v[182:185], v140 offset:17408
	ds_read_b128 v[186:189], v140 offset:18432
	ds_read_b128 v[190:193], v140 offset:19456
	ds_read_b128 v[194:197], v140 offset:20480
	ds_read_b128 v[198:201], v140 offset:21504
	ds_read_b128 v[202:205], v140 offset:22528
	ds_read_b128 v[206:209], v140 offset:23552
	buffer_load_dwordx4 v137, s[20:23], s80 offen lds
	s_add_i32 s81, s80, 0x80000
	s_mov_b32 m0, s48
	s_nop 0
	buffer_load_dwordx4 v137, s[20:23], s81 offen lds
	s_add_i32 s81, s80, 0x100000
	s_mov_b32 m0, s49
	s_nop 0
	buffer_load_dwordx4 v137, s[20:23], s81 offen lds
	s_add_i32 s81, s80, 0x180000
	s_mov_b32 m0, s50
	s_nop 0
	buffer_load_dwordx4 v137, s[20:23], s81 offen lds
	s_mov_b32 m0, s30
	s_add_i32 s81, s78, 0x80000
	buffer_load_dwordx4 v136, s[16:19], s78 offen lds
	s_mov_b32 m0, s51
	s_nop 0
	buffer_load_dwordx4 v136, s[16:19], s81 offen lds
	s_waitcnt vmcnt(8)
	s_waitcnt lgkmcnt(0)
	s_setprio 1
	v_mfma_f32_16x16x32_bf16 v[62:65], v[146:149], v[178:181], v[62:65]
	s_barrier
	v_mfma_f32_16x16x32_bf16 v[62:65], v[150:153], v[182:185], v[62:65]
	v_mfma_f32_16x16x32_bf16 v[54:57], v[154:157], v[178:181], v[54:57]
	v_mfma_f32_16x16x32_bf16 v[54:57], v[158:161], v[182:185], v[54:57]
	v_mfma_f32_16x16x32_bf16 v[38:41], v[154:157], v[186:189], v[38:41]
	v_mfma_f32_16x16x32_bf16 v[38:41], v[158:161], v[190:193], v[38:41]
	v_mfma_f32_16x16x32_bf16 v[46:49], v[146:149], v[186:189], v[46:49]
	v_mfma_f32_16x16x32_bf16 v[46:49], v[150:153], v[190:193], v[46:49]
	v_mfma_f32_16x16x32_bf16 v[58:61], v[162:165], v[178:181], v[58:61]
	v_mfma_f32_16x16x32_bf16 v[58:61], v[166:169], v[182:185], v[58:61]
	v_mfma_f32_16x16x32_bf16 v[50:53], v[170:173], v[178:181], v[50:53]
	v_mfma_f32_16x16x32_bf16 v[50:53], v[174:177], v[182:185], v[50:53]
	v_mfma_f32_16x16x32_bf16 v[34:37], v[170:173], v[186:189], v[34:37]
	v_mfma_f32_16x16x32_bf16 v[34:37], v[174:177], v[190:193], v[34:37]
	v_mfma_f32_16x16x32_bf16 v[42:45], v[162:165], v[186:189], v[42:45]
	v_mfma_f32_16x16x32_bf16 v[42:45], v[166:169], v[190:193], v[42:45]
	v_mfma_f32_16x16x32_bf16 v[30:33], v[146:149], v[194:197], v[30:33]
	v_mfma_f32_16x16x32_bf16 v[30:33], v[150:153], v[198:201], v[30:33]
	v_mfma_f32_16x16x32_bf16 v[22:25], v[154:157], v[194:197], v[22:25]
	v_mfma_f32_16x16x32_bf16 v[22:25], v[158:161], v[198:201], v[22:25]
	v_mfma_f32_16x16x32_bf16 v[6:9], v[154:157], v[202:205], v[6:9]
	v_mfma_f32_16x16x32_bf16 v[6:9], v[158:161], v[206:209], v[6:9]
	v_mfma_f32_16x16x32_bf16 v[14:17], v[146:149], v[202:205], v[14:17]
	v_mfma_f32_16x16x32_bf16 v[14:17], v[150:153], v[206:209], v[14:17]
	v_mfma_f32_16x16x32_bf16 v[26:29], v[162:165], v[194:197], v[26:29]
	v_mfma_f32_16x16x32_bf16 v[26:29], v[166:169], v[198:201], v[26:29]
	v_mfma_f32_16x16x32_bf16 v[18:21], v[170:173], v[194:197], v[18:21]
	v_mfma_f32_16x16x32_bf16 v[18:21], v[174:177], v[198:201], v[18:21]
	v_mfma_f32_16x16x32_bf16 v[2:5], v[170:173], v[202:205], v[2:5]
	v_mfma_f32_16x16x32_bf16 v[2:5], v[174:177], v[206:209], v[2:5]
	v_mfma_f32_16x16x32_bf16 v[10:13], v[162:165], v[202:205], v[10:13]
	v_mfma_f32_16x16x32_bf16 v[10:13], v[166:169], v[206:209], v[10:13]
	s_setprio 0
	s_barrier
	ds_read_b128 v[146:149], v141
	ds_read_b128 v[150:153], v141 offset:1024
	ds_read_b128 v[154:157], v141 offset:2048
	ds_read_b128 v[158:161], v141 offset:3072
	ds_read_b128 v[162:165], v142
	ds_read_b128 v[166:169], v142 offset:1024
	ds_read_b128 v[170:173], v142 offset:2048
	ds_read_b128 v[174:177], v142 offset:3072
	s_mov_b32 m0, s52
	s_add_i32 s81, s78, 0x100000
	ds_read_b128 v[178:181], v140 offset:32768
	ds_read_b128 v[182:185], v140 offset:33792
	ds_read_b128 v[186:189], v140 offset:34816
	ds_read_b128 v[190:193], v140 offset:35840
	ds_read_b128 v[194:197], v140 offset:36864
	ds_read_b128 v[198:201], v140 offset:37888
	ds_read_b128 v[202:205], v140 offset:38912
	ds_read_b128 v[206:209], v140 offset:39936
	buffer_load_dwordx4 v136, s[16:19], s81 offen lds
	s_add_i32 s81, s78, 0x180000
	s_mov_b32 m0, s53
	s_nop 0
	buffer_load_dwordx4 v136, s[16:19], s81 offen lds
	s_waitcnt vmcnt(8)
	s_waitcnt lgkmcnt(0)
	s_setprio 1
	v_mfma_f32_16x16x32_bf16 v[118:121], v[146:149], v[178:181], v[118:121]
	s_barrier
	v_mfma_f32_16x16x32_bf16 v[118:121], v[150:153], v[182:185], v[118:121]
	v_mfma_f32_16x16x32_bf16 v[114:117], v[154:157], v[178:181], v[114:117]
	v_mfma_f32_16x16x32_bf16 v[114:117], v[158:161], v[182:185], v[114:117]
	v_mfma_f32_16x16x32_bf16 v[102:105], v[154:157], v[186:189], v[102:105]
	v_mfma_f32_16x16x32_bf16 v[102:105], v[158:161], v[190:193], v[102:105]
	v_mfma_f32_16x16x32_bf16 v[110:113], v[146:149], v[186:189], v[110:113]
	v_mfma_f32_16x16x32_bf16 v[110:113], v[150:153], v[190:193], v[110:113]
	v_mfma_f32_16x16x32_bf16 v[126:129], v[162:165], v[178:181], v[126:129]
	v_mfma_f32_16x16x32_bf16 v[126:129], v[166:169], v[182:185], v[126:129]
	v_mfma_f32_16x16x32_bf16 v[122:125], v[170:173], v[178:181], v[122:125]
	v_mfma_f32_16x16x32_bf16 v[122:125], v[174:177], v[182:185], v[122:125]
	v_mfma_f32_16x16x32_bf16 v[98:101], v[170:173], v[186:189], v[98:101]
	v_mfma_f32_16x16x32_bf16 v[98:101], v[174:177], v[190:193], v[98:101]
	v_mfma_f32_16x16x32_bf16 v[106:109], v[162:165], v[186:189], v[106:109]
	v_mfma_f32_16x16x32_bf16 v[106:109], v[166:169], v[190:193], v[106:109]
	v_mfma_f32_16x16x32_bf16 v[94:97], v[146:149], v[194:197], v[94:97]
	v_mfma_f32_16x16x32_bf16 v[94:97], v[150:153], v[198:201], v[94:97]
	v_mfma_f32_16x16x32_bf16 v[86:89], v[154:157], v[194:197], v[86:89]
	v_mfma_f32_16x16x32_bf16 v[86:89], v[158:161], v[198:201], v[86:89]
	v_mfma_f32_16x16x32_bf16 v[66:69], v[154:157], v[202:205], v[66:69]
	v_mfma_f32_16x16x32_bf16 v[66:69], v[158:161], v[206:209], v[66:69]
	v_mfma_f32_16x16x32_bf16 v[78:81], v[146:149], v[202:205], v[78:81]
	v_mfma_f32_16x16x32_bf16 v[78:81], v[150:153], v[206:209], v[78:81]
	v_mfma_f32_16x16x32_bf16 v[90:93], v[162:165], v[194:197], v[90:93]
	v_mfma_f32_16x16x32_bf16 v[90:93], v[166:169], v[198:201], v[90:93]
	v_mfma_f32_16x16x32_bf16 v[82:85], v[170:173], v[194:197], v[82:85]
	v_mfma_f32_16x16x32_bf16 v[82:85], v[174:177], v[198:201], v[82:85]
	v_mfma_f32_16x16x32_bf16 v[70:73], v[170:173], v[202:205], v[70:73]
	v_mfma_f32_16x16x32_bf16 v[70:73], v[174:177], v[206:209], v[70:73]
	v_mfma_f32_16x16x32_bf16 v[74:77], v[162:165], v[202:205], v[74:77]
	v_mfma_f32_16x16x32_bf16 v[74:77], v[166:169], v[206:209], v[74:77]
	s_setprio 0
	s_barrier
	s_mov_b32 m0, s54
	s_or_b32 s81, s80, 0x80
	ds_read_b128 v[178:181], v140 offset:49152
	ds_read_b128 v[182:185], v140 offset:50176
	ds_read_b128 v[186:189], v140 offset:51200
	ds_read_b128 v[190:193], v140 offset:52224
	ds_read_b128 v[194:197], v140 offset:53248
	ds_read_b128 v[198:201], v140 offset:54272
	ds_read_b128 v[202:205], v140 offset:55296
	ds_read_b128 v[206:209], v140 offset:56320
	buffer_load_dwordx4 v137, s[20:23], s81 offen lds
	s_add_i32 s81, s80, 0x80080
	s_mov_b32 m0, s55
	s_add_i32 s78, s78, 0x80080
	buffer_load_dwordx4 v137, s[20:23], s81 offen lds
	s_add_i32 s81, s80, 0x100080
	s_mov_b32 m0, s58
	s_add_i32 s80, s80, 0x180080
	buffer_load_dwordx4 v137, s[20:23], s81 offen lds
	s_mov_b32 m0, s59
	s_nop 0
	buffer_load_dwordx4 v137, s[20:23], s80 offen lds
	s_mov_b32 m0, s56
	s_nop 0
	buffer_load_dwordx4 v136, s[16:19], s79 offen lds
	s_mov_b32 m0, s57
	s_nop 0
	buffer_load_dwordx4 v136, s[16:19], s78 offen lds
	s_waitcnt vmcnt(8)
	s_waitcnt lgkmcnt(0)
	s_setprio 1
	v_mfma_f32_16x16x32_bf16 v[62:65], v[146:149], v[178:181], v[62:65]
	s_barrier
	v_mfma_f32_16x16x32_bf16 v[62:65], v[150:153], v[182:185], v[62:65]
	v_mfma_f32_16x16x32_bf16 v[54:57], v[154:157], v[178:181], v[54:57]
	v_mfma_f32_16x16x32_bf16 v[54:57], v[158:161], v[182:185], v[54:57]
	v_mfma_f32_16x16x32_bf16 v[38:41], v[154:157], v[186:189], v[38:41]
	v_mfma_f32_16x16x32_bf16 v[38:41], v[158:161], v[190:193], v[38:41]
	v_mfma_f32_16x16x32_bf16 v[46:49], v[146:149], v[186:189], v[46:49]
	v_mfma_f32_16x16x32_bf16 v[46:49], v[150:153], v[190:193], v[46:49]
	v_mfma_f32_16x16x32_bf16 v[58:61], v[162:165], v[178:181], v[58:61]
	v_mfma_f32_16x16x32_bf16 v[58:61], v[166:169], v[182:185], v[58:61]
	v_mfma_f32_16x16x32_bf16 v[50:53], v[170:173], v[178:181], v[50:53]
	v_mfma_f32_16x16x32_bf16 v[50:53], v[174:177], v[182:185], v[50:53]
	v_mfma_f32_16x16x32_bf16 v[34:37], v[170:173], v[186:189], v[34:37]
	v_mfma_f32_16x16x32_bf16 v[34:37], v[174:177], v[190:193], v[34:37]
	v_mfma_f32_16x16x32_bf16 v[42:45], v[162:165], v[186:189], v[42:45]
	v_mfma_f32_16x16x32_bf16 v[42:45], v[166:169], v[190:193], v[42:45]
	v_mfma_f32_16x16x32_bf16 v[30:33], v[146:149], v[194:197], v[30:33]
	v_mfma_f32_16x16x32_bf16 v[30:33], v[150:153], v[198:201], v[30:33]
	v_mfma_f32_16x16x32_bf16 v[22:25], v[154:157], v[194:197], v[22:25]
	v_mfma_f32_16x16x32_bf16 v[22:25], v[158:161], v[198:201], v[22:25]
	v_mfma_f32_16x16x32_bf16 v[6:9], v[154:157], v[202:205], v[6:9]
	v_mfma_f32_16x16x32_bf16 v[6:9], v[158:161], v[206:209], v[6:9]
	v_mfma_f32_16x16x32_bf16 v[14:17], v[146:149], v[202:205], v[14:17]
	v_mfma_f32_16x16x32_bf16 v[14:17], v[150:153], v[206:209], v[14:17]
	v_mfma_f32_16x16x32_bf16 v[26:29], v[162:165], v[194:197], v[26:29]
	v_mfma_f32_16x16x32_bf16 v[26:29], v[166:169], v[198:201], v[26:29]
	v_mfma_f32_16x16x32_bf16 v[18:21], v[170:173], v[194:197], v[18:21]
	v_mfma_f32_16x16x32_bf16 v[18:21], v[174:177], v[198:201], v[18:21]
	v_mfma_f32_16x16x32_bf16 v[2:5], v[170:173], v[202:205], v[2:5]
	v_mfma_f32_16x16x32_bf16 v[2:5], v[174:177], v[206:209], v[2:5]
	v_mfma_f32_16x16x32_bf16 v[10:13], v[162:165], v[202:205], v[10:13]
	v_mfma_f32_16x16x32_bf16 v[10:13], v[166:169], v[206:209], v[10:13]
	s_setprio 0
	s_barrier
	s_add_i32 s77, s77, 2
	s_addk_i32 s75, 0x100
	s_addk_i32 s76, 0x100
	s_cmp_ge_i32 s77, s13
	s_cbranch_scc0 .LBB0_1402
	s_and_b64 vcc, exec, s[46:47]
	s_cbranch_vccz .LBB0_1405

.LBB0_1519:
	ds_read_b128 v[134:137], v208
	ds_read_b128 v[138:141], v208 offset:1024
	ds_read_b128 v[142:145], v208 offset:2048
	ds_read_b128 v[146:149], v208 offset:3072
	ds_read_b128 v[150:153], v209
	ds_read_b128 v[154:157], v209 offset:1024
	ds_read_b128 v[158:161], v209 offset:2048
	ds_read_b128 v[162:165], v209 offset:3072
	s_add_i32 s18, s80, 0xffbf8080
	s_cmp_eq_u32 s65, s82
	s_cselect_b32 s83, s6, s18
	s_cselect_b32 s85, s7, s81
	s_or_b32 s84, s83, 0x80
	s_add_i32 s18, s80, 0xffea8000
	s_mov_b32 m0, s66
	ds_read_b128 v[166:169], v210
	ds_read_b128 v[170:173], v210 offset:1024
	ds_read_b128 v[174:177], v210 offset:2048
	ds_read_b128 v[178:181], v210 offset:3072
	ds_read_b128 v[182:185], v210 offset:4096
	ds_read_b128 v[186:189], v210 offset:5120
	ds_read_b128 v[190:193], v210 offset:6144
	ds_read_b128 v[194:197], v210 offset:7168
	buffer_load_dwordx4 v206, s[12:15], s18 offen lds
	s_mov_b32 m0, s69
	s_nop 0
	buffer_load_dwordx4 v206, s[12:15], s80 offen lds
	s_waitcnt vmcnt(8)
	s_waitcnt lgkmcnt(0)
	s_setprio 1
	v_mfma_f32_16x16x32_bf16 v[126:129], v[134:137], v[166:169], v[126:129]
	s_barrier
	v_mfma_f32_16x16x32_bf16 v[126:129], v[138:141], v[170:173], v[126:129]
	v_mfma_f32_16x16x32_bf16 v[122:125], v[142:145], v[166:169], v[122:125]
	v_mfma_f32_16x16x32_bf16 v[122:125], v[146:149], v[170:173], v[122:125]
	v_mfma_f32_16x16x32_bf16 v[114:117], v[142:145], v[174:177], v[114:117]
	v_mfma_f32_16x16x32_bf16 v[114:117], v[146:149], v[178:181], v[114:117]
	v_mfma_f32_16x16x32_bf16 v[118:121], v[134:137], v[174:177], v[118:121]
	v_mfma_f32_16x16x32_bf16 v[118:121], v[138:141], v[178:181], v[118:121]
	v_mfma_f32_16x16x32_bf16 v[110:113], v[150:153], v[166:169], v[110:113]
	v_mfma_f32_16x16x32_bf16 v[110:113], v[154:157], v[170:173], v[110:113]
	v_mfma_f32_16x16x32_bf16 v[102:105], v[158:161], v[166:169], v[102:105]
	v_mfma_f32_16x16x32_bf16 v[102:105], v[162:165], v[170:173], v[102:105]
	v_mfma_f32_16x16x32_bf16 v[86:89], v[158:161], v[174:177], v[86:89]
	v_mfma_f32_16x16x32_bf16 v[86:89], v[162:165], v[178:181], v[86:89]
	v_mfma_f32_16x16x32_bf16 v[94:97], v[150:153], v[174:177], v[94:97]
	v_mfma_f32_16x16x32_bf16 v[94:97], v[154:157], v[178:181], v[94:97]
	v_mfma_f32_16x16x32_bf16 v[106:109], v[134:137], v[182:185], v[106:109]
	v_mfma_f32_16x16x32_bf16 v[106:109], v[138:141], v[186:189], v[106:109]
	v_mfma_f32_16x16x32_bf16 v[98:101], v[142:145], v[182:185], v[98:101]
	v_mfma_f32_16x16x32_bf16 v[98:101], v[146:149], v[186:189], v[98:101]
	v_mfma_f32_16x16x32_bf16 v[82:85], v[142:145], v[190:193], v[82:85]
	v_mfma_f32_16x16x32_bf16 v[82:85], v[146:149], v[194:197], v[82:85]
	v_mfma_f32_16x16x32_bf16 v[90:93], v[134:137], v[190:193], v[90:93]
	v_mfma_f32_16x16x32_bf16 v[90:93], v[138:141], v[194:197], v[90:93]
	v_mfma_f32_16x16x32_bf16 v[78:81], v[150:153], v[182:185], v[78:81]
	v_mfma_f32_16x16x32_bf16 v[78:81], v[154:157], v[186:189], v[78:81]
	v_mfma_f32_16x16x32_bf16 v[74:77], v[158:161], v[182:185], v[74:77]
	v_mfma_f32_16x16x32_bf16 v[74:77], v[162:165], v[186:189], v[74:77]
	v_mfma_f32_16x16x32_bf16 v[66:69], v[158:161], v[190:193], v[66:69]
	v_mfma_f32_16x16x32_bf16 v[66:69], v[162:165], v[194:197], v[66:69]
	v_mfma_f32_16x16x32_bf16 v[70:73], v[150:153], v[190:193], v[70:73]
	v_mfma_f32_16x16x32_bf16 v[70:73], v[154:157], v[194:197], v[70:73]
	s_setprio 0
	s_barrier
	s_mov_b32 m0, s27
	s_mov_b32 s18, s14
	s_mov_b32 s19, s15
	ds_read_b128 v[166:169], v210 offset:16384
	ds_read_b128 v[170:173], v210 offset:17408
	ds_read_b128 v[174:177], v210 offset:18432
	ds_read_b128 v[178:181], v210 offset:19456
	ds_read_b128 v[182:185], v210 offset:20480
	ds_read_b128 v[186:189], v210 offset:21504
	ds_read_b128 v[190:193], v210 offset:22528
	ds_read_b128 v[194:197], v210 offset:23552
	buffer_load_dwordx4 v207, s[16:19], s85 offen lds
	s_add_i32 s86, s85, 0x158000
	s_mov_b32 m0, s30
	s_nop 0
	buffer_load_dwordx4 v207, s[16:19], s86 offen lds
	s_add_i32 s86, s85, 0x2b0000
	s_mov_b32 m0, s31
	s_nop 0
	buffer_load_dwordx4 v207, s[16:19], s86 offen lds
	s_add_i32 s86, s85, 0x408000
	s_mov_b32 m0, s50
	s_nop 0
	buffer_load_dwordx4 v207, s[16:19], s86 offen lds
	s_mov_b32 m0, s25
	s_add_i32 s86, s83, 0x158000
	buffer_load_dwordx4 v206, s[12:15], s83 offen lds
	s_mov_b32 m0, s51
	s_nop 0
	buffer_load_dwordx4 v206, s[12:15], s86 offen lds
	s_waitcnt vmcnt(8)
	s_waitcnt lgkmcnt(0)
	s_setprio 1
	v_mfma_f32_16x16x32_bf16 v[62:65], v[134:137], v[166:169], v[62:65]
	s_barrier
	v_mfma_f32_16x16x32_bf16 v[62:65], v[138:141], v[170:173], v[62:65]
	v_mfma_f32_16x16x32_bf16 v[58:61], v[142:145], v[166:169], v[58:61]
	v_mfma_f32_16x16x32_bf16 v[58:61], v[146:149], v[170:173], v[58:61]
	v_mfma_f32_16x16x32_bf16 v[50:53], v[142:145], v[174:177], v[50:53]
	v_mfma_f32_16x16x32_bf16 v[50:53], v[146:149], v[178:181], v[50:53]
	v_mfma_f32_16x16x32_bf16 v[54:57], v[134:137], v[174:177], v[54:57]
	v_mfma_f32_16x16x32_bf16 v[54:57], v[138:141], v[178:181], v[54:57]
	v_mfma_f32_16x16x32_bf16 v[46:49], v[150:153], v[166:169], v[46:49]
	v_mfma_f32_16x16x32_bf16 v[46:49], v[154:157], v[170:173], v[46:49]
	v_mfma_f32_16x16x32_bf16 v[38:41], v[158:161], v[166:169], v[38:41]
	v_mfma_f32_16x16x32_bf16 v[38:41], v[162:165], v[170:173], v[38:41]
	v_mfma_f32_16x16x32_bf16 v[22:25], v[158:161], v[174:177], v[22:25]
	v_mfma_f32_16x16x32_bf16 v[22:25], v[162:165], v[178:181], v[22:25]
	v_mfma_f32_16x16x32_bf16 v[30:33], v[150:153], v[174:177], v[30:33]
	v_mfma_f32_16x16x32_bf16 v[30:33], v[154:157], v[178:181], v[30:33]
	v_mfma_f32_16x16x32_bf16 v[42:45], v[134:137], v[182:185], v[42:45]
	v_mfma_f32_16x16x32_bf16 v[42:45], v[138:141], v[186:189], v[42:45]
	v_mfma_f32_16x16x32_bf16 v[34:37], v[142:145], v[182:185], v[34:37]
	v_mfma_f32_16x16x32_bf16 v[34:37], v[146:149], v[186:189], v[34:37]
	v_mfma_f32_16x16x32_bf16 v[18:21], v[142:145], v[190:193], v[18:21]
	v_mfma_f32_16x16x32_bf16 v[18:21], v[146:149], v[194:197], v[18:21]
	v_mfma_f32_16x16x32_bf16 v[26:29], v[134:137], v[190:193], v[26:29]
	v_mfma_f32_16x16x32_bf16 v[26:29], v[138:141], v[194:197], v[26:29]
	v_mfma_f32_16x16x32_bf16 v[14:17], v[150:153], v[182:185], v[14:17]
	v_mfma_f32_16x16x32_bf16 v[14:17], v[154:157], v[186:189], v[14:17]
	v_mfma_f32_16x16x32_bf16 v[10:13], v[158:161], v[182:185], v[10:13]
	v_mfma_f32_16x16x32_bf16 v[10:13], v[162:165], v[186:189], v[10:13]
	v_mfma_f32_16x16x32_bf16 v[2:5], v[158:161], v[190:193], v[2:5]
	v_mfma_f32_16x16x32_bf16 v[2:5], v[162:165], v[194:197], v[2:5]
	v_mfma_f32_16x16x32_bf16 v[6:9], v[150:153], v[190:193], v[6:9]
	v_mfma_f32_16x16x32_bf16 v[6:9], v[154:157], v[194:197], v[6:9]
	s_setprio 0
	s_barrier
	ds_read_b128 v[134:137], v211
	ds_read_b128 v[138:141], v211 offset:1024
	ds_read_b128 v[142:145], v211 offset:2048
	ds_read_b128 v[146:149], v211 offset:3072
	ds_read_b128 v[150:153], v212
	ds_read_b128 v[154:157], v212 offset:1024
	ds_read_b128 v[158:161], v212 offset:2048
	ds_read_b128 v[162:165], v212 offset:3072
	s_mov_b32 m0, s52
	s_add_i32 s86, s83, 0x2b0000
	ds_read_b128 v[166:169], v210 offset:32768
	ds_read_b128 v[170:173], v210 offset:33792
	ds_read_b128 v[174:177], v210 offset:34816
	ds_read_b128 v[178:181], v210 offset:35840
	ds_read_b128 v[182:185], v210 offset:36864
	ds_read_b128 v[186:189], v210 offset:37888
	ds_read_b128 v[190:193], v210 offset:38912
	ds_read_b128 v[194:197], v210 offset:39936
	buffer_load_dwordx4 v206, s[12:15], s86 offen lds
	s_add_i32 s86, s83, 0x408000
	s_mov_b32 m0, s53
	s_nop 0
	buffer_load_dwordx4 v206, s[12:15], s86 offen lds
	s_waitcnt vmcnt(8)
	s_waitcnt lgkmcnt(0)
	s_setprio 1
	v_mfma_f32_16x16x32_bf16 v[126:129], v[134:137], v[166:169], v[126:129]
	s_barrier
	v_mfma_f32_16x16x32_bf16 v[126:129], v[138:141], v[170:173], v[126:129]
	v_mfma_f32_16x16x32_bf16 v[122:125], v[142:145], v[166:169], v[122:125]
	v_mfma_f32_16x16x32_bf16 v[122:125], v[146:149], v[170:173], v[122:125]
	v_mfma_f32_16x16x32_bf16 v[114:117], v[142:145], v[174:177], v[114:117]
	v_mfma_f32_16x16x32_bf16 v[114:117], v[146:149], v[178:181], v[114:117]
	v_mfma_f32_16x16x32_bf16 v[118:121], v[134:137], v[174:177], v[118:121]
	v_mfma_f32_16x16x32_bf16 v[118:121], v[138:141], v[178:181], v[118:121]
	v_mfma_f32_16x16x32_bf16 v[110:113], v[150:153], v[166:169], v[110:113]
	v_mfma_f32_16x16x32_bf16 v[110:113], v[154:157], v[170:173], v[110:113]
	v_mfma_f32_16x16x32_bf16 v[102:105], v[158:161], v[166:169], v[102:105]
	v_mfma_f32_16x16x32_bf16 v[102:105], v[162:165], v[170:173], v[102:105]
	v_mfma_f32_16x16x32_bf16 v[86:89], v[158:161], v[174:177], v[86:89]
	v_mfma_f32_16x16x32_bf16 v[86:89], v[162:165], v[178:181], v[86:89]
	v_mfma_f32_16x16x32_bf16 v[94:97], v[150:153], v[174:177], v[94:97]
	v_mfma_f32_16x16x32_bf16 v[94:97], v[154:157], v[178:181], v[94:97]
	v_mfma_f32_16x16x32_bf16 v[106:109], v[134:137], v[182:185], v[106:109]
	v_mfma_f32_16x16x32_bf16 v[106:109], v[138:141], v[186:189], v[106:109]
	v_mfma_f32_16x16x32_bf16 v[98:101], v[142:145], v[182:185], v[98:101]
	v_mfma_f32_16x16x32_bf16 v[98:101], v[146:149], v[186:189], v[98:101]
	v_mfma_f32_16x16x32_bf16 v[82:85], v[142:145], v[190:193], v[82:85]
	v_mfma_f32_16x16x32_bf16 v[82:85], v[146:149], v[194:197], v[82:85]
	v_mfma_f32_16x16x32_bf16 v[90:93], v[134:137], v[190:193], v[90:93]
	v_mfma_f32_16x16x32_bf16 v[90:93], v[138:141], v[194:197], v[90:93]
	v_mfma_f32_16x16x32_bf16 v[78:81], v[150:153], v[182:185], v[78:81]
	v_mfma_f32_16x16x32_bf16 v[78:81], v[154:157], v[186:189], v[78:81]
	v_mfma_f32_16x16x32_bf16 v[74:77], v[158:161], v[182:185], v[74:77]
	v_mfma_f32_16x16x32_bf16 v[74:77], v[162:165], v[186:189], v[74:77]
	v_mfma_f32_16x16x32_bf16 v[66:69], v[158:161], v[190:193], v[66:69]
	v_mfma_f32_16x16x32_bf16 v[66:69], v[162:165], v[194:197], v[66:69]
	v_mfma_f32_16x16x32_bf16 v[70:73], v[150:153], v[190:193], v[70:73]
	v_mfma_f32_16x16x32_bf16 v[70:73], v[154:157], v[194:197], v[70:73]
	s_setprio 0
	s_barrier
	s_mov_b32 m0, s57
	s_or_b32 s86, s85, 0x80
	ds_read_b128 v[166:169], v210 offset:49152
	ds_read_b128 v[170:173], v210 offset:50176
	ds_read_b128 v[174:177], v210 offset:51200
	ds_read_b128 v[178:181], v210 offset:52224
	ds_read_b128 v[182:185], v210 offset:53248
	ds_read_b128 v[186:189], v210 offset:54272
	ds_read_b128 v[190:193], v210 offset:55296
	ds_read_b128 v[194:197], v210 offset:56320
	buffer_load_dwordx4 v207, s[16:19], s86 offen lds
	s_add_i32 s86, s85, 0x158080
	s_mov_b32 m0, s58
	s_add_i32 s83, s83, 0x158080
	buffer_load_dwordx4 v207, s[16:19], s86 offen lds
	s_add_i32 s86, s85, 0x2b0080
	s_mov_b32 m0, s61
	s_add_i32 s85, s85, 0x408080
	buffer_load_dwordx4 v207, s[16:19], s86 offen lds
	s_mov_b32 m0, s62
	s_nop 0
	buffer_load_dwordx4 v207, s[16:19], s85 offen lds
	s_mov_b32 m0, s59
	s_nop 0
	buffer_load_dwordx4 v206, s[12:15], s84 offen lds
	s_mov_b32 m0, s60
	s_nop 0
	buffer_load_dwordx4 v206, s[12:15], s83 offen lds
	s_waitcnt vmcnt(8)
	s_waitcnt lgkmcnt(0)
	s_setprio 1
	v_mfma_f32_16x16x32_bf16 v[62:65], v[134:137], v[166:169], v[62:65]
	s_barrier
	v_mfma_f32_16x16x32_bf16 v[62:65], v[138:141], v[170:173], v[62:65]
	v_mfma_f32_16x16x32_bf16 v[58:61], v[142:145], v[166:169], v[58:61]
	v_mfma_f32_16x16x32_bf16 v[58:61], v[146:149], v[170:173], v[58:61]
	v_mfma_f32_16x16x32_bf16 v[50:53], v[142:145], v[174:177], v[50:53]
	v_mfma_f32_16x16x32_bf16 v[50:53], v[146:149], v[178:181], v[50:53]
	v_mfma_f32_16x16x32_bf16 v[54:57], v[134:137], v[174:177], v[54:57]
	v_mfma_f32_16x16x32_bf16 v[54:57], v[138:141], v[178:181], v[54:57]
	v_mfma_f32_16x16x32_bf16 v[46:49], v[150:153], v[166:169], v[46:49]
	v_mfma_f32_16x16x32_bf16 v[46:49], v[154:157], v[170:173], v[46:49]
	v_mfma_f32_16x16x32_bf16 v[38:41], v[158:161], v[166:169], v[38:41]
	v_mfma_f32_16x16x32_bf16 v[38:41], v[162:165], v[170:173], v[38:41]
	v_mfma_f32_16x16x32_bf16 v[22:25], v[158:161], v[174:177], v[22:25]
	v_mfma_f32_16x16x32_bf16 v[22:25], v[162:165], v[178:181], v[22:25]
	v_mfma_f32_16x16x32_bf16 v[30:33], v[150:153], v[174:177], v[30:33]
	v_mfma_f32_16x16x32_bf16 v[30:33], v[154:157], v[178:181], v[30:33]
	v_mfma_f32_16x16x32_bf16 v[42:45], v[134:137], v[182:185], v[42:45]
	v_mfma_f32_16x16x32_bf16 v[42:45], v[138:141], v[186:189], v[42:45]
	v_mfma_f32_16x16x32_bf16 v[34:37], v[142:145], v[182:185], v[34:37]
	v_mfma_f32_16x16x32_bf16 v[34:37], v[146:149], v[186:189], v[34:37]
	v_mfma_f32_16x16x32_bf16 v[18:21], v[142:145], v[190:193], v[18:21]
	v_mfma_f32_16x16x32_bf16 v[18:21], v[146:149], v[194:197], v[18:21]
	v_mfma_f32_16x16x32_bf16 v[26:29], v[134:137], v[190:193], v[26:29]
	v_mfma_f32_16x16x32_bf16 v[26:29], v[138:141], v[194:197], v[26:29]
	v_mfma_f32_16x16x32_bf16 v[14:17], v[150:153], v[182:185], v[14:17]
	v_mfma_f32_16x16x32_bf16 v[14:17], v[154:157], v[186:189], v[14:17]
	v_mfma_f32_16x16x32_bf16 v[10:13], v[158:161], v[182:185], v[10:13]
	v_mfma_f32_16x16x32_bf16 v[10:13], v[162:165], v[186:189], v[10:13]
	v_mfma_f32_16x16x32_bf16 v[2:5], v[158:161], v[190:193], v[2:5]
	v_mfma_f32_16x16x32_bf16 v[2:5], v[162:165], v[194:197], v[2:5]
	v_mfma_f32_16x16x32_bf16 v[6:9], v[150:153], v[190:193], v[6:9]
	v_mfma_f32_16x16x32_bf16 v[6:9], v[154:157], v[194:197], v[6:9]
	s_setprio 0
	s_barrier
	s_add_i32 s82, s82, 2
	s_addk_i32 s80, 0x100
	s_addk_i32 s81, 0x100
	s_cmp_ge_i32 s82, s3
	s_cbranch_scc0 .LBB0_1519
	v_pk_mul_f32 v[182:183], v[128:129], 0.5 op_sel_hi:[1,0]
	v_pk_mul_f32 v[184:185], v[126:127], 0.5 op_sel_hi:[1,0]
	v_pk_mul_f32 v[186:187], v[124:125], 0.5 op_sel_hi:[1,0]
	v_pk_mul_f32 v[188:189], v[122:123], 0.5 op_sel_hi:[1,0]
	v_pk_mul_f32 v[196:197], v[112:113], 0.5 op_sel_hi:[1,0]
	v_pk_mul_f32 v[194:195], v[110:111], 0.5 op_sel_hi:[1,0]
	v_pk_mul_f32 v[192:193], v[104:105], 0.5 op_sel_hi:[1,0]
	v_pk_mul_f32 v[190:191], v[102:103], 0.5 op_sel_hi:[1,0]
	v_pk_mul_f32 v[180:181], v[120:121], 0.5 op_sel_hi:[1,0]
	v_pk_mul_f32 v[178:179], v[118:119], 0.5 op_sel_hi:[1,0]
	v_pk_mul_f32 v[176:177], v[116:117], 0.5 op_sel_hi:[1,0]
	v_pk_mul_f32 v[174:175], v[114:115], 0.5 op_sel_hi:[1,0]
	v_pk_mul_f32 v[170:171], v[96:97], 0.5 op_sel_hi:[1,0]
	v_pk_mul_f32 v[168:169], v[94:95], 0.5 op_sel_hi:[1,0]
	v_pk_mul_f32 v[166:167], v[88:89], 0.5 op_sel_hi:[1,0]
	v_pk_mul_f32 v[164:165], v[86:87], 0.5 op_sel_hi:[1,0]
	v_pk_mul_f32 v[162:163], v[108:109], 0.5 op_sel_hi:[1,0]
	v_pk_mul_f32 v[160:161], v[106:107], 0.5 op_sel_hi:[1,0]
	v_pk_mul_f32 v[158:159], v[100:101], 0.5 op_sel_hi:[1,0]
	v_pk_mul_f32 v[156:157], v[98:99], 0.5 op_sel_hi:[1,0]
	v_pk_mul_f32 v[154:155], v[80:81], 0.5 op_sel_hi:[1,0]
	v_pk_mul_f32 v[152:153], v[78:79], 0.5 op_sel_hi:[1,0]
	v_pk_mul_f32 v[150:151], v[76:77], 0.5 op_sel_hi:[1,0]
	v_pk_mul_f32 v[148:149], v[74:75], 0.5 op_sel_hi:[1,0]
	v_pk_mul_f32 v[144:145], v[92:93], 0.5 op_sel_hi:[1,0]
	v_pk_mul_f32 v[142:143], v[90:91], 0.5 op_sel_hi:[1,0]
	v_pk_mul_f32 v[140:141], v[84:85], 0.5 op_sel_hi:[1,0]
	v_pk_mul_f32 v[138:139], v[82:83], 0.5 op_sel_hi:[1,0]
	v_pk_mul_f32 v[136:137], v[72:73], 0.5 op_sel_hi:[1,0]
	v_pk_mul_f32 v[134:135], v[70:71], 0.5 op_sel_hi:[1,0]
	v_pk_mul_f32 v[128:129], v[68:69], 0.5 op_sel_hi:[1,0]
	v_pk_mul_f32 v[126:127], v[66:67], 0.5 op_sel_hi:[1,0]
	v_pk_mul_f32 v[122:123], v[64:65], 0.5 op_sel_hi:[1,0]
	v_pk_mul_f32 v[120:121], v[62:63], 0.5 op_sel_hi:[1,0]
	v_pk_mul_f32 v[118:119], v[60:61], 0.5 op_sel_hi:[1,0]
	v_pk_mul_f32 v[116:117], v[58:59], 0.5 op_sel_hi:[1,0]
	v_pk_mul_f32 v[112:113], v[48:49], 0.5 op_sel_hi:[1,0]
	v_pk_mul_f32 v[110:111], v[46:47], 0.5 op_sel_hi:[1,0]
	v_pk_mul_f32 v[108:109], v[40:41], 0.5 op_sel_hi:[1,0]
	v_pk_mul_f32 v[106:107], v[38:39], 0.5 op_sel_hi:[1,0]
	v_pk_mul_f32 v[104:105], v[56:57], 0.5 op_sel_hi:[1,0]
	v_pk_mul_f32 v[102:103], v[54:55], 0.5 op_sel_hi:[1,0]
	v_pk_mul_f32 v[100:101], v[52:53], 0.5 op_sel_hi:[1,0]
	v_pk_mul_f32 v[98:99], v[50:51], 0.5 op_sel_hi:[1,0]
	v_pk_mul_f32 v[96:97], v[32:33], 0.5 op_sel_hi:[1,0]
	v_pk_mul_f32 v[94:95], v[30:31], 0.5 op_sel_hi:[1,0]
	v_pk_mul_f32 v[92:93], v[24:25], 0.5 op_sel_hi:[1,0]
	v_pk_mul_f32 v[90:91], v[22:23], 0.5 op_sel_hi:[1,0]
	v_pk_mul_f32 v[88:89], v[44:45], 0.5 op_sel_hi:[1,0]
	v_pk_mul_f32 v[86:87], v[42:43], 0.5 op_sel_hi:[1,0]
	v_pk_mul_f32 v[84:85], v[36:37], 0.5 op_sel_hi:[1,0]
	v_pk_mul_f32 v[82:83], v[34:35], 0.5 op_sel_hi:[1,0]
	v_pk_mul_f32 v[80:81], v[16:17], 0.5 op_sel_hi:[1,0]
	v_pk_mul_f32 v[78:79], v[14:15], 0.5 op_sel_hi:[1,0]
	v_pk_mul_f32 v[76:77], v[12:13], 0.5 op_sel_hi:[1,0]
	v_pk_mul_f32 v[74:75], v[10:11], 0.5 op_sel_hi:[1,0]
	v_pk_mul_f32 v[72:73], v[28:29], 0.5 op_sel_hi:[1,0]
	v_pk_mul_f32 v[70:71], v[26:27], 0.5 op_sel_hi:[1,0]
	v_pk_mul_f32 v[68:69], v[20:21], 0.5 op_sel_hi:[1,0]
	v_pk_mul_f32 v[66:67], v[18:19], 0.5 op_sel_hi:[1,0]
	v_pk_mul_f32 v[64:65], v[8:9], 0.5 op_sel_hi:[1,0]
	v_pk_mul_f32 v[62:63], v[6:7], 0.5 op_sel_hi:[1,0]
	v_pk_mul_f32 v[60:61], v[4:5], 0.5 op_sel_hi:[1,0]
	v_pk_mul_f32 v[58:59], v[2:3], 0.5 op_sel_hi:[1,0]
	s_and_b64 vcc, exec, s[40:41]
	s_cbranch_vccz .LBB0_1522
